# combined: v15b + MFMA-VALU interleaved solve + gdn ticket prefetch + P2 static loop load hoists + P6 epilogue rowsq load batching + transposes end-of-item wait relaxed (each validated separately befor
# baseline (speedup 1.0000x reference)
; __device__ __forceinline__ float bf2f(bf16 v) { return __uint_as_float(((unsigned)v) << 16); }
; #define GDN_LOADROW(buf, rr_, i_) do { _Pragma("unroll") for (int j4 = 0; j4 < ((i_) + 3) / 4; ++j4) buf[j4] = *(const f32x4*)(Lm + (i_) * GP_LSTR + 4 * j4); rr_ = bf2f(*(const bf16*)(xsrc + (i_) * GP_STR * 2)) * scl[i_]; } while (0)
; template <int STRIP> __device__ __forceinline__ void ph_gdn_prep_fast(const bf16* __restrict__ proj, const float* __restrict__ small, const float* __restrict__ conv_w, const float* __restrict__ a_log, const float* __restrict__ dt_bias, ...
;     ...
;         if (tid == 0) *qw = __hip_atomic_fetch_add(queue, 1u, __ATOMIC_RELAXED, __HIP_MEMORY_SCOPE_AGENT);
;     ...
;             const int cs = wave >> 2, ci = 2 * pair + cs;
;             unsigned char* L = lds_dyn + cs * GP_CHUNK; const float* sgc = (const float*)(L + GP_SC); const float* sbeta = sgc + 64; const float* segc = sgc + 128; const float* sekd = sgc + 192;
;             const int c = (wave & 3) * 64 + lane; const bool isw = c >= 128; const int cc = c & 127;
;             const unsigned char* xsrc = L + (isw ? GP_K : GP_V) + cc * 2;
;             const float* Lm = (const float*)(L + GP_L);
;             float U[64];
;             const float* scl = isw ? (sgc + 256) : sbeta;
;             f32x4 bA[16], bB[16]; float rA, rB = 0.f;
;             rA = bf2f(*(const bf16*)xsrc) * scl[0];
;     ...
; #pragma unroll
;             for (int i = 0; i < 64; i += 2) {
;                 GDN_LOADROW(bB, rB, i + 1);
;                 GDN_ROW(bA, rA, i);
;                 if (i + 2 < 64) GDN_LOADROW(bA, rA, i + 2);
;                 GDN_ROW(bB, rB, i + 1);
;             }
.LBB0_1303:
	s_or_b64 exec, exec, s[8:9]
	v_ashrrev_i32_e32 v8, 8, v78
	s_mov_b32 s0, 0x11500
	v_and_b32_e32 v4, 0x80, v78
	v_and_b32_e32 v2, 0x80, v78
	v_mad_i32_i24 v10, v8, s0, 0
	v_cmp_ne_u32_e32 vcc, 0, v2
	v_and_b32_e32 v2, 0x7f, v78
	v_cmp_eq_u32_e64 s[0:1], 0, v4
	v_mov_b32_e32 v4, 0x8800
	v_lshlrev_b32_e32 v18, 1, v2
	v_cndmask_b32_e64 v4, v236, v4, s[0:1]
	s_waitcnt lgkmcnt(0)
	s_barrier
	v_add3_u32 v123, v10, v4, v18
	v_mov_b32_e32 v126, 0x11400
	v_mov_b32_e32 v127, 0x11100
	v_and_b32_e32 v125, 3, v78
	v_cndmask_b32_e64 v126, v126, v127, s[0:1]
	v_lshlrev_b32_e32 v125, 3, v125
	v_add_u32_e32 v124, v10, v126
	v_add_u32_e32 v125, 0xcc00, v125
	v_add_u32_e32 v125, v10, v125
	v_cmp_eq_u32_e64 s[2:3], 0, v78
	s_and_saveexec_b64 s[4:5], s[2:3]
	v_mov_b32_e32 v239, 1
	global_atomic_add v239, v3, v239, s[52:53] sc0
	s_mov_b64 exec, s[4:5]
	v_and_b32_e32 v130, 31, v78
	v_bfe_u32 v127, v78, 5, 1
	v_add_u32_e32 v130, 32, v130
	v_mul_u32_u24_e32 v130, 0x110, v130
	v_lshl_add_u32 v130, v127, 2, v130
	v_add_u32_e32 v130, 0xcc00, v130
	v_add_u32_e32 v130, v10, v130
	ds_read_b32 v172, v130 offset:0
	ds_read_b32 v173, v130 offset:8
	ds_read_b32 v174, v130 offset:16
	ds_read_b32 v175, v130 offset:24
	ds_read_b32 v176, v130 offset:32
	ds_read_b32 v177, v130 offset:40
	ds_read_b32 v178, v130 offset:48
	ds_read_b32 v179, v130 offset:56
	ds_read_b32 v222, v130 offset:64
	ds_read_b32 v223, v130 offset:72
	ds_read_b32 v224, v130 offset:80
	ds_read_b32 v225, v130 offset:88
	ds_read_b32 v226, v130 offset:96
	ds_read_b32 v227, v130 offset:104
	ds_read_b32 v228, v130 offset:112
	ds_read_b32 v229, v130 offset:120
	v_mov_b32_e32 v244, 0
	v_mov_b32_e32 v245, 0
	v_mov_b32_e32 v246, 0
	v_mov_b32_e32 v247, 0
	v_mov_b32_e32 v248, 0
	v_mov_b32_e32 v249, 0
	v_mov_b32_e32 v250, 0
	v_mov_b32_e32 v251, 0
	v_mov_b32_e32 v252, 0
	v_mov_b32_e32 v253, 0
	v_mov_b32_e32 v126, 0
	v_mov_b32_e32 v127, 0
	ds_read_b32 v208, v124 offset:0
	ds_read_u16_d16_hi v244, v123 offset:0
	ds_read_b64 v[186:187], v125 offset:272
	ds_read_b32 v209, v124 offset:4
	ds_read_u16_d16_hi v245, v123 offset:272
	ds_read_b64 v[188:189], v125 offset:544
	ds_read_b32 v210, v124 offset:8
	ds_read_u16_d16_hi v246, v123 offset:544
	ds_read_b64 v[190:191], v125 offset:816
	ds_read_b32 v211, v124 offset:12
	ds_read_u16_d16_hi v247, v123 offset:816
	ds_read_b64 v[192:193], v125 offset:1088
	ds_read_b32 v212, v124 offset:16
	ds_read_u16_d16_hi v248, v123 offset:1088
	ds_read_b64 v[194:195], v125 offset:1360
	ds_read_b32 v213, v124 offset:20
	ds_read_u16_d16_hi v249, v123 offset:1360
	ds_read_b64 v[196:197], v125 offset:1632
	ds_read_b32 v214, v124 offset:24
	ds_read_u16_d16_hi v250, v123 offset:1632
	ds_read_b64 v[198:199], v125 offset:1904
	ds_read_b32 v215, v124 offset:28
	ds_read_u16_d16_hi v251, v123 offset:1904
	ds_read_b64 v[200:201], v125 offset:2176
	ds_read_b32 v216, v124 offset:32
	ds_read_u16_d16_hi v252, v123 offset:2176
	ds_read_b64 v[202:203], v125 offset:2448
	ds_read_b64 v[204:205], v125 offset:2480
	ds_read_b32 v217, v124 offset:36
	ds_read_u16_d16_hi v253, v123 offset:2448
	ds_read_b64 v[206:207], v125 offset:2720
	ds_read_b64 v[164:165], v125 offset:2752
	ds_read_b32 v218, v124 offset:40
	ds_read_u16_d16_hi v126, v123 offset:2720
	s_waitcnt lgkmcnt(15)
	v_fma_f32 v4, v208, v244, 0
	s_waitcnt lgkmcnt(15)
	v_mul_f32_dpp v120, v186, v4 quad_perm:[0,0,0,0] row_mask:0xf bank_mask:0xf
	v_fma_f32 v116, v209, v245, -v120
	v_add_f32_e32 v5, 0, v116
	v_mov_b32_e32 v128, v4
	v_mov_b32_e32 v129, v5
	s_waitcnt lgkmcnt(15)
	v_mul_f32_dpp v120, v188, v4 quad_perm:[0,0,0,0] row_mask:0xf bank_mask:0xf
	v_fma_f32 v116, v210, v246, -v120
	v_permlane32_swap_b32_e32 v128, v129
	v_mul_f32_dpp v117, -v189, v5 quad_perm:[0,0,0,0] row_mask:0xf bank_mask:0xf
	v_add_f32_e32 v6, v117, v116
	v_mfma_f32_32x32x2_f32 v[132:147], v172, v128, 0
	s_waitcnt lgkmcnt(15)
	v_mul_f32_dpp v120, v190, v4 quad_perm:[0,0,0,0] row_mask:0xf bank_mask:0xf
	v_fma_f32 v116, v211, v247, -v120
	v_mul_f32_dpp v117, -v191, v5 quad_perm:[0,0,0,0] row_mask:0xf bank_mask:0xf
	v_mul_f32_dpp v118, -v190, v6 quad_perm:[1,1,1,1] row_mask:0xf bank_mask:0xf
	ds_read_b64 v[166:167], v125 offset:2992
	v_add_f32_e32 v121, v117, v116
	v_add_f32_e32 v12, v118, v121
	v_mov_b32_e32 v220, v6
	v_mov_b32_e32 v221, v12
	s_waitcnt lgkmcnt(15)
	v_mul_f32_dpp v120, v192, v4 quad_perm:[0,0,0,0] row_mask:0xf bank_mask:0xf
	v_fma_f32 v116, v212, v248, -v120
	v_permlane32_swap_b32_e32 v220, v221
	v_mul_f32_dpp v117, -v193, v5 quad_perm:[0,0,0,0] row_mask:0xf bank_mask:0xf
	v_mul_f32_dpp v118, -v192, v6 quad_perm:[1,1,1,1] row_mask:0xf bank_mask:0xf
	v_mfma_f32_32x32x2_f32 v[132:147], v173, v220, v[132:147]
	v_mul_f32_dpp v119, -v193, v12 quad_perm:[1,1,1,1] row_mask:0xf bank_mask:0xf
	ds_read_b64 v[168:169], v125 offset:3024
	v_add_f32_e32 v121, v117, v116
	v_add_f32_e32 v122, v118, v119
	v_add_f32_e32 v7, v122, v121
	s_waitcnt lgkmcnt(15)
	v_mul_f32_dpp v120, v194, v4 quad_perm:[0,0,0,0] row_mask:0xf bank_mask:0xf
	v_fma_f32 v116, v213, v249, -v120
	v_mfma_f32_32x32x2_f32 v[148:163], v172, v129, 0
	v_mul_f32_dpp v117, -v195, v5 quad_perm:[0,0,0,0] row_mask:0xf bank_mask:0xf
	v_mul_f32_dpp v118, -v194, v6 quad_perm:[1,1,1,1] row_mask:0xf bank_mask:0xf
	v_mul_f32_dpp v119, -v195, v12 quad_perm:[1,1,1,1] row_mask:0xf bank_mask:0xf
	ds_read_b32 v219, v124 offset:44
	v_fmac_f32_dpp v116, -v194, v7 quad_perm:[2,2,2,2] row_mask:0xf bank_mask:0xf
	v_add_f32_e32 v121, v117, v116
	v_add_f32_e32 v122, v118, v119
	v_add_f32_e32 v13, v122, v121
	v_mov_b32_e32 v128, v7
	v_mov_b32_e32 v129, v13
	s_waitcnt lgkmcnt(15)
; __device__ __forceinline__ float bf2f(bf16 v) { return __uint_as_float(((unsigned)v) << 16); }
; #define GDN_LOADROW(buf, rr_, i_) do { _Pragma("unroll") for (int j4 = 0; j4 < ((i_) + 3) / 4; ++j4) buf[j4] = *(const f32x4*)(Lm + (i_) * GP_LSTR + 4 * j4); rr_ = bf2f(*(const bf16*)(xsrc + (i_) * GP_STR * 2)) * scl[i_]; } while (0)
; template <int STRIP> __device__ __forceinline__ void ph_gdn_prep_fast(const bf16* __restrict__ proj, const float* __restrict__ small, const float* __restrict__ conv_w, const float* __restrict__ a_log, const float* __restrict__ dt_bias, ...
;     ...
;             f32x4 bA[16], bB[16]; float rA, rB = 0.f;
;             rA = bf2f(*(const bf16*)xsrc) * scl[0];
;     ...
; #pragma unroll
;             for (int i = 0; i < 64; i += 2) {
;                 GDN_LOADROW(bB, rB, i + 1);
;                 GDN_ROW(bA, rA, i);
;                 if (i + 2 < 64) GDN_LOADROW(bA, rA, i + 2);
;                 GDN_ROW(bB, rB, i + 1);
;             }
	v_mul_f32_dpp v120, v196, v4 quad_perm:[0,0,0,0] row_mask:0xf bank_mask:0xf
	v_fma_f32 v116, v214, v250, -v120
	v_permlane32_swap_b32_e32 v128, v129
	v_mul_f32_dpp v117, -v197, v5 quad_perm:[0,0,0,0] row_mask:0xf bank_mask:0xf
	v_mfma_f32_32x32x2_f32 v[148:163], v173, v221, v[148:163]
	v_mul_f32_dpp v118, -v196, v6 quad_perm:[1,1,1,1] row_mask:0xf bank_mask:0xf
	v_mfma_f32_32x32x2_f32 v[132:147], v174, v128, v[132:147]
	ds_read_u16_d16_hi v127, v123 offset:2992
	v_mul_f32_dpp v119, -v197, v12 quad_perm:[1,1,1,1] row_mask:0xf bank_mask:0xf
	v_fmac_f32_dpp v116, -v196, v7 quad_perm:[2,2,2,2] row_mask:0xf bank_mask:0xf
	v_fmac_f32_dpp v117, -v197, v13 quad_perm:[2,2,2,2] row_mask:0xf bank_mask:0xf
	ds_read_b64 v[170:171], v125 offset:3264
	v_add_f32_e32 v121, v117, v116
	v_add_f32_e32 v122, v118, v119
	v_add_f32_e32 v14, v122, v121
	s_waitcnt lgkmcnt(15)
	v_mul_f32_dpp v120, v198, v4 quad_perm:[0,0,0,0] row_mask:0xf bank_mask:0xf
	v_fma_f32 v116, v215, v251, -v120
	v_mul_f32_dpp v117, -v199, v5 quad_perm:[0,0,0,0] row_mask:0xf bank_mask:0xf
	v_mul_f32_dpp v118, -v198, v6 quad_perm:[1,1,1,1] row_mask:0xf bank_mask:0xf
	v_mul_f32_dpp v119, -v199, v12 quad_perm:[1,1,1,1] row_mask:0xf bank_mask:0xf
	ds_read_b64 v[84:85], v125 offset:3296
	v_fmac_f32_dpp v116, -v198, v7 quad_perm:[2,2,2,2] row_mask:0xf bank_mask:0xf
	v_fmac_f32_dpp v117, -v199, v13 quad_perm:[2,2,2,2] row_mask:0xf bank_mask:0xf
	v_fmac_f32_dpp v118, -v198, v14 quad_perm:[3,3,3,3] row_mask:0xf bank_mask:0xf
	ds_read_b32 v181, v124 offset:48
	v_add_f32_e32 v121, v117, v116
	v_add_f32_e32 v122, v118, v119
	v_mfma_f32_32x32x2_f32 v[148:163], v174, v129, v[148:163]
	v_add_f32_e32 v15, v122, v121
	v_mov_b32_e32 v220, v14
	v_mov_b32_e32 v221, v15
	s_waitcnt lgkmcnt(15)
	v_mul_f32_dpp v120, v200, v4 quad_perm:[0,0,0,0] row_mask:0xf bank_mask:0xf
	v_fma_f32 v116, v216, v252, -v120
	v_permlane32_swap_b32_e32 v220, v221
	v_mul_f32_dpp v117, -v201, v5 quad_perm:[0,0,0,0] row_mask:0xf bank_mask:0xf
	v_mul_f32_dpp v118, -v200, v6 quad_perm:[1,1,1,1] row_mask:0xf bank_mask:0xf
	v_mfma_f32_32x32x2_f32 v[132:147], v175, v220, v[132:147]
	v_mul_f32_dpp v119, -v201, v12 quad_perm:[1,1,1,1] row_mask:0xf bank_mask:0xf
	ds_read_u16_d16_hi v244, v123 offset:3264
	v_fmac_f32_dpp v116, -v200, v7 quad_perm:[2,2,2,2] row_mask:0xf bank_mask:0xf
	v_fmac_f32_dpp v117, -v201, v13 quad_perm:[2,2,2,2] row_mask:0xf bank_mask:0xf
	v_fmac_f32_dpp v118, -v200, v14 quad_perm:[3,3,3,3] row_mask:0xf bank_mask:0xf
	ds_read_b64 v[86:87], v125 offset:3536
	v_fmac_f32_dpp v119, -v201, v15 quad_perm:[3,3,3,3] row_mask:0xf bank_mask:0xf
	v_add_f32_e32 v121, v117, v116
	v_add_f32_e32 v122, v118, v119
	v_add_f32_e32 v16, v122, v121
	s_waitcnt lgkmcnt(13)
	v_mul_f32_dpp v120, v202, v4 quad_perm:[0,0,0,0] row_mask:0xf bank_mask:0xf
	v_fma_f32 v116, v217, v253, -v120
	v_mul_f32_dpp v117, -v203, v5 quad_perm:[0,0,0,0] row_mask:0xf bank_mask:0xf
	v_mul_f32_dpp v118, -v202, v6 quad_perm:[1,1,1,1] row_mask:0xf bank_mask:0xf
	ds_read_b64 v[88:89], v125 offset:3568
	v_mul_f32_dpp v119, -v203, v12 quad_perm:[1,1,1,1] row_mask:0xf bank_mask:0xf
	v_fmac_f32_dpp v116, -v202, v7 quad_perm:[2,2,2,2] row_mask:0xf bank_mask:0xf
	v_fmac_f32_dpp v117, -v203, v13 quad_perm:[2,2,2,2] row_mask:0xf bank_mask:0xf
	ds_read_b32 v182, v124 offset:52
	v_fmac_f32_dpp v118, -v202, v14 quad_perm:[3,3,3,3] row_mask:0xf bank_mask:0xf
	v_mfma_f32_32x32x2_f32 v[148:163], v175, v221, v[148:163]
	v_fmac_f32_dpp v119, -v203, v15 quad_perm:[3,3,3,3] row_mask:0xf bank_mask:0xf
	v_fmac_f32_dpp v116, -v204, v16 quad_perm:[0,0,0,0] row_mask:0xf bank_mask:0xf
	ds_read_u16_d16_hi v245, v123 offset:3536
	v_add_f32_e32 v121, v117, v116
	v_add_f32_e32 v122, v118, v119
	v_add_f32_e32 v17, v122, v121
	v_mov_b32_e32 v128, v16
	v_mov_b32_e32 v129, v17
	s_waitcnt lgkmcnt(12)
	v_mul_f32_dpp v120, v206, v4 quad_perm:[0,0,0,0] row_mask:0xf bank_mask:0xf
	v_fma_f32 v116, v218, v126, -v120
	v_permlane32_swap_b32_e32 v128, v129
	v_mul_f32_dpp v117, -v207, v5 quad_perm:[0,0,0,0] row_mask:0xf bank_mask:0xf
	v_mul_f32_dpp v118, -v206, v6 quad_perm:[1,1,1,1] row_mask:0xf bank_mask:0xf
	v_mfma_f32_32x32x2_f32 v[132:147], v176, v128, v[132:147]
	v_mul_f32_dpp v119, -v207, v12 quad_perm:[1,1,1,1] row_mask:0xf bank_mask:0xf
	ds_read_b64 v[90:91], v125 offset:3808
	v_fmac_f32_dpp v116, -v206, v7 quad_perm:[2,2,2,2] row_mask:0xf bank_mask:0xf
	v_fmac_f32_dpp v117, -v207, v13 quad_perm:[2,2,2,2] row_mask:0xf bank_mask:0xf
	v_fmac_f32_dpp v118, -v206, v14 quad_perm:[3,3,3,3] row_mask:0xf bank_mask:0xf
	ds_read_b64 v[92:93], v125 offset:3840
	v_fmac_f32_dpp v119, -v207, v15 quad_perm:[3,3,3,3] row_mask:0xf bank_mask:0xf
	v_fmac_f32_dpp v116, -v164, v16 quad_perm:[0,0,0,0] row_mask:0xf bank_mask:0xf
	v_fmac_f32_dpp v117, -v165, v17 quad_perm:[0,0,0,0] row_mask:0xf bank_mask:0xf
	ds_read_b32 v183, v124 offset:56
	v_add_f32_e32 v121, v117, v116
	v_add_f32_e32 v122, v118, v119
	v_add_f32_e32 v19, v122, v121
	s_waitcnt lgkmcnt(11)
	v_mul_f32_dpp v120, v166, v4 quad_perm:[0,0,0,0] row_mask:0xf bank_mask:0xf
	v_fma_f32 v116, v219, v127, -v120
	v_mul_f32_dpp v117, -v167, v5 quad_perm:[0,0,0,0] row_mask:0xf bank_mask:0xf
	v_mul_f32_dpp v118, -v166, v6 quad_perm:[1,1,1,1] row_mask:0xf bank_mask:0xf
	v_mul_f32_dpp v119, -v167, v12 quad_perm:[1,1,1,1] row_mask:0xf bank_mask:0xf
	ds_read_u16_d16_hi v246, v123 offset:3808
	v_fmac_f32_dpp v116, -v166, v7 quad_perm:[2,2,2,2] row_mask:0xf bank_mask:0xf
	v_mfma_f32_32x32x2_f32 v[148:163], v176, v129, v[148:163]
	v_fmac_f32_dpp v117, -v167, v13 quad_perm:[2,2,2,2] row_mask:0xf bank_mask:0xf
	v_fmac_f32_dpp v118, -v166, v14 quad_perm:[3,3,3,3] row_mask:0xf bank_mask:0xf
	ds_read_b64 v[186:187], v125 offset:4080
	v_fmac_f32_dpp v119, -v167, v15 quad_perm:[3,3,3,3] row_mask:0xf bank_mask:0xf
	v_fmac_f32_dpp v116, -v168, v16 quad_perm:[0,0,0,0] row_mask:0xf bank_mask:0xf
	v_fmac_f32_dpp v117, -v169, v17 quad_perm:[0,0,0,0] row_mask:0xf bank_mask:0xf
	ds_read_b64 v[188:189], v125 offset:4112
	v_fmac_f32_dpp v118, -v168, v19 quad_perm:[1,1,1,1] row_mask:0xf bank_mask:0xf
	v_add_f32_e32 v121, v117, v116
	v_add_f32_e32 v122, v118, v119
	v_add_f32_e32 v20, v122, v121
	v_mov_b32_e32 v220, v19
	v_mov_b32_e32 v221, v20
	s_waitcnt lgkmcnt(10)
; __device__ __forceinline__ float bf2f(bf16 v) { return __uint_as_float(((unsigned)v) << 16); }
; #define GDN_LOADROW(buf, rr_, i_) do { _Pragma("unroll") for (int j4 = 0; j4 < ((i_) + 3) / 4; ++j4) buf[j4] = *(const f32x4*)(Lm + (i_) * GP_LSTR + 4 * j4); rr_ = bf2f(*(const bf16*)(xsrc + (i_) * GP_STR * 2)) * scl[i_]; } while (0)
; template <int STRIP> __device__ __forceinline__ void ph_gdn_prep_fast(const bf16* __restrict__ proj, const float* __restrict__ small, const float* __restrict__ conv_w, const float* __restrict__ a_log, const float* __restrict__ dt_bias, ...
;     ...
;             rA = bf2f(*(const bf16*)xsrc) * scl[0];
;     ...
; #pragma unroll
;             for (int i = 0; i < 64; i += 2) {
;                 GDN_LOADROW(bB, rB, i + 1);
;                 GDN_ROW(bA, rA, i);
;                 if (i + 2 < 64) GDN_LOADROW(bA, rA, i + 2);
;                 GDN_ROW(bB, rB, i + 1);
;             }
	v_mul_f32_dpp v120, v170, v4 quad_perm:[0,0,0,0] row_mask:0xf bank_mask:0xf
	v_fma_f32 v116, v181, v244, -v120
	v_permlane32_swap_b32_e32 v220, v221
	v_mul_f32_dpp v117, -v171, v5 quad_perm:[0,0,0,0] row_mask:0xf bank_mask:0xf
	v_mul_f32_dpp v118, -v170, v6 quad_perm:[1,1,1,1] row_mask:0xf bank_mask:0xf
	v_mfma_f32_32x32x2_f32 v[132:147], v177, v220, v[132:147]
	ds_read_b32 v185, v124 offset:60
	v_mul_f32_dpp v119, -v171, v12 quad_perm:[1,1,1,1] row_mask:0xf bank_mask:0xf
	v_fmac_f32_dpp v116, -v170, v7 quad_perm:[2,2,2,2] row_mask:0xf bank_mask:0xf
	v_fmac_f32_dpp v117, -v171, v13 quad_perm:[2,2,2,2] row_mask:0xf bank_mask:0xf
	ds_read_u16_d16_hi v247, v123 offset:4080
	v_fmac_f32_dpp v118, -v170, v14 quad_perm:[3,3,3,3] row_mask:0xf bank_mask:0xf
	v_fmac_f32_dpp v119, -v171, v15 quad_perm:[3,3,3,3] row_mask:0xf bank_mask:0xf
	v_fmac_f32_dpp v116, -v84, v16 quad_perm:[0,0,0,0] row_mask:0xf bank_mask:0xf
	ds_read_b64 v[190:191], v125 offset:4352
	v_fmac_f32_dpp v117, -v85, v17 quad_perm:[0,0,0,0] row_mask:0xf bank_mask:0xf
	v_fmac_f32_dpp v118, -v84, v19 quad_perm:[1,1,1,1] row_mask:0xf bank_mask:0xf
	v_fmac_f32_dpp v119, -v85, v20 quad_perm:[1,1,1,1] row_mask:0xf bank_mask:0xf
	ds_read_b64 v[192:193], v125 offset:4384
	v_add_f32_e32 v121, v117, v116
	v_add_f32_e32 v122, v118, v119
	v_add_f32_e32 v21, v122, v121
	s_waitcnt lgkmcnt(10)
	v_mul_f32_dpp v120, v86, v4 quad_perm:[0,0,0,0] row_mask:0xf bank_mask:0xf
	v_fma_f32 v116, v182, v245, -v120
	v_mul_f32_dpp v117, -v87, v5 quad_perm:[0,0,0,0] row_mask:0xf bank_mask:0xf
	v_mul_f32_dpp v118, -v86, v6 quad_perm:[1,1,1,1] row_mask:0xf bank_mask:0xf
	v_mfma_f32_32x32x2_f32 v[148:163], v177, v221, v[148:163]
	v_mul_f32_dpp v119, -v87, v12 quad_perm:[1,1,1,1] row_mask:0xf bank_mask:0xf
	ds_read_b32 v208, v124 offset:64
	v_fmac_f32_dpp v116, -v86, v7 quad_perm:[2,2,2,2] row_mask:0xf bank_mask:0xf
	v_fmac_f32_dpp v117, -v87, v13 quad_perm:[2,2,2,2] row_mask:0xf bank_mask:0xf
	v_fmac_f32_dpp v118, -v86, v14 quad_perm:[3,3,3,3] row_mask:0xf bank_mask:0xf
	ds_read_u16_d16_hi v248, v123 offset:4352
	v_fmac_f32_dpp v119, -v87, v15 quad_perm:[3,3,3,3] row_mask:0xf bank_mask:0xf
	v_fmac_f32_dpp v116, -v88, v16 quad_perm:[0,0,0,0] row_mask:0xf bank_mask:0xf
	v_fmac_f32_dpp v117, -v89, v17 quad_perm:[0,0,0,0] row_mask:0xf bank_mask:0xf
	ds_read_b64 v[194:195], v125 offset:4624
	v_fmac_f32_dpp v118, -v88, v19 quad_perm:[1,1,1,1] row_mask:0xf bank_mask:0xf
	v_fmac_f32_dpp v119, -v89, v20 quad_perm:[1,1,1,1] row_mask:0xf bank_mask:0xf
	v_fmac_f32_dpp v116, -v88, v21 quad_perm:[2,2,2,2] row_mask:0xf bank_mask:0xf
	ds_read_b64 v[196:197], v125 offset:4656
	v_add_f32_e32 v121, v117, v116
	v_add_f32_e32 v122, v118, v119
	v_add_f32_e32 v22, v122, v121
	v_mov_b32_e32 v128, v21
	v_mov_b32_e32 v129, v22
	s_waitcnt lgkmcnt(10)
	v_mul_f32_dpp v120, v90, v4 quad_perm:[0,0,0,0] row_mask:0xf bank_mask:0xf
	v_fma_f32 v116, v183, v246, -v120
	v_permlane32_swap_b32_e32 v128, v129
	v_mul_f32_dpp v117, -v91, v5 quad_perm:[0,0,0,0] row_mask:0xf bank_mask:0xf
	v_mul_f32_dpp v118, -v90, v6 quad_perm:[1,1,1,1] row_mask:0xf bank_mask:0xf
	v_mfma_f32_32x32x2_f32 v[132:147], v178, v128, v[132:147]
	v_mul_f32_dpp v119, -v91, v12 quad_perm:[1,1,1,1] row_mask:0xf bank_mask:0xf
	ds_read_b64 v[198:199], v125 offset:4688
	v_fmac_f32_dpp v116, -v90, v7 quad_perm:[2,2,2,2] row_mask:0xf bank_mask:0xf
	v_fmac_f32_dpp v117, -v91, v13 quad_perm:[2,2,2,2] row_mask:0xf bank_mask:0xf
	v_fmac_f32_dpp v118, -v90, v14 quad_perm:[3,3,3,3] row_mask:0xf bank_mask:0xf
	ds_read_b32 v209, v124 offset:68
	v_fmac_f32_dpp v119, -v91, v15 quad_perm:[3,3,3,3] row_mask:0xf bank_mask:0xf
	v_fmac_f32_dpp v116, -v92, v16 quad_perm:[0,0,0,0] row_mask:0xf bank_mask:0xf
	v_fmac_f32_dpp v117, -v93, v17 quad_perm:[0,0,0,0] row_mask:0xf bank_mask:0xf
	ds_read_u16_d16_hi v249, v123 offset:4624
	v_fmac_f32_dpp v118, -v92, v19 quad_perm:[1,1,1,1] row_mask:0xf bank_mask:0xf
	v_fmac_f32_dpp v119, -v93, v20 quad_perm:[1,1,1,1] row_mask:0xf bank_mask:0xf
	v_fmac_f32_dpp v116, -v92, v21 quad_perm:[2,2,2,2] row_mask:0xf bank_mask:0xf
	ds_read_b64 v[200:201], v125 offset:4896
	v_fmac_f32_dpp v117, -v93, v22 quad_perm:[2,2,2,2] row_mask:0xf bank_mask:0xf
	v_add_f32_e32 v121, v117, v116
	v_add_f32_e32 v122, v118, v119
	v_add_f32_e32 v23, v122, v121
	s_waitcnt lgkmcnt(10)
	v_mul_f32_dpp v120, v186, v4 quad_perm:[0,0,0,0] row_mask:0xf bank_mask:0xf
	v_fma_f32 v116, v185, v247, -v120
	v_mfma_f32_32x32x2_f32 v[148:163], v178, v129, v[148:163]
	v_mul_f32_dpp v117, -v187, v5 quad_perm:[0,0,0,0] row_mask:0xf bank_mask:0xf
	v_mul_f32_dpp v118, -v186, v6 quad_perm:[1,1,1,1] row_mask:0xf bank_mask:0xf
	ds_read_b64 v[202:203], v125 offset:4928
	v_mul_f32_dpp v119, -v187, v12 quad_perm:[1,1,1,1] row_mask:0xf bank_mask:0xf
	v_fmac_f32_dpp v116, -v186, v7 quad_perm:[2,2,2,2] row_mask:0xf bank_mask:0xf
	v_fmac_f32_dpp v117, -v187, v13 quad_perm:[2,2,2,2] row_mask:0xf bank_mask:0xf
	ds_read_b64 v[204:205], v125 offset:4960
	v_fmac_f32_dpp v118, -v186, v14 quad_perm:[3,3,3,3] row_mask:0xf bank_mask:0xf
	v_fmac_f32_dpp v119, -v187, v15 quad_perm:[3,3,3,3] row_mask:0xf bank_mask:0xf
	v_fmac_f32_dpp v116, -v188, v16 quad_perm:[0,0,0,0] row_mask:0xf bank_mask:0xf
	ds_read_b32 v210, v124 offset:72
	v_fmac_f32_dpp v117, -v189, v17 quad_perm:[0,0,0,0] row_mask:0xf bank_mask:0xf
	v_fmac_f32_dpp v118, -v188, v19 quad_perm:[1,1,1,1] row_mask:0xf bank_mask:0xf
	v_fmac_f32_dpp v119, -v189, v20 quad_perm:[1,1,1,1] row_mask:0xf bank_mask:0xf
	ds_read_u16_d16_hi v250, v123 offset:4896
	v_fmac_f32_dpp v116, -v188, v21 quad_perm:[2,2,2,2] row_mask:0xf bank_mask:0xf
	v_fmac_f32_dpp v117, -v189, v22 quad_perm:[2,2,2,2] row_mask:0xf bank_mask:0xf
	v_fmac_f32_dpp v118, -v188, v23 quad_perm:[3,3,3,3] row_mask:0xf bank_mask:0xf
	ds_read_b64 v[206:207], v125 offset:5168
	v_add_f32_e32 v121, v117, v116
	v_add_f32_e32 v122, v118, v119
	v_add_f32_e32 v24, v122, v121
	v_mov_b32_e32 v220, v23
	v_mov_b32_e32 v221, v24
	s_waitcnt lgkmcnt(11)
; __device__ __forceinline__ float bf2f(bf16 v) { return __uint_as_float(((unsigned)v) << 16); }
; #define GDN_LOADROW(buf, rr_, i_) do { _Pragma("unroll") for (int j4 = 0; j4 < ((i_) + 3) / 4; ++j4) buf[j4] = *(const f32x4*)(Lm + (i_) * GP_LSTR + 4 * j4); rr_ = bf2f(*(const bf16*)(xsrc + (i_) * GP_STR * 2)) * scl[i_]; } while (0)
; template <int STRIP> __device__ __forceinline__ void ph_gdn_prep_fast(const bf16* __restrict__ proj, const float* __restrict__ small, const float* __restrict__ conv_w, const float* __restrict__ a_log, const float* __restrict__ dt_bias, ...
;     ...
;             rA = bf2f(*(const bf16*)xsrc) * scl[0];
;     ...
; #pragma unroll
;             for (int i = 0; i < 64; i += 2) {
;                 GDN_LOADROW(bB, rB, i + 1);
;                 GDN_ROW(bA, rA, i);
;                 if (i + 2 < 64) GDN_LOADROW(bA, rA, i + 2);
;                 GDN_ROW(bB, rB, i + 1);
;             }
	v_mul_f32_dpp v120, v190, v4 quad_perm:[0,0,0,0] row_mask:0xf bank_mask:0xf
	v_fma_f32 v116, v208, v248, -v120
	v_permlane32_swap_b32_e32 v220, v221
	v_mul_f32_dpp v117, -v191, v5 quad_perm:[0,0,0,0] row_mask:0xf bank_mask:0xf
	v_mul_f32_dpp v118, -v190, v6 quad_perm:[1,1,1,1] row_mask:0xf bank_mask:0xf
	v_mfma_f32_32x32x2_f32 v[132:147], v179, v220, v[132:147]
	v_mul_f32_dpp v119, -v191, v12 quad_perm:[1,1,1,1] row_mask:0xf bank_mask:0xf
	ds_read_b64 v[164:165], v125 offset:5200
	v_fmac_f32_dpp v116, -v190, v7 quad_perm:[2,2,2,2] row_mask:0xf bank_mask:0xf
	v_fmac_f32_dpp v117, -v191, v13 quad_perm:[2,2,2,2] row_mask:0xf bank_mask:0xf
	v_fmac_f32_dpp v118, -v190, v14 quad_perm:[3,3,3,3] row_mask:0xf bank_mask:0xf
	ds_read_b64 v[166:167], v125 offset:5232
	v_fmac_f32_dpp v119, -v191, v15 quad_perm:[3,3,3,3] row_mask:0xf bank_mask:0xf
	v_fmac_f32_dpp v116, -v192, v16 quad_perm:[0,0,0,0] row_mask:0xf bank_mask:0xf
	v_fmac_f32_dpp v117, -v193, v17 quad_perm:[0,0,0,0] row_mask:0xf bank_mask:0xf
	ds_read_b32 v211, v124 offset:76
	v_fmac_f32_dpp v118, -v192, v19 quad_perm:[1,1,1,1] row_mask:0xf bank_mask:0xf
	v_fmac_f32_dpp v119, -v193, v20 quad_perm:[1,1,1,1] row_mask:0xf bank_mask:0xf
	v_fmac_f32_dpp v116, -v192, v21 quad_perm:[2,2,2,2] row_mask:0xf bank_mask:0xf
	ds_read_u16_d16_hi v251, v123 offset:5168
	v_fmac_f32_dpp v117, -v193, v22 quad_perm:[2,2,2,2] row_mask:0xf bank_mask:0xf
	v_fmac_f32_dpp v118, -v192, v23 quad_perm:[3,3,3,3] row_mask:0xf bank_mask:0xf
	v_fmac_f32_dpp v119, -v193, v24 quad_perm:[3,3,3,3] row_mask:0xf bank_mask:0xf
	ds_read_b64 v[168:169], v125 offset:5440
	v_add_f32_e32 v121, v117, v116
	v_add_f32_e32 v122, v118, v119
	v_add_f32_e32 v25, v122, v121
	v_mfma_f32_32x32x2_f32 v[148:163], v179, v221, v[148:163]
	s_waitcnt lgkmcnt(11)
	v_mul_f32_dpp v120, v194, v4 quad_perm:[0,0,0,0] row_mask:0xf bank_mask:0xf
	v_fma_f32 v116, v209, v249, -v120
	v_mul_f32_dpp v117, -v195, v5 quad_perm:[0,0,0,0] row_mask:0xf bank_mask:0xf
	v_mul_f32_dpp v118, -v194, v6 quad_perm:[1,1,1,1] row_mask:0xf bank_mask:0xf
	v_mul_f32_dpp v119, -v195, v12 quad_perm:[1,1,1,1] row_mask:0xf bank_mask:0xf
	ds_read_b64 v[170:171], v125 offset:5472
	v_fmac_f32_dpp v116, -v194, v7 quad_perm:[2,2,2,2] row_mask:0xf bank_mask:0xf
	v_fmac_f32_dpp v117, -v195, v13 quad_perm:[2,2,2,2] row_mask:0xf bank_mask:0xf
	v_fmac_f32_dpp v118, -v194, v14 quad_perm:[3,3,3,3] row_mask:0xf bank_mask:0xf
	ds_read_b64 v[84:85], v125 offset:5504
	v_fmac_f32_dpp v119, -v195, v15 quad_perm:[3,3,3,3] row_mask:0xf bank_mask:0xf
	v_fmac_f32_dpp v116, -v196, v16 quad_perm:[0,0,0,0] row_mask:0xf bank_mask:0xf
	v_fmac_f32_dpp v117, -v197, v17 quad_perm:[0,0,0,0] row_mask:0xf bank_mask:0xf
	ds_read_b32 v212, v124 offset:80
	v_fmac_f32_dpp v118, -v196, v19 quad_perm:[1,1,1,1] row_mask:0xf bank_mask:0xf
	v_fmac_f32_dpp v119, -v197, v20 quad_perm:[1,1,1,1] row_mask:0xf bank_mask:0xf
	v_fmac_f32_dpp v116, -v196, v21 quad_perm:[2,2,2,2] row_mask:0xf bank_mask:0xf
	ds_read_u16_d16_hi v252, v123 offset:5440
	v_fmac_f32_dpp v117, -v197, v22 quad_perm:[2,2,2,2] row_mask:0xf bank_mask:0xf
	v_fmac_f32_dpp v118, -v196, v23 quad_perm:[3,3,3,3] row_mask:0xf bank_mask:0xf
	v_fmac_f32_dpp v119, -v197, v24 quad_perm:[3,3,3,3] row_mask:0xf bank_mask:0xf
	ds_read_b64 v[86:87], v125 offset:5712
	v_fmac_f32_dpp v116, -v198, v25 quad_perm:[0,0,0,0] row_mask:0xf bank_mask:0xf
	v_add_f32_e32 v121, v117, v116
	v_add_f32_e32 v122, v118, v119
	v_add_f32_e32 v27, v122, v121
	v_mov_b32_e32 v128, v25
	v_mov_b32_e32 v129, v27
	s_waitcnt lgkmcnt(11)
	v_mul_f32_dpp v120, v200, v4 quad_perm:[0,0,0,0] row_mask:0xf bank_mask:0xf
	v_fma_f32 v116, v210, v250, -v120
	v_permlane32_swap_b32_e32 v128, v129
	v_mul_f32_dpp v117, -v201, v5 quad_perm:[0,0,0,0] row_mask:0xf bank_mask:0xf
	v_mul_f32_dpp v118, -v200, v6 quad_perm:[1,1,1,1] row_mask:0xf bank_mask:0xf
	v_mfma_f32_32x32x2_f32 v[132:147], v222, v128, v[132:147]
	ds_read_b64 v[88:89], v125 offset:5744
	v_mul_f32_dpp v119, -v201, v12 quad_perm:[1,1,1,1] row_mask:0xf bank_mask:0xf
	v_fmac_f32_dpp v116, -v200, v7 quad_perm:[2,2,2,2] row_mask:0xf bank_mask:0xf
	v_fmac_f32_dpp v117, -v201, v13 quad_perm:[2,2,2,2] row_mask:0xf bank_mask:0xf
	ds_read_b64 v[90:91], v125 offset:5776
	v_fmac_f32_dpp v118, -v200, v14 quad_perm:[3,3,3,3] row_mask:0xf bank_mask:0xf
	v_fmac_f32_dpp v119, -v201, v15 quad_perm:[3,3,3,3] row_mask:0xf bank_mask:0xf
	v_fmac_f32_dpp v116, -v202, v16 quad_perm:[0,0,0,0] row_mask:0xf bank_mask:0xf
	ds_read_b32 v213, v124 offset:84
	v_fmac_f32_dpp v117, -v203, v17 quad_perm:[0,0,0,0] row_mask:0xf bank_mask:0xf
	v_fmac_f32_dpp v118, -v202, v19 quad_perm:[1,1,1,1] row_mask:0xf bank_mask:0xf
	v_fmac_f32_dpp v119, -v203, v20 quad_perm:[1,1,1,1] row_mask:0xf bank_mask:0xf
	ds_read_u16_d16_hi v253, v123 offset:5712
	v_fmac_f32_dpp v116, -v202, v21 quad_perm:[2,2,2,2] row_mask:0xf bank_mask:0xf
	v_fmac_f32_dpp v117, -v203, v22 quad_perm:[2,2,2,2] row_mask:0xf bank_mask:0xf
	v_fmac_f32_dpp v118, -v202, v23 quad_perm:[3,3,3,3] row_mask:0xf bank_mask:0xf
	ds_read_b64 v[92:93], v125 offset:5984
	v_fmac_f32_dpp v119, -v203, v24 quad_perm:[3,3,3,3] row_mask:0xf bank_mask:0xf
	v_fmac_f32_dpp v116, -v204, v25 quad_perm:[0,0,0,0] row_mask:0xf bank_mask:0xf
	v_fmac_f32_dpp v117, -v205, v27 quad_perm:[0,0,0,0] row_mask:0xf bank_mask:0xf
	ds_read_b64 v[186:187], v125 offset:6016
	v_add_f32_e32 v121, v117, v116
	v_mfma_f32_32x32x2_f32 v[148:163], v222, v129, v[148:163]
	v_add_f32_e32 v122, v118, v119
	v_add_f32_e32 v28, v122, v121
	s_waitcnt lgkmcnt(12)
; __device__ __forceinline__ float bf2f(bf16 v) { return __uint_as_float(((unsigned)v) << 16); }
; #define GDN_LOADROW(buf, rr_, i_) do { _Pragma("unroll") for (int j4 = 0; j4 < ((i_) + 3) / 4; ++j4) buf[j4] = *(const f32x4*)(Lm + (i_) * GP_LSTR + 4 * j4); rr_ = bf2f(*(const bf16*)(xsrc + (i_) * GP_STR * 2)) * scl[i_]; } while (0)
; template <int STRIP> __device__ __forceinline__ void ph_gdn_prep_fast(const bf16* __restrict__ proj, const float* __restrict__ small, const float* __restrict__ conv_w, const float* __restrict__ a_log, const float* __restrict__ dt_bias, ...
;     ...
;             rA = bf2f(*(const bf16*)xsrc) * scl[0];
;     ...
; #pragma unroll
;             for (int i = 0; i < 64; i += 2) {
;                 GDN_LOADROW(bB, rB, i + 1);
;                 GDN_ROW(bA, rA, i);
;                 if (i + 2 < 64) GDN_LOADROW(bA, rA, i + 2);
;                 GDN_ROW(bB, rB, i + 1);
;             }
	v_mul_f32_dpp v120, v206, v4 quad_perm:[0,0,0,0] row_mask:0xf bank_mask:0xf
	v_fma_f32 v116, v211, v251, -v120
	v_mul_f32_dpp v117, -v207, v5 quad_perm:[0,0,0,0] row_mask:0xf bank_mask:0xf
	v_mul_f32_dpp v118, -v206, v6 quad_perm:[1,1,1,1] row_mask:0xf bank_mask:0xf
	v_mul_f32_dpp v119, -v207, v12 quad_perm:[1,1,1,1] row_mask:0xf bank_mask:0xf
	ds_read_b64 v[188:189], v125 offset:6048
	v_fmac_f32_dpp v116, -v206, v7 quad_perm:[2,2,2,2] row_mask:0xf bank_mask:0xf
	v_fmac_f32_dpp v117, -v207, v13 quad_perm:[2,2,2,2] row_mask:0xf bank_mask:0xf
	v_fmac_f32_dpp v118, -v206, v14 quad_perm:[3,3,3,3] row_mask:0xf bank_mask:0xf
	ds_read_b32 v214, v124 offset:88
	v_fmac_f32_dpp v119, -v207, v15 quad_perm:[3,3,3,3] row_mask:0xf bank_mask:0xf
	v_fmac_f32_dpp v116, -v164, v16 quad_perm:[0,0,0,0] row_mask:0xf bank_mask:0xf
	v_fmac_f32_dpp v117, -v165, v17 quad_perm:[0,0,0,0] row_mask:0xf bank_mask:0xf
	ds_read_u16_d16_hi v126, v123 offset:5984
	v_fmac_f32_dpp v118, -v164, v19 quad_perm:[1,1,1,1] row_mask:0xf bank_mask:0xf
	v_fmac_f32_dpp v119, -v165, v20 quad_perm:[1,1,1,1] row_mask:0xf bank_mask:0xf
	v_fmac_f32_dpp v116, -v164, v21 quad_perm:[2,2,2,2] row_mask:0xf bank_mask:0xf
	ds_read_b64 v[190:191], v125 offset:6256
	v_fmac_f32_dpp v117, -v165, v22 quad_perm:[2,2,2,2] row_mask:0xf bank_mask:0xf
	v_fmac_f32_dpp v118, -v164, v23 quad_perm:[3,3,3,3] row_mask:0xf bank_mask:0xf
	v_fmac_f32_dpp v119, -v165, v24 quad_perm:[3,3,3,3] row_mask:0xf bank_mask:0xf
	ds_read_b64 v[192:193], v125 offset:6288
	v_fmac_f32_dpp v116, -v166, v25 quad_perm:[0,0,0,0] row_mask:0xf bank_mask:0xf
	v_fmac_f32_dpp v117, -v167, v27 quad_perm:[0,0,0,0] row_mask:0xf bank_mask:0xf
	v_fmac_f32_dpp v118, -v166, v28 quad_perm:[1,1,1,1] row_mask:0xf bank_mask:0xf
	ds_read_b64 v[194:195], v125 offset:6320
	v_add_f32_e32 v121, v117, v116
	v_add_f32_e32 v122, v118, v119
	v_add_f32_e32 v29, v122, v121
	v_mov_b32_e32 v220, v28
	v_mov_b32_e32 v221, v29
	s_waitcnt lgkmcnt(13)
	v_mul_f32_dpp v120, v168, v4 quad_perm:[0,0,0,0] row_mask:0xf bank_mask:0xf
	v_fma_f32 v116, v212, v252, -v120
	v_permlane32_swap_b32_e32 v220, v221
	v_mul_f32_dpp v117, -v169, v5 quad_perm:[0,0,0,0] row_mask:0xf bank_mask:0xf
	v_mul_f32_dpp v118, -v168, v6 quad_perm:[1,1,1,1] row_mask:0xf bank_mask:0xf
	v_mfma_f32_32x32x2_f32 v[132:147], v223, v220, v[132:147]
	v_mul_f32_dpp v119, -v169, v12 quad_perm:[1,1,1,1] row_mask:0xf bank_mask:0xf
	ds_read_b32 v215, v124 offset:92
	v_fmac_f32_dpp v116, -v168, v7 quad_perm:[2,2,2,2] row_mask:0xf bank_mask:0xf
	v_fmac_f32_dpp v117, -v169, v13 quad_perm:[2,2,2,2] row_mask:0xf bank_mask:0xf
	v_fmac_f32_dpp v118, -v168, v14 quad_perm:[3,3,3,3] row_mask:0xf bank_mask:0xf
	ds_read_u16_d16_hi v127, v123 offset:6256
	v_fmac_f32_dpp v119, -v169, v15 quad_perm:[3,3,3,3] row_mask:0xf bank_mask:0xf
	v_fmac_f32_dpp v116, -v170, v16 quad_perm:[0,0,0,0] row_mask:0xf bank_mask:0xf
	v_fmac_f32_dpp v117, -v171, v17 quad_perm:[0,0,0,0] row_mask:0xf bank_mask:0xf
	ds_read_b64 v[196:197], v125 offset:6528
	v_fmac_f32_dpp v118, -v170, v19 quad_perm:[1,1,1,1] row_mask:0xf bank_mask:0xf
	v_fmac_f32_dpp v119, -v171, v20 quad_perm:[1,1,1,1] row_mask:0xf bank_mask:0xf
	v_fmac_f32_dpp v116, -v170, v21 quad_perm:[2,2,2,2] row_mask:0xf bank_mask:0xf
	ds_read_b64 v[198:199], v125 offset:6560
	v_fmac_f32_dpp v117, -v171, v22 quad_perm:[2,2,2,2] row_mask:0xf bank_mask:0xf
	v_fmac_f32_dpp v118, -v170, v23 quad_perm:[3,3,3,3] row_mask:0xf bank_mask:0xf
	v_fmac_f32_dpp v119, -v171, v24 quad_perm:[3,3,3,3] row_mask:0xf bank_mask:0xf
	ds_read_b64 v[200:201], v125 offset:6592
	v_fmac_f32_dpp v116, -v84, v25 quad_perm:[0,0,0,0] row_mask:0xf bank_mask:0xf
	v_fmac_f32_dpp v117, -v85, v27 quad_perm:[0,0,0,0] row_mask:0xf bank_mask:0xf
	v_fmac_f32_dpp v118, -v84, v28 quad_perm:[1,1,1,1] row_mask:0xf bank_mask:0xf
	v_mfma_f32_32x32x2_f32 v[148:163], v223, v221, v[148:163]
	ds_read_b32 v216, v124 offset:96
	v_fmac_f32_dpp v119, -v85, v29 quad_perm:[1,1,1,1] row_mask:0xf bank_mask:0xf
	v_add_f32_e32 v121, v117, v116
	v_add_f32_e32 v122, v118, v119
	v_add_f32_e32 v30, v122, v121
	s_waitcnt lgkmcnt(14)
	v_mul_f32_dpp v120, v86, v4 quad_perm:[0,0,0,0] row_mask:0xf bank_mask:0xf
	v_fma_f32 v116, v213, v253, -v120
	v_mul_f32_dpp v117, -v87, v5 quad_perm:[0,0,0,0] row_mask:0xf bank_mask:0xf
	v_mul_f32_dpp v118, -v86, v6 quad_perm:[1,1,1,1] row_mask:0xf bank_mask:0xf
	ds_read_u16_d16_hi v244, v123 offset:6528
	v_mul_f32_dpp v119, -v87, v12 quad_perm:[1,1,1,1] row_mask:0xf bank_mask:0xf
	v_fmac_f32_dpp v116, -v86, v7 quad_perm:[2,2,2,2] row_mask:0xf bank_mask:0xf
	v_fmac_f32_dpp v117, -v87, v13 quad_perm:[2,2,2,2] row_mask:0xf bank_mask:0xf
	v_fmac_f32_dpp v118, -v86, v14 quad_perm:[3,3,3,3] row_mask:0xf bank_mask:0xf
	v_fmac_f32_dpp v119, -v87, v15 quad_perm:[3,3,3,3] row_mask:0xf bank_mask:0xf
	v_fmac_f32_dpp v116, -v88, v16 quad_perm:[0,0,0,0] row_mask:0xf bank_mask:0xf
	v_fmac_f32_dpp v117, -v89, v17 quad_perm:[0,0,0,0] row_mask:0xf bank_mask:0xf
	v_fmac_f32_dpp v118, -v88, v19 quad_perm:[1,1,1,1] row_mask:0xf bank_mask:0xf
	v_fmac_f32_dpp v119, -v89, v20 quad_perm:[1,1,1,1] row_mask:0xf bank_mask:0xf
	v_fmac_f32_dpp v116, -v88, v21 quad_perm:[2,2,2,2] row_mask:0xf bank_mask:0xf
	v_fmac_f32_dpp v117, -v89, v22 quad_perm:[2,2,2,2] row_mask:0xf bank_mask:0xf
	v_fmac_f32_dpp v118, -v88, v23 quad_perm:[3,3,3,3] row_mask:0xf bank_mask:0xf
	v_fmac_f32_dpp v119, -v89, v24 quad_perm:[3,3,3,3] row_mask:0xf bank_mask:0xf
	v_fmac_f32_dpp v116, -v90, v25 quad_perm:[0,0,0,0] row_mask:0xf bank_mask:0xf
	v_fmac_f32_dpp v117, -v91, v27 quad_perm:[0,0,0,0] row_mask:0xf bank_mask:0xf
	v_fmac_f32_dpp v118, -v90, v28 quad_perm:[1,1,1,1] row_mask:0xf bank_mask:0xf
	v_fmac_f32_dpp v119, -v91, v29 quad_perm:[1,1,1,1] row_mask:0xf bank_mask:0xf
	v_fmac_f32_dpp v116, -v90, v30 quad_perm:[2,2,2,2] row_mask:0xf bank_mask:0xf
	v_add_f32_e32 v121, v117, v116
	v_add_f32_e32 v122, v118, v119
	v_add_f32_e32 v31, v122, v121
	v_mov_b32_e32 v128, v30
	v_mov_b32_e32 v129, v31
	s_waitcnt lgkmcnt(10)
; __device__ __forceinline__ float bf2f(bf16 v) { return __uint_as_float(((unsigned)v) << 16); }
; #define GDN_LOADROW(buf, rr_, i_) do { _Pragma("unroll") for (int j4 = 0; j4 < ((i_) + 3) / 4; ++j4) buf[j4] = *(const f32x4*)(Lm + (i_) * GP_LSTR + 4 * j4); rr_ = bf2f(*(const bf16*)(xsrc + (i_) * GP_STR * 2)) * scl[i_]; } while (0)
; template <int STRIP> __device__ __forceinline__ void ph_gdn_prep_fast(const bf16* __restrict__ proj, const float* __restrict__ small, const float* __restrict__ conv_w, const float* __restrict__ a_log, const float* __restrict__ dt_bias, ...
;     ...
;             rA = bf2f(*(const bf16*)xsrc) * scl[0];
;     ...
; #pragma unroll
;             for (int i = 0; i < 64; i += 2) {
;                 GDN_LOADROW(bB, rB, i + 1);
;                 GDN_ROW(bA, rA, i);
;                 if (i + 2 < 64) GDN_LOADROW(bA, rA, i + 2);
;                 GDN_ROW(bB, rB, i + 1);
;             }
	v_mul_f32_dpp v120, v92, v4 quad_perm:[0,0,0,0] row_mask:0xf bank_mask:0xf
	v_fma_f32 v116, v214, v126, -v120
	v_permlane32_swap_b32_e32 v128, v129
	v_mul_f32_dpp v117, -v93, v5 quad_perm:[0,0,0,0] row_mask:0xf bank_mask:0xf
	v_mul_f32_dpp v118, -v92, v6 quad_perm:[1,1,1,1] row_mask:0xf bank_mask:0xf
	v_mfma_f32_32x32x2_f32 v[132:147], v224, v128, v[132:147]
	v_mul_f32_dpp v119, -v93, v12 quad_perm:[1,1,1,1] row_mask:0xf bank_mask:0xf
	ds_read_b64 v[202:203], v125 offset:6800
	v_fmac_f32_dpp v116, -v92, v7 quad_perm:[2,2,2,2] row_mask:0xf bank_mask:0xf
	v_fmac_f32_dpp v117, -v93, v13 quad_perm:[2,2,2,2] row_mask:0xf bank_mask:0xf
	v_fmac_f32_dpp v118, -v92, v14 quad_perm:[3,3,3,3] row_mask:0xf bank_mask:0xf
	ds_read_b64 v[204:205], v125 offset:6832
	v_fmac_f32_dpp v119, -v93, v15 quad_perm:[3,3,3,3] row_mask:0xf bank_mask:0xf
	v_fmac_f32_dpp v116, -v186, v16 quad_perm:[0,0,0,0] row_mask:0xf bank_mask:0xf
	v_fmac_f32_dpp v117, -v187, v17 quad_perm:[0,0,0,0] row_mask:0xf bank_mask:0xf
	ds_read_b64 v[206:207], v125 offset:6864
	v_fmac_f32_dpp v118, -v186, v19 quad_perm:[1,1,1,1] row_mask:0xf bank_mask:0xf
	v_fmac_f32_dpp v119, -v187, v20 quad_perm:[1,1,1,1] row_mask:0xf bank_mask:0xf
	v_fmac_f32_dpp v116, -v186, v21 quad_perm:[2,2,2,2] row_mask:0xf bank_mask:0xf
	ds_read_b64 v[164:165], v125 offset:6896
	v_fmac_f32_dpp v117, -v187, v22 quad_perm:[2,2,2,2] row_mask:0xf bank_mask:0xf
	v_fmac_f32_dpp v118, -v186, v23 quad_perm:[3,3,3,3] row_mask:0xf bank_mask:0xf
	v_fmac_f32_dpp v119, -v187, v24 quad_perm:[3,3,3,3] row_mask:0xf bank_mask:0xf
	ds_read_b32 v217, v124 offset:100
	v_fmac_f32_dpp v116, -v188, v25 quad_perm:[0,0,0,0] row_mask:0xf bank_mask:0xf
	v_fmac_f32_dpp v117, -v189, v27 quad_perm:[0,0,0,0] row_mask:0xf bank_mask:0xf
	v_fmac_f32_dpp v118, -v188, v28 quad_perm:[1,1,1,1] row_mask:0xf bank_mask:0xf
	v_mfma_f32_32x32x2_f32 v[148:163], v224, v129, v[148:163]
	ds_read_u16_d16_hi v245, v123 offset:6800
	v_fmac_f32_dpp v119, -v189, v29 quad_perm:[1,1,1,1] row_mask:0xf bank_mask:0xf
	v_fmac_f32_dpp v116, -v188, v30 quad_perm:[2,2,2,2] row_mask:0xf bank_mask:0xf
	v_fmac_f32_dpp v117, -v189, v31 quad_perm:[2,2,2,2] row_mask:0xf bank_mask:0xf
	v_add_f32_e32 v121, v117, v116
	v_add_f32_e32 v122, v118, v119
	v_add_f32_e32 v32, v122, v121
	s_waitcnt lgkmcnt(11)
	v_mul_f32_dpp v120, v190, v4 quad_perm:[0,0,0,0] row_mask:0xf bank_mask:0xf
	v_fma_f32 v116, v215, v127, -v120
	v_mul_f32_dpp v117, -v191, v5 quad_perm:[0,0,0,0] row_mask:0xf bank_mask:0xf
	v_mul_f32_dpp v118, -v190, v6 quad_perm:[1,1,1,1] row_mask:0xf bank_mask:0xf
	v_mul_f32_dpp v119, -v191, v12 quad_perm:[1,1,1,1] row_mask:0xf bank_mask:0xf
	ds_read_b64 v[166:167], v125 offset:7072
	v_fmac_f32_dpp v116, -v190, v7 quad_perm:[2,2,2,2] row_mask:0xf bank_mask:0xf
	v_fmac_f32_dpp v117, -v191, v13 quad_perm:[2,2,2,2] row_mask:0xf bank_mask:0xf
	v_fmac_f32_dpp v118, -v190, v14 quad_perm:[3,3,3,3] row_mask:0xf bank_mask:0xf
	ds_read_b64 v[168:169], v125 offset:7104
	v_fmac_f32_dpp v119, -v191, v15 quad_perm:[3,3,3,3] row_mask:0xf bank_mask:0xf
	v_fmac_f32_dpp v116, -v192, v16 quad_perm:[0,0,0,0] row_mask:0xf bank_mask:0xf
	v_fmac_f32_dpp v117, -v193, v17 quad_perm:[0,0,0,0] row_mask:0xf bank_mask:0xf
	ds_read_b64 v[170:171], v125 offset:7136
	v_fmac_f32_dpp v118, -v192, v19 quad_perm:[1,1,1,1] row_mask:0xf bank_mask:0xf
	v_fmac_f32_dpp v119, -v193, v20 quad_perm:[1,1,1,1] row_mask:0xf bank_mask:0xf
	v_fmac_f32_dpp v116, -v192, v21 quad_perm:[2,2,2,2] row_mask:0xf bank_mask:0xf
	ds_read_b64 v[84:85], v125 offset:7168
	v_fmac_f32_dpp v117, -v193, v22 quad_perm:[2,2,2,2] row_mask:0xf bank_mask:0xf
	v_fmac_f32_dpp v118, -v192, v23 quad_perm:[3,3,3,3] row_mask:0xf bank_mask:0xf
	v_fmac_f32_dpp v119, -v193, v24 quad_perm:[3,3,3,3] row_mask:0xf bank_mask:0xf
	ds_read_b32 v218, v124 offset:104
	v_fmac_f32_dpp v116, -v194, v25 quad_perm:[0,0,0,0] row_mask:0xf bank_mask:0xf
	v_fmac_f32_dpp v117, -v195, v27 quad_perm:[0,0,0,0] row_mask:0xf bank_mask:0xf
	v_fmac_f32_dpp v118, -v194, v28 quad_perm:[1,1,1,1] row_mask:0xf bank_mask:0xf
	ds_read_u16_d16_hi v246, v123 offset:7072
	v_fmac_f32_dpp v119, -v195, v29 quad_perm:[1,1,1,1] row_mask:0xf bank_mask:0xf
	v_fmac_f32_dpp v116, -v194, v30 quad_perm:[2,2,2,2] row_mask:0xf bank_mask:0xf
	v_fmac_f32_dpp v117, -v195, v31 quad_perm:[2,2,2,2] row_mask:0xf bank_mask:0xf
	v_fmac_f32_dpp v118, -v194, v32 quad_perm:[3,3,3,3] row_mask:0xf bank_mask:0xf
	v_add_f32_e32 v121, v117, v116
	v_add_f32_e32 v122, v118, v119
	v_add_f32_e32 v33, v122, v121
	v_mov_b32_e32 v220, v32
	v_mov_b32_e32 v221, v33
	s_waitcnt lgkmcnt(12)
; __device__ __forceinline__ float bf2f(bf16 v) { return __uint_as_float(((unsigned)v) << 16); }
; #define GDN_LOADROW(buf, rr_, i_) do { _Pragma("unroll") for (int j4 = 0; j4 < ((i_) + 3) / 4; ++j4) buf[j4] = *(const f32x4*)(Lm + (i_) * GP_LSTR + 4 * j4); rr_ = bf2f(*(const bf16*)(xsrc + (i_) * GP_STR * 2)) * scl[i_]; } while (0)
; template <int STRIP> __device__ __forceinline__ void ph_gdn_prep_fast(const bf16* __restrict__ proj, const float* __restrict__ small, const float* __restrict__ conv_w, const float* __restrict__ a_log, const float* __restrict__ dt_bias, ...
;     ...
;             rA = bf2f(*(const bf16*)xsrc) * scl[0];
;     ...
; #pragma unroll
;             for (int i = 0; i < 64; i += 2) {
;                 GDN_LOADROW(bB, rB, i + 1);
;                 GDN_ROW(bA, rA, i);
;                 if (i + 2 < 64) GDN_LOADROW(bA, rA, i + 2);
;                 GDN_ROW(bB, rB, i + 1);
;             }
	v_mul_f32_dpp v120, v196, v4 quad_perm:[0,0,0,0] row_mask:0xf bank_mask:0xf
	v_fma_f32 v116, v216, v244, -v120
	v_permlane32_swap_b32_e32 v220, v221
	v_mul_f32_dpp v117, -v197, v5 quad_perm:[0,0,0,0] row_mask:0xf bank_mask:0xf
	v_mul_f32_dpp v118, -v196, v6 quad_perm:[1,1,1,1] row_mask:0xf bank_mask:0xf
	v_mfma_f32_32x32x2_f32 v[132:147], v225, v220, v[132:147]
	ds_read_b64 v[86:87], v125 offset:7344
	v_mul_f32_dpp v119, -v197, v12 quad_perm:[1,1,1,1] row_mask:0xf bank_mask:0xf
	v_fmac_f32_dpp v116, -v196, v7 quad_perm:[2,2,2,2] row_mask:0xf bank_mask:0xf
	v_fmac_f32_dpp v117, -v197, v13 quad_perm:[2,2,2,2] row_mask:0xf bank_mask:0xf
	ds_read_b64 v[88:89], v125 offset:7376
	v_fmac_f32_dpp v118, -v196, v14 quad_perm:[3,3,3,3] row_mask:0xf bank_mask:0xf
	v_fmac_f32_dpp v119, -v197, v15 quad_perm:[3,3,3,3] row_mask:0xf bank_mask:0xf
	v_fmac_f32_dpp v116, -v198, v16 quad_perm:[0,0,0,0] row_mask:0xf bank_mask:0xf
	ds_read_b64 v[90:91], v125 offset:7408
	v_fmac_f32_dpp v117, -v199, v17 quad_perm:[0,0,0,0] row_mask:0xf bank_mask:0xf
	v_fmac_f32_dpp v118, -v198, v19 quad_perm:[1,1,1,1] row_mask:0xf bank_mask:0xf
	v_fmac_f32_dpp v119, -v199, v20 quad_perm:[1,1,1,1] row_mask:0xf bank_mask:0xf
	ds_read_b64 v[92:93], v125 offset:7440
	v_fmac_f32_dpp v116, -v198, v21 quad_perm:[2,2,2,2] row_mask:0xf bank_mask:0xf
	v_fmac_f32_dpp v117, -v199, v22 quad_perm:[2,2,2,2] row_mask:0xf bank_mask:0xf
	v_fmac_f32_dpp v118, -v198, v23 quad_perm:[3,3,3,3] row_mask:0xf bank_mask:0xf
	ds_read_b32 v219, v124 offset:108
	v_fmac_f32_dpp v119, -v199, v24 quad_perm:[3,3,3,3] row_mask:0xf bank_mask:0xf
	v_fmac_f32_dpp v116, -v200, v25 quad_perm:[0,0,0,0] row_mask:0xf bank_mask:0xf
	v_fmac_f32_dpp v117, -v201, v27 quad_perm:[0,0,0,0] row_mask:0xf bank_mask:0xf
	ds_read_u16_d16_hi v247, v123 offset:7344
	v_fmac_f32_dpp v118, -v200, v28 quad_perm:[1,1,1,1] row_mask:0xf bank_mask:0xf
	v_mfma_f32_32x32x2_f32 v[148:163], v225, v221, v[148:163]
	v_fmac_f32_dpp v119, -v201, v29 quad_perm:[1,1,1,1] row_mask:0xf bank_mask:0xf
	v_fmac_f32_dpp v116, -v200, v30 quad_perm:[2,2,2,2] row_mask:0xf bank_mask:0xf
	v_fmac_f32_dpp v117, -v201, v31 quad_perm:[2,2,2,2] row_mask:0xf bank_mask:0xf
	v_fmac_f32_dpp v118, -v200, v32 quad_perm:[3,3,3,3] row_mask:0xf bank_mask:0xf
	v_fmac_f32_dpp v119, -v201, v33 quad_perm:[3,3,3,3] row_mask:0xf bank_mask:0xf
	v_add_f32_e32 v121, v117, v116
	v_add_f32_e32 v122, v118, v119
	v_add_f32_e32 v34, v122, v121
	s_waitcnt lgkmcnt(12)
	v_mul_f32_dpp v120, v202, v4 quad_perm:[0,0,0,0] row_mask:0xf bank_mask:0xf
	v_fma_f32 v116, v217, v245, -v120
	v_mul_f32_dpp v117, -v203, v5 quad_perm:[0,0,0,0] row_mask:0xf bank_mask:0xf
	v_mul_f32_dpp v118, -v202, v6 quad_perm:[1,1,1,1] row_mask:0xf bank_mask:0xf
	v_mul_f32_dpp v119, -v203, v12 quad_perm:[1,1,1,1] row_mask:0xf bank_mask:0xf
	ds_read_b64 v[186:187], v125 offset:7616
	v_fmac_f32_dpp v116, -v202, v7 quad_perm:[2,2,2,2] row_mask:0xf bank_mask:0xf
	v_fmac_f32_dpp v117, -v203, v13 quad_perm:[2,2,2,2] row_mask:0xf bank_mask:0xf
	v_fmac_f32_dpp v118, -v202, v14 quad_perm:[3,3,3,3] row_mask:0xf bank_mask:0xf
	ds_read_b64 v[188:189], v125 offset:7648
	v_fmac_f32_dpp v119, -v203, v15 quad_perm:[3,3,3,3] row_mask:0xf bank_mask:0xf
	v_fmac_f32_dpp v116, -v204, v16 quad_perm:[0,0,0,0] row_mask:0xf bank_mask:0xf
	v_fmac_f32_dpp v117, -v205, v17 quad_perm:[0,0,0,0] row_mask:0xf bank_mask:0xf
	ds_read_b64 v[190:191], v125 offset:7680
	v_fmac_f32_dpp v118, -v204, v19 quad_perm:[1,1,1,1] row_mask:0xf bank_mask:0xf
	v_fmac_f32_dpp v119, -v205, v20 quad_perm:[1,1,1,1] row_mask:0xf bank_mask:0xf
	v_fmac_f32_dpp v116, -v204, v21 quad_perm:[2,2,2,2] row_mask:0xf bank_mask:0xf
	ds_read_b64 v[192:193], v125 offset:7712
	v_fmac_f32_dpp v117, -v205, v22 quad_perm:[2,2,2,2] row_mask:0xf bank_mask:0xf
	v_fmac_f32_dpp v118, -v204, v23 quad_perm:[3,3,3,3] row_mask:0xf bank_mask:0xf
	v_fmac_f32_dpp v119, -v205, v24 quad_perm:[3,3,3,3] row_mask:0xf bank_mask:0xf
	ds_read_b32 v181, v124 offset:112
	v_fmac_f32_dpp v116, -v206, v25 quad_perm:[0,0,0,0] row_mask:0xf bank_mask:0xf
	v_fmac_f32_dpp v117, -v207, v27 quad_perm:[0,0,0,0] row_mask:0xf bank_mask:0xf
	v_fmac_f32_dpp v118, -v206, v28 quad_perm:[1,1,1,1] row_mask:0xf bank_mask:0xf
	ds_read_u16_d16_hi v248, v123 offset:7616
	v_fmac_f32_dpp v119, -v207, v29 quad_perm:[1,1,1,1] row_mask:0xf bank_mask:0xf
	v_fmac_f32_dpp v116, -v206, v30 quad_perm:[2,2,2,2] row_mask:0xf bank_mask:0xf
	v_fmac_f32_dpp v117, -v207, v31 quad_perm:[2,2,2,2] row_mask:0xf bank_mask:0xf
	v_fmac_f32_dpp v118, -v206, v32 quad_perm:[3,3,3,3] row_mask:0xf bank_mask:0xf
	v_fmac_f32_dpp v119, -v207, v33 quad_perm:[3,3,3,3] row_mask:0xf bank_mask:0xf
	v_fmac_f32_dpp v116, -v164, v34 quad_perm:[0,0,0,0] row_mask:0xf bank_mask:0xf
	v_add_f32_e32 v121, v117, v116
	v_add_f32_e32 v122, v118, v119
	v_add_f32_e32 v35, v122, v121
	v_mov_b32_e32 v128, v34
	v_mov_b32_e32 v129, v35
	s_waitcnt lgkmcnt(12)
; __device__ __forceinline__ float bf2f(bf16 v) { return __uint_as_float(((unsigned)v) << 16); }
; #define GDN_LOADROW(buf, rr_, i_) do { _Pragma("unroll") for (int j4 = 0; j4 < ((i_) + 3) / 4; ++j4) buf[j4] = *(const f32x4*)(Lm + (i_) * GP_LSTR + 4 * j4); rr_ = bf2f(*(const bf16*)(xsrc + (i_) * GP_STR * 2)) * scl[i_]; } while (0)
; template <int STRIP> __device__ __forceinline__ void ph_gdn_prep_fast(const bf16* __restrict__ proj, const float* __restrict__ small, const float* __restrict__ conv_w, const float* __restrict__ a_log, const float* __restrict__ dt_bias, ...
;     ...
;             rA = bf2f(*(const bf16*)xsrc) * scl[0];
;     ...
; #pragma unroll
;             for (int i = 0; i < 64; i += 2) {
;                 GDN_LOADROW(bB, rB, i + 1);
;                 GDN_ROW(bA, rA, i);
;                 if (i + 2 < 64) GDN_LOADROW(bA, rA, i + 2);
;                 GDN_ROW(bB, rB, i + 1);
;             }
	v_mul_f32_dpp v120, v166, v4 quad_perm:[0,0,0,0] row_mask:0xf bank_mask:0xf
	v_fma_f32 v116, v218, v246, -v120
	v_permlane32_swap_b32_e32 v128, v129
	v_mul_f32_dpp v117, -v167, v5 quad_perm:[0,0,0,0] row_mask:0xf bank_mask:0xf
	v_mul_f32_dpp v118, -v166, v6 quad_perm:[1,1,1,1] row_mask:0xf bank_mask:0xf
	v_mfma_f32_32x32x2_f32 v[132:147], v226, v128, v[132:147]
	v_mul_f32_dpp v119, -v167, v12 quad_perm:[1,1,1,1] row_mask:0xf bank_mask:0xf
	ds_read_b64 v[194:195], v125 offset:7888
	v_fmac_f32_dpp v116, -v166, v7 quad_perm:[2,2,2,2] row_mask:0xf bank_mask:0xf
	v_fmac_f32_dpp v117, -v167, v13 quad_perm:[2,2,2,2] row_mask:0xf bank_mask:0xf
	v_fmac_f32_dpp v118, -v166, v14 quad_perm:[3,3,3,3] row_mask:0xf bank_mask:0xf
	ds_read_b64 v[196:197], v125 offset:7920
	v_fmac_f32_dpp v119, -v167, v15 quad_perm:[3,3,3,3] row_mask:0xf bank_mask:0xf
	v_fmac_f32_dpp v116, -v168, v16 quad_perm:[0,0,0,0] row_mask:0xf bank_mask:0xf
	v_fmac_f32_dpp v117, -v169, v17 quad_perm:[0,0,0,0] row_mask:0xf bank_mask:0xf
	ds_read_b64 v[198:199], v125 offset:7952
	v_fmac_f32_dpp v118, -v168, v19 quad_perm:[1,1,1,1] row_mask:0xf bank_mask:0xf
	v_fmac_f32_dpp v119, -v169, v20 quad_perm:[1,1,1,1] row_mask:0xf bank_mask:0xf
	v_fmac_f32_dpp v116, -v168, v21 quad_perm:[2,2,2,2] row_mask:0xf bank_mask:0xf
	ds_read_b64 v[200:201], v125 offset:7984
	v_fmac_f32_dpp v117, -v169, v22 quad_perm:[2,2,2,2] row_mask:0xf bank_mask:0xf
	v_fmac_f32_dpp v118, -v168, v23 quad_perm:[3,3,3,3] row_mask:0xf bank_mask:0xf
	v_fmac_f32_dpp v119, -v169, v24 quad_perm:[3,3,3,3] row_mask:0xf bank_mask:0xf
	ds_read_b32 v182, v124 offset:116
	v_fmac_f32_dpp v116, -v170, v25 quad_perm:[0,0,0,0] row_mask:0xf bank_mask:0xf
	v_fmac_f32_dpp v117, -v171, v27 quad_perm:[0,0,0,0] row_mask:0xf bank_mask:0xf
	v_fmac_f32_dpp v118, -v170, v28 quad_perm:[1,1,1,1] row_mask:0xf bank_mask:0xf
	v_mfma_f32_32x32x2_f32 v[148:163], v226, v129, v[148:163]
	ds_read_u16_d16_hi v249, v123 offset:7888
	v_fmac_f32_dpp v119, -v171, v29 quad_perm:[1,1,1,1] row_mask:0xf bank_mask:0xf
	v_fmac_f32_dpp v116, -v170, v30 quad_perm:[2,2,2,2] row_mask:0xf bank_mask:0xf
	v_fmac_f32_dpp v117, -v171, v31 quad_perm:[2,2,2,2] row_mask:0xf bank_mask:0xf
	v_fmac_f32_dpp v118, -v170, v32 quad_perm:[3,3,3,3] row_mask:0xf bank_mask:0xf
	v_fmac_f32_dpp v119, -v171, v33 quad_perm:[3,3,3,3] row_mask:0xf bank_mask:0xf
	v_fmac_f32_dpp v116, -v84, v34 quad_perm:[0,0,0,0] row_mask:0xf bank_mask:0xf
	v_fmac_f32_dpp v117, -v85, v35 quad_perm:[0,0,0,0] row_mask:0xf bank_mask:0xf
	v_add_f32_e32 v121, v117, v116
	v_add_f32_e32 v122, v118, v119
	v_add_f32_e32 v36, v122, v121
	s_waitcnt lgkmcnt(12)
	v_mul_f32_dpp v120, v86, v4 quad_perm:[0,0,0,0] row_mask:0xf bank_mask:0xf
	v_fma_f32 v116, v219, v247, -v120
	v_mul_f32_dpp v117, -v87, v5 quad_perm:[0,0,0,0] row_mask:0xf bank_mask:0xf
	v_mul_f32_dpp v118, -v86, v6 quad_perm:[1,1,1,1] row_mask:0xf bank_mask:0xf
	ds_read_b64 v[202:203], v125 offset:8160
	v_mul_f32_dpp v119, -v87, v12 quad_perm:[1,1,1,1] row_mask:0xf bank_mask:0xf
	v_fmac_f32_dpp v116, -v86, v7 quad_perm:[2,2,2,2] row_mask:0xf bank_mask:0xf
	v_fmac_f32_dpp v117, -v87, v13 quad_perm:[2,2,2,2] row_mask:0xf bank_mask:0xf
	ds_read_b64 v[204:205], v125 offset:8192
	v_fmac_f32_dpp v118, -v86, v14 quad_perm:[3,3,3,3] row_mask:0xf bank_mask:0xf
	v_fmac_f32_dpp v119, -v87, v15 quad_perm:[3,3,3,3] row_mask:0xf bank_mask:0xf
	v_fmac_f32_dpp v116, -v88, v16 quad_perm:[0,0,0,0] row_mask:0xf bank_mask:0xf
	ds_read_b64 v[206:207], v125 offset:8224
	v_fmac_f32_dpp v117, -v89, v17 quad_perm:[0,0,0,0] row_mask:0xf bank_mask:0xf
	v_fmac_f32_dpp v118, -v88, v19 quad_perm:[1,1,1,1] row_mask:0xf bank_mask:0xf
	v_fmac_f32_dpp v119, -v89, v20 quad_perm:[1,1,1,1] row_mask:0xf bank_mask:0xf
	ds_read_b64 v[164:165], v125 offset:8256
	v_fmac_f32_dpp v116, -v88, v21 quad_perm:[2,2,2,2] row_mask:0xf bank_mask:0xf
	v_fmac_f32_dpp v117, -v89, v22 quad_perm:[2,2,2,2] row_mask:0xf bank_mask:0xf
	v_fmac_f32_dpp v118, -v88, v23 quad_perm:[3,3,3,3] row_mask:0xf bank_mask:0xf
	ds_read_b32 v183, v124 offset:120
	v_fmac_f32_dpp v119, -v89, v24 quad_perm:[3,3,3,3] row_mask:0xf bank_mask:0xf
	v_fmac_f32_dpp v116, -v90, v25 quad_perm:[0,0,0,0] row_mask:0xf bank_mask:0xf
	v_fmac_f32_dpp v117, -v91, v27 quad_perm:[0,0,0,0] row_mask:0xf bank_mask:0xf
	ds_read_u16_d16_hi v250, v123 offset:8160
	v_fmac_f32_dpp v118, -v90, v28 quad_perm:[1,1,1,1] row_mask:0xf bank_mask:0xf
	v_fmac_f32_dpp v119, -v91, v29 quad_perm:[1,1,1,1] row_mask:0xf bank_mask:0xf
	v_fmac_f32_dpp v116, -v90, v30 quad_perm:[2,2,2,2] row_mask:0xf bank_mask:0xf
	v_fmac_f32_dpp v117, -v91, v31 quad_perm:[2,2,2,2] row_mask:0xf bank_mask:0xf
	v_fmac_f32_dpp v118, -v90, v32 quad_perm:[3,3,3,3] row_mask:0xf bank_mask:0xf
	v_fmac_f32_dpp v119, -v91, v33 quad_perm:[3,3,3,3] row_mask:0xf bank_mask:0xf
	v_fmac_f32_dpp v116, -v92, v34 quad_perm:[0,0,0,0] row_mask:0xf bank_mask:0xf
	v_fmac_f32_dpp v117, -v93, v35 quad_perm:[0,0,0,0] row_mask:0xf bank_mask:0xf
	v_fmac_f32_dpp v118, -v92, v36 quad_perm:[1,1,1,1] row_mask:0xf bank_mask:0xf
	v_add_f32_e32 v121, v117, v116
	v_add_f32_e32 v122, v118, v119
	v_add_f32_e32 v37, v122, v121
	v_mov_b32_e32 v220, v36
	v_mov_b32_e32 v221, v37
	s_waitcnt lgkmcnt(12)
; __device__ __forceinline__ float bf2f(bf16 v) { return __uint_as_float(((unsigned)v) << 16); }
; #define GDN_LOADROW(buf, rr_, i_) do { _Pragma("unroll") for (int j4 = 0; j4 < ((i_) + 3) / 4; ++j4) buf[j4] = *(const f32x4*)(Lm + (i_) * GP_LSTR + 4 * j4); rr_ = bf2f(*(const bf16*)(xsrc + (i_) * GP_STR * 2)) * scl[i_]; } while (0)
; template <int STRIP> __device__ __forceinline__ void ph_gdn_prep_fast(const bf16* __restrict__ proj, const float* __restrict__ small, const float* __restrict__ conv_w, const float* __restrict__ a_log, const float* __restrict__ dt_bias, ...
;     ...
;             rA = bf2f(*(const bf16*)xsrc) * scl[0];
;     ...
; #pragma unroll
;             for (int i = 0; i < 64; i += 2) {
;                 GDN_LOADROW(bB, rB, i + 1);
;                 GDN_ROW(bA, rA, i);
;                 if (i + 2 < 64) GDN_LOADROW(bA, rA, i + 2);
;                 GDN_ROW(bB, rB, i + 1);
;             }
	v_mul_f32_dpp v120, v186, v4 quad_perm:[0,0,0,0] row_mask:0xf bank_mask:0xf
	v_fma_f32 v116, v181, v248, -v120
	v_permlane32_swap_b32_e32 v220, v221
	v_mul_f32_dpp v117, -v187, v5 quad_perm:[0,0,0,0] row_mask:0xf bank_mask:0xf
	v_mul_f32_dpp v118, -v186, v6 quad_perm:[1,1,1,1] row_mask:0xf bank_mask:0xf
	v_mfma_f32_32x32x2_f32 v[132:147], v227, v220, v[132:147]
	v_mul_f32_dpp v119, -v187, v12 quad_perm:[1,1,1,1] row_mask:0xf bank_mask:0xf
	ds_read_b64 v[166:167], v125 offset:8432
	v_fmac_f32_dpp v116, -v186, v7 quad_perm:[2,2,2,2] row_mask:0xf bank_mask:0xf
	v_fmac_f32_dpp v117, -v187, v13 quad_perm:[2,2,2,2] row_mask:0xf bank_mask:0xf
	v_fmac_f32_dpp v118, -v186, v14 quad_perm:[3,3,3,3] row_mask:0xf bank_mask:0xf
	ds_read_b64 v[168:169], v125 offset:8464
	v_fmac_f32_dpp v119, -v187, v15 quad_perm:[3,3,3,3] row_mask:0xf bank_mask:0xf
	v_fmac_f32_dpp v116, -v188, v16 quad_perm:[0,0,0,0] row_mask:0xf bank_mask:0xf
	v_fmac_f32_dpp v117, -v189, v17 quad_perm:[0,0,0,0] row_mask:0xf bank_mask:0xf
	ds_read_b64 v[170:171], v125 offset:8496
	v_fmac_f32_dpp v118, -v188, v19 quad_perm:[1,1,1,1] row_mask:0xf bank_mask:0xf
	v_fmac_f32_dpp v119, -v189, v20 quad_perm:[1,1,1,1] row_mask:0xf bank_mask:0xf
	v_fmac_f32_dpp v116, -v188, v21 quad_perm:[2,2,2,2] row_mask:0xf bank_mask:0xf
	ds_read_b64 v[84:85], v125 offset:8528
	v_fmac_f32_dpp v117, -v189, v22 quad_perm:[2,2,2,2] row_mask:0xf bank_mask:0xf
	v_fmac_f32_dpp v118, -v188, v23 quad_perm:[3,3,3,3] row_mask:0xf bank_mask:0xf
	v_fmac_f32_dpp v119, -v189, v24 quad_perm:[3,3,3,3] row_mask:0xf bank_mask:0xf
	ds_read_b32 v185, v124 offset:124
	v_fmac_f32_dpp v116, -v190, v25 quad_perm:[0,0,0,0] row_mask:0xf bank_mask:0xf
	v_fmac_f32_dpp v117, -v191, v27 quad_perm:[0,0,0,0] row_mask:0xf bank_mask:0xf
	v_fmac_f32_dpp v118, -v190, v28 quad_perm:[1,1,1,1] row_mask:0xf bank_mask:0xf
	v_mfma_f32_32x32x2_f32 v[148:163], v227, v221, v[148:163]
	ds_read_u16_d16_hi v251, v123 offset:8432
	v_fmac_f32_dpp v119, -v191, v29 quad_perm:[1,1,1,1] row_mask:0xf bank_mask:0xf
	v_fmac_f32_dpp v116, -v190, v30 quad_perm:[2,2,2,2] row_mask:0xf bank_mask:0xf
	v_fmac_f32_dpp v117, -v191, v31 quad_perm:[2,2,2,2] row_mask:0xf bank_mask:0xf
	v_fmac_f32_dpp v118, -v190, v32 quad_perm:[3,3,3,3] row_mask:0xf bank_mask:0xf
	v_fmac_f32_dpp v119, -v191, v33 quad_perm:[3,3,3,3] row_mask:0xf bank_mask:0xf
	v_fmac_f32_dpp v116, -v192, v34 quad_perm:[0,0,0,0] row_mask:0xf bank_mask:0xf
	v_fmac_f32_dpp v117, -v193, v35 quad_perm:[0,0,0,0] row_mask:0xf bank_mask:0xf
	v_fmac_f32_dpp v118, -v192, v36 quad_perm:[1,1,1,1] row_mask:0xf bank_mask:0xf
	v_fmac_f32_dpp v119, -v193, v37 quad_perm:[1,1,1,1] row_mask:0xf bank_mask:0xf
	v_add_f32_e32 v121, v117, v116
	v_add_f32_e32 v122, v118, v119
	v_add_f32_e32 v38, v122, v121
	s_waitcnt lgkmcnt(12)
	v_mul_f32_dpp v120, v194, v4 quad_perm:[0,0,0,0] row_mask:0xf bank_mask:0xf
	v_fma_f32 v116, v182, v249, -v120
	v_mul_f32_dpp v117, -v195, v5 quad_perm:[0,0,0,0] row_mask:0xf bank_mask:0xf
	v_mul_f32_dpp v118, -v194, v6 quad_perm:[1,1,1,1] row_mask:0xf bank_mask:0xf
	v_mul_f32_dpp v119, -v195, v12 quad_perm:[1,1,1,1] row_mask:0xf bank_mask:0xf
	v_fmac_f32_dpp v116, -v194, v7 quad_perm:[2,2,2,2] row_mask:0xf bank_mask:0xf
	v_fmac_f32_dpp v117, -v195, v13 quad_perm:[2,2,2,2] row_mask:0xf bank_mask:0xf
	v_fmac_f32_dpp v118, -v194, v14 quad_perm:[3,3,3,3] row_mask:0xf bank_mask:0xf
	v_fmac_f32_dpp v119, -v195, v15 quad_perm:[3,3,3,3] row_mask:0xf bank_mask:0xf
	v_fmac_f32_dpp v116, -v196, v16 quad_perm:[0,0,0,0] row_mask:0xf bank_mask:0xf
	v_fmac_f32_dpp v117, -v197, v17 quad_perm:[0,0,0,0] row_mask:0xf bank_mask:0xf
	v_fmac_f32_dpp v118, -v196, v19 quad_perm:[1,1,1,1] row_mask:0xf bank_mask:0xf
	v_fmac_f32_dpp v119, -v197, v20 quad_perm:[1,1,1,1] row_mask:0xf bank_mask:0xf
	v_fmac_f32_dpp v116, -v196, v21 quad_perm:[2,2,2,2] row_mask:0xf bank_mask:0xf
	v_fmac_f32_dpp v117, -v197, v22 quad_perm:[2,2,2,2] row_mask:0xf bank_mask:0xf
	v_fmac_f32_dpp v118, -v196, v23 quad_perm:[3,3,3,3] row_mask:0xf bank_mask:0xf
	v_fmac_f32_dpp v119, -v197, v24 quad_perm:[3,3,3,3] row_mask:0xf bank_mask:0xf
	v_fmac_f32_dpp v116, -v198, v25 quad_perm:[0,0,0,0] row_mask:0xf bank_mask:0xf
	v_fmac_f32_dpp v117, -v199, v27 quad_perm:[0,0,0,0] row_mask:0xf bank_mask:0xf
	v_fmac_f32_dpp v118, -v198, v28 quad_perm:[1,1,1,1] row_mask:0xf bank_mask:0xf
	v_fmac_f32_dpp v119, -v199, v29 quad_perm:[1,1,1,1] row_mask:0xf bank_mask:0xf
	v_fmac_f32_dpp v116, -v198, v30 quad_perm:[2,2,2,2] row_mask:0xf bank_mask:0xf
	v_fmac_f32_dpp v117, -v199, v31 quad_perm:[2,2,2,2] row_mask:0xf bank_mask:0xf
	v_fmac_f32_dpp v118, -v198, v32 quad_perm:[3,3,3,3] row_mask:0xf bank_mask:0xf
	v_fmac_f32_dpp v119, -v199, v33 quad_perm:[3,3,3,3] row_mask:0xf bank_mask:0xf
	v_fmac_f32_dpp v116, -v200, v34 quad_perm:[0,0,0,0] row_mask:0xf bank_mask:0xf
	v_fmac_f32_dpp v117, -v201, v35 quad_perm:[0,0,0,0] row_mask:0xf bank_mask:0xf
	v_fmac_f32_dpp v118, -v200, v36 quad_perm:[1,1,1,1] row_mask:0xf bank_mask:0xf
	v_fmac_f32_dpp v119, -v201, v37 quad_perm:[1,1,1,1] row_mask:0xf bank_mask:0xf
	v_fmac_f32_dpp v116, -v200, v38 quad_perm:[2,2,2,2] row_mask:0xf bank_mask:0xf
	v_add_f32_e32 v121, v117, v116
	v_add_f32_e32 v122, v118, v119
	v_add_f32_e32 v39, v122, v121
	v_mov_b32_e32 v128, v38
	v_mov_b32_e32 v129, v39
	s_waitcnt lgkmcnt(6)
; __device__ __forceinline__ float bf2f(bf16 v) { return __uint_as_float(((unsigned)v) << 16); }
; #define GDN_LOADROW(buf, rr_, i_) do { _Pragma("unroll") for (int j4 = 0; j4 < ((i_) + 3) / 4; ++j4) buf[j4] = *(const f32x4*)(Lm + (i_) * GP_LSTR + 4 * j4); rr_ = bf2f(*(const bf16*)(xsrc + (i_) * GP_STR * 2)) * scl[i_]; } while (0)
; template <int STRIP> __device__ __forceinline__ void ph_gdn_prep_fast(const bf16* __restrict__ proj, const float* __restrict__ small, const float* __restrict__ conv_w, const float* __restrict__ a_log, const float* __restrict__ dt_bias, ...
;     ...
;             rA = bf2f(*(const bf16*)xsrc) * scl[0];
;     ...
; #pragma unroll
;             for (int i = 0; i < 64; i += 2) {
;                 GDN_LOADROW(bB, rB, i + 1);
;                 GDN_ROW(bA, rA, i);
;                 if (i + 2 < 64) GDN_LOADROW(bA, rA, i + 2);
;                 GDN_ROW(bB, rB, i + 1);
;             }
	v_mul_f32_dpp v120, v202, v4 quad_perm:[0,0,0,0] row_mask:0xf bank_mask:0xf
	v_fma_f32 v116, v183, v250, -v120
	v_permlane32_swap_b32_e32 v128, v129
	v_mul_f32_dpp v117, -v203, v5 quad_perm:[0,0,0,0] row_mask:0xf bank_mask:0xf
	v_mul_f32_dpp v118, -v202, v6 quad_perm:[1,1,1,1] row_mask:0xf bank_mask:0xf
	v_mfma_f32_32x32x2_f32 v[132:147], v228, v128, v[132:147]
	v_mul_f32_dpp v119, -v203, v12 quad_perm:[1,1,1,1] row_mask:0xf bank_mask:0xf
	v_fmac_f32_dpp v116, -v202, v7 quad_perm:[2,2,2,2] row_mask:0xf bank_mask:0xf
	v_fmac_f32_dpp v117, -v203, v13 quad_perm:[2,2,2,2] row_mask:0xf bank_mask:0xf
	v_fmac_f32_dpp v118, -v202, v14 quad_perm:[3,3,3,3] row_mask:0xf bank_mask:0xf
	v_fmac_f32_dpp v119, -v203, v15 quad_perm:[3,3,3,3] row_mask:0xf bank_mask:0xf
	v_fmac_f32_dpp v116, -v204, v16 quad_perm:[0,0,0,0] row_mask:0xf bank_mask:0xf
	v_fmac_f32_dpp v117, -v205, v17 quad_perm:[0,0,0,0] row_mask:0xf bank_mask:0xf
	v_fmac_f32_dpp v118, -v204, v19 quad_perm:[1,1,1,1] row_mask:0xf bank_mask:0xf
	v_fmac_f32_dpp v119, -v205, v20 quad_perm:[1,1,1,1] row_mask:0xf bank_mask:0xf
	v_fmac_f32_dpp v116, -v204, v21 quad_perm:[2,2,2,2] row_mask:0xf bank_mask:0xf
	v_fmac_f32_dpp v117, -v205, v22 quad_perm:[2,2,2,2] row_mask:0xf bank_mask:0xf
	v_fmac_f32_dpp v118, -v204, v23 quad_perm:[3,3,3,3] row_mask:0xf bank_mask:0xf
	v_fmac_f32_dpp v119, -v205, v24 quad_perm:[3,3,3,3] row_mask:0xf bank_mask:0xf
	v_fmac_f32_dpp v116, -v206, v25 quad_perm:[0,0,0,0] row_mask:0xf bank_mask:0xf
	v_fmac_f32_dpp v117, -v207, v27 quad_perm:[0,0,0,0] row_mask:0xf bank_mask:0xf
	v_fmac_f32_dpp v118, -v206, v28 quad_perm:[1,1,1,1] row_mask:0xf bank_mask:0xf
	v_mfma_f32_32x32x2_f32 v[148:163], v228, v129, v[148:163]
	v_fmac_f32_dpp v119, -v207, v29 quad_perm:[1,1,1,1] row_mask:0xf bank_mask:0xf
	v_fmac_f32_dpp v116, -v206, v30 quad_perm:[2,2,2,2] row_mask:0xf bank_mask:0xf
	v_fmac_f32_dpp v117, -v207, v31 quad_perm:[2,2,2,2] row_mask:0xf bank_mask:0xf
	v_fmac_f32_dpp v118, -v206, v32 quad_perm:[3,3,3,3] row_mask:0xf bank_mask:0xf
	v_fmac_f32_dpp v119, -v207, v33 quad_perm:[3,3,3,3] row_mask:0xf bank_mask:0xf
	v_fmac_f32_dpp v116, -v164, v34 quad_perm:[0,0,0,0] row_mask:0xf bank_mask:0xf
	v_fmac_f32_dpp v117, -v165, v35 quad_perm:[0,0,0,0] row_mask:0xf bank_mask:0xf
	v_fmac_f32_dpp v118, -v164, v36 quad_perm:[1,1,1,1] row_mask:0xf bank_mask:0xf
	v_fmac_f32_dpp v119, -v165, v37 quad_perm:[1,1,1,1] row_mask:0xf bank_mask:0xf
	v_fmac_f32_dpp v116, -v164, v38 quad_perm:[2,2,2,2] row_mask:0xf bank_mask:0xf
	v_fmac_f32_dpp v117, -v165, v39 quad_perm:[2,2,2,2] row_mask:0xf bank_mask:0xf
	v_add_f32_e32 v121, v117, v116
	v_add_f32_e32 v122, v118, v119
	v_add_f32_e32 v40, v122, v121
	s_waitcnt lgkmcnt(0)
	v_mul_f32_dpp v120, v166, v4 quad_perm:[0,0,0,0] row_mask:0xf bank_mask:0xf
	v_fma_f32 v116, v185, v251, -v120
	v_mul_f32_dpp v117, -v167, v5 quad_perm:[0,0,0,0] row_mask:0xf bank_mask:0xf
	v_mul_f32_dpp v118, -v166, v6 quad_perm:[1,1,1,1] row_mask:0xf bank_mask:0xf
	v_mul_f32_dpp v119, -v167, v12 quad_perm:[1,1,1,1] row_mask:0xf bank_mask:0xf
	v_fmac_f32_dpp v116, -v166, v7 quad_perm:[2,2,2,2] row_mask:0xf bank_mask:0xf
	v_fmac_f32_dpp v117, -v167, v13 quad_perm:[2,2,2,2] row_mask:0xf bank_mask:0xf
	v_fmac_f32_dpp v118, -v166, v14 quad_perm:[3,3,3,3] row_mask:0xf bank_mask:0xf
	v_fmac_f32_dpp v119, -v167, v15 quad_perm:[3,3,3,3] row_mask:0xf bank_mask:0xf
	v_fmac_f32_dpp v116, -v168, v16 quad_perm:[0,0,0,0] row_mask:0xf bank_mask:0xf
	v_fmac_f32_dpp v117, -v169, v17 quad_perm:[0,0,0,0] row_mask:0xf bank_mask:0xf
	v_fmac_f32_dpp v118, -v168, v19 quad_perm:[1,1,1,1] row_mask:0xf bank_mask:0xf
	v_fmac_f32_dpp v119, -v169, v20 quad_perm:[1,1,1,1] row_mask:0xf bank_mask:0xf
	v_fmac_f32_dpp v116, -v168, v21 quad_perm:[2,2,2,2] row_mask:0xf bank_mask:0xf
	v_fmac_f32_dpp v117, -v169, v22 quad_perm:[2,2,2,2] row_mask:0xf bank_mask:0xf
	v_fmac_f32_dpp v118, -v168, v23 quad_perm:[3,3,3,3] row_mask:0xf bank_mask:0xf
	v_fmac_f32_dpp v119, -v169, v24 quad_perm:[3,3,3,3] row_mask:0xf bank_mask:0xf
	v_fmac_f32_dpp v116, -v170, v25 quad_perm:[0,0,0,0] row_mask:0xf bank_mask:0xf
	v_fmac_f32_dpp v117, -v171, v27 quad_perm:[0,0,0,0] row_mask:0xf bank_mask:0xf
	v_fmac_f32_dpp v118, -v170, v28 quad_perm:[1,1,1,1] row_mask:0xf bank_mask:0xf
	v_fmac_f32_dpp v119, -v171, v29 quad_perm:[1,1,1,1] row_mask:0xf bank_mask:0xf
	v_fmac_f32_dpp v116, -v170, v30 quad_perm:[2,2,2,2] row_mask:0xf bank_mask:0xf
	v_fmac_f32_dpp v117, -v171, v31 quad_perm:[2,2,2,2] row_mask:0xf bank_mask:0xf
	v_fmac_f32_dpp v118, -v170, v32 quad_perm:[3,3,3,3] row_mask:0xf bank_mask:0xf
	v_fmac_f32_dpp v119, -v171, v33 quad_perm:[3,3,3,3] row_mask:0xf bank_mask:0xf
	v_fmac_f32_dpp v116, -v84, v34 quad_perm:[0,0,0,0] row_mask:0xf bank_mask:0xf
	v_fmac_f32_dpp v117, -v85, v35 quad_perm:[0,0,0,0] row_mask:0xf bank_mask:0xf
	v_fmac_f32_dpp v118, -v84, v36 quad_perm:[1,1,1,1] row_mask:0xf bank_mask:0xf
	v_fmac_f32_dpp v119, -v85, v37 quad_perm:[1,1,1,1] row_mask:0xf bank_mask:0xf
	v_fmac_f32_dpp v116, -v84, v38 quad_perm:[2,2,2,2] row_mask:0xf bank_mask:0xf
	v_fmac_f32_dpp v117, -v85, v39 quad_perm:[2,2,2,2] row_mask:0xf bank_mask:0xf
	v_fmac_f32_dpp v118, -v84, v40 quad_perm:[3,3,3,3] row_mask:0xf bank_mask:0xf
	v_add_f32_e32 v121, v117, v116
	v_add_f32_e32 v122, v118, v119
	v_add_f32_e32 v41, v122, v121
	v_mov_b32_e32 v220, v40
	v_mov_b32_e32 v221, v41
	s_nop 1
	v_permlane32_swap_b32_e32 v220, v221
	s_nop 1
	v_mfma_f32_32x32x2_f32 v[132:147], v229, v220, v[132:147]
	s_nop 1
	v_mfma_f32_32x32x2_f32 v[148:163], v229, v221, v[148:163]
	ds_read_b32 v208, v124 offset:128
	ds_read_u16_d16_hi v252, v123 offset:8704
	ds_read_b64 v[86:87], v125 offset:9104
	ds_read_b32 v209, v124 offset:132
	ds_read_u16_d16_hi v253, v123 offset:8976
	ds_read_b64 v[88:89], v125 offset:9376
	ds_read_b32 v210, v124 offset:136
	ds_read_u16_d16_hi v126, v123 offset:9248
	s_nop 7
	s_nop 7
	s_nop 3
	v_permlane32_swap_b32_e32 v132, v148
	v_permlane32_swap_b32_e32 v133, v149
	v_permlane32_swap_b32_e32 v134, v150
	v_permlane32_swap_b32_e32 v135, v151
	v_permlane32_swap_b32_e32 v136, v152
	v_permlane32_swap_b32_e32 v137, v153
	v_permlane32_swap_b32_e32 v138, v154
	v_permlane32_swap_b32_e32 v139, v155
	v_permlane32_swap_b32_e32 v140, v156
	v_permlane32_swap_b32_e32 v141, v157
	v_permlane32_swap_b32_e32 v142, v158
	v_permlane32_swap_b32_e32 v143, v159
	v_permlane32_swap_b32_e32 v144, v160
	v_permlane32_swap_b32_e32 v145, v161
	v_permlane32_swap_b32_e32 v146, v162
	v_permlane32_swap_b32_e32 v147, v163
	s_waitcnt lgkmcnt(6)
; __device__ __forceinline__ float bf2f(bf16 v) { return __uint_as_float(((unsigned)v) << 16); }
; #define GDN_LOADROW(buf, rr_, i_) do { _Pragma("unroll") for (int j4 = 0; j4 < ((i_) + 3) / 4; ++j4) buf[j4] = *(const f32x4*)(Lm + (i_) * GP_LSTR + 4 * j4); rr_ = bf2f(*(const bf16*)(xsrc + (i_) * GP_STR * 2)) * scl[i_]; } while (0)
; template <int STRIP> __device__ __forceinline__ void ph_gdn_prep_fast(const bf16* __restrict__ proj, const float* __restrict__ small, const float* __restrict__ conv_w, const float* __restrict__ a_log, const float* __restrict__ dt_bias, ...
;     ...
;             rA = bf2f(*(const bf16*)xsrc) * scl[0];
;     ...
; #pragma unroll
;             for (int i = 0; i < 64; i += 2) {
;                 GDN_LOADROW(bB, rB, i + 1);
;                 GDN_ROW(bA, rA, i);
;                 if (i + 2 < 64) GDN_LOADROW(bA, rA, i + 2);
;                 GDN_ROW(bB, rB, i + 1);
;             }
	v_fma_f32 v116, v208, v252, -v132
	v_add_f32_e32 v42, 0, v116
	s_waitcnt lgkmcnt(3)
	v_fma_f32 v116, v209, v253, -v133
	v_fmac_f32_dpp v116, -v86, v42 quad_perm:[0,0,0,0] row_mask:0xf bank_mask:0xf
	v_add_f32_e32 v43, 0, v116
	s_waitcnt lgkmcnt(0)
	v_fma_f32 v116, v210, v126, -v134
	v_fmac_f32_dpp v116, -v88, v42 quad_perm:[0,0,0,0] row_mask:0xf bank_mask:0xf
	v_mul_f32_dpp v117, -v89, v43 quad_perm:[0,0,0,0] row_mask:0xf bank_mask:0xf
	ds_read_b64 v[90:91], v125 offset:9648
	v_add_f32_e32 v44, v117, v116
	ds_read_b32 v211, v124 offset:140
	ds_read_u16_d16_hi v127, v123 offset:9520
	s_waitcnt lgkmcnt(0)
	v_fma_f32 v116, v211, v127, -v135
	v_fmac_f32_dpp v116, -v90, v42 quad_perm:[0,0,0,0] row_mask:0xf bank_mask:0xf
	v_mul_f32_dpp v117, -v91, v43 quad_perm:[0,0,0,0] row_mask:0xf bank_mask:0xf
	v_mul_f32_dpp v118, -v90, v44 quad_perm:[1,1,1,1] row_mask:0xf bank_mask:0xf
	ds_read_b64 v[92:93], v125 offset:9920
	v_add_f32_e32 v121, v117, v116
	v_add_f32_e32 v45, v118, v121
	ds_read_b32 v212, v124 offset:144
	ds_read_u16_d16_hi v244, v123 offset:9792
	s_waitcnt lgkmcnt(0)
	v_fma_f32 v116, v212, v244, -v148
	v_fmac_f32_dpp v116, -v92, v42 quad_perm:[0,0,0,0] row_mask:0xf bank_mask:0xf
	v_mul_f32_dpp v117, -v93, v43 quad_perm:[0,0,0,0] row_mask:0xf bank_mask:0xf
	v_mul_f32_dpp v118, -v92, v44 quad_perm:[1,1,1,1] row_mask:0xf bank_mask:0xf
	ds_read_b64 v[186:187], v125 offset:10192
	v_mul_f32_dpp v119, -v93, v45 quad_perm:[1,1,1,1] row_mask:0xf bank_mask:0xf
	v_add_f32_e32 v121, v117, v116
	v_add_f32_e32 v122, v118, v119
	v_add_f32_e32 v46, v122, v121
	ds_read_b32 v213, v124 offset:148
	ds_read_u16_d16_hi v245, v123 offset:10064
	s_waitcnt lgkmcnt(0)
	v_fma_f32 v116, v213, v245, -v149
	v_fmac_f32_dpp v116, -v186, v42 quad_perm:[0,0,0,0] row_mask:0xf bank_mask:0xf
	v_mul_f32_dpp v117, -v187, v43 quad_perm:[0,0,0,0] row_mask:0xf bank_mask:0xf
	ds_read_b64 v[188:189], v125 offset:10464
	v_mul_f32_dpp v118, -v186, v44 quad_perm:[1,1,1,1] row_mask:0xf bank_mask:0xf
	v_mul_f32_dpp v119, -v187, v45 quad_perm:[1,1,1,1] row_mask:0xf bank_mask:0xf
	v_fmac_f32_dpp v116, -v186, v46 quad_perm:[2,2,2,2] row_mask:0xf bank_mask:0xf
	ds_read_b32 v214, v124 offset:152
	v_add_f32_e32 v121, v117, v116
	v_add_f32_e32 v122, v118, v119
	v_add_f32_e32 v47, v122, v121
	ds_read_u16_d16_hi v246, v123 offset:10336
	s_waitcnt lgkmcnt(0)
	v_fma_f32 v116, v214, v246, -v150
	v_fmac_f32_dpp v116, -v188, v42 quad_perm:[0,0,0,0] row_mask:0xf bank_mask:0xf
	v_mul_f32_dpp v117, -v189, v43 quad_perm:[0,0,0,0] row_mask:0xf bank_mask:0xf
	v_mul_f32_dpp v118, -v188, v44 quad_perm:[1,1,1,1] row_mask:0xf bank_mask:0xf
	ds_read_b64 v[190:191], v125 offset:10736
	v_mul_f32_dpp v119, -v189, v45 quad_perm:[1,1,1,1] row_mask:0xf bank_mask:0xf
	v_fmac_f32_dpp v116, -v188, v46 quad_perm:[2,2,2,2] row_mask:0xf bank_mask:0xf
	v_fmac_f32_dpp v117, -v189, v47 quad_perm:[2,2,2,2] row_mask:0xf bank_mask:0xf
	ds_read_b32 v215, v124 offset:156
	v_add_f32_e32 v121, v117, v116
	v_add_f32_e32 v122, v118, v119
	v_add_f32_e32 v48, v122, v121
	ds_read_u16_d16_hi v247, v123 offset:10608
	s_waitcnt lgkmcnt(0)
	v_fma_f32 v116, v215, v247, -v151
	v_fmac_f32_dpp v116, -v190, v42 quad_perm:[0,0,0,0] row_mask:0xf bank_mask:0xf
	v_mul_f32_dpp v117, -v191, v43 quad_perm:[0,0,0,0] row_mask:0xf bank_mask:0xf
	v_mul_f32_dpp v118, -v190, v44 quad_perm:[1,1,1,1] row_mask:0xf bank_mask:0xf
	ds_read_b64 v[192:193], v125 offset:11008
	v_mul_f32_dpp v119, -v191, v45 quad_perm:[1,1,1,1] row_mask:0xf bank_mask:0xf
	v_fmac_f32_dpp v116, -v190, v46 quad_perm:[2,2,2,2] row_mask:0xf bank_mask:0xf
	v_fmac_f32_dpp v117, -v191, v47 quad_perm:[2,2,2,2] row_mask:0xf bank_mask:0xf
	ds_read_b32 v216, v124 offset:160
	v_fmac_f32_dpp v118, -v190, v48 quad_perm:[3,3,3,3] row_mask:0xf bank_mask:0xf
	v_add_f32_e32 v121, v117, v116
	v_add_f32_e32 v122, v118, v119
	v_add_f32_e32 v49, v122, v121
	ds_read_u16_d16_hi v248, v123 offset:10880
	s_waitcnt lgkmcnt(0)
	v_fma_f32 v116, v216, v248, -v136
	v_fmac_f32_dpp v116, -v192, v42 quad_perm:[0,0,0,0] row_mask:0xf bank_mask:0xf
	v_mul_f32_dpp v117, -v193, v43 quad_perm:[0,0,0,0] row_mask:0xf bank_mask:0xf
	ds_read_b64 v[194:195], v125 offset:11280
	v_mul_f32_dpp v118, -v192, v44 quad_perm:[1,1,1,1] row_mask:0xf bank_mask:0xf
	v_mul_f32_dpp v119, -v193, v45 quad_perm:[1,1,1,1] row_mask:0xf bank_mask:0xf
	v_fmac_f32_dpp v116, -v192, v46 quad_perm:[2,2,2,2] row_mask:0xf bank_mask:0xf
	ds_read_b64 v[196:197], v125 offset:11312
	v_fmac_f32_dpp v117, -v193, v47 quad_perm:[2,2,2,2] row_mask:0xf bank_mask:0xf
	v_fmac_f32_dpp v118, -v192, v48 quad_perm:[3,3,3,3] row_mask:0xf bank_mask:0xf
	v_fmac_f32_dpp v119, -v193, v49 quad_perm:[3,3,3,3] row_mask:0xf bank_mask:0xf
	ds_read_b32 v217, v124 offset:164
	v_add_f32_e32 v121, v117, v116
	v_add_f32_e32 v122, v118, v119
	v_add_f32_e32 v50, v122, v121
	ds_read_u16_d16_hi v249, v123 offset:11152
	s_waitcnt lgkmcnt(0)
	v_fma_f32 v116, v217, v249, -v137
	v_fmac_f32_dpp v116, -v194, v42 quad_perm:[0,0,0,0] row_mask:0xf bank_mask:0xf
	v_mul_f32_dpp v117, -v195, v43 quad_perm:[0,0,0,0] row_mask:0xf bank_mask:0xf
	v_mul_f32_dpp v118, -v194, v44 quad_perm:[1,1,1,1] row_mask:0xf bank_mask:0xf
	ds_read_b64 v[198:199], v125 offset:11552
	v_mul_f32_dpp v119, -v195, v45 quad_perm:[1,1,1,1] row_mask:0xf bank_mask:0xf
	v_fmac_f32_dpp v116, -v194, v46 quad_perm:[2,2,2,2] row_mask:0xf bank_mask:0xf
	v_fmac_f32_dpp v117, -v195, v47 quad_perm:[2,2,2,2] row_mask:0xf bank_mask:0xf
	ds_read_b64 v[200:201], v125 offset:11584
	v_fmac_f32_dpp v118, -v194, v48 quad_perm:[3,3,3,3] row_mask:0xf bank_mask:0xf
	v_fmac_f32_dpp v119, -v195, v49 quad_perm:[3,3,3,3] row_mask:0xf bank_mask:0xf
	v_fmac_f32_dpp v116, -v196, v50 quad_perm:[0,0,0,0] row_mask:0xf bank_mask:0xf
	ds_read_b32 v218, v124 offset:168
	v_add_f32_e32 v121, v117, v116
	v_add_f32_e32 v122, v118, v119
	v_add_f32_e32 v51, v122, v121
	ds_read_u16_d16_hi v250, v123 offset:11424
	s_waitcnt lgkmcnt(0)
; __device__ __forceinline__ float bf2f(bf16 v) { return __uint_as_float(((unsigned)v) << 16); }
; #define GDN_LOADROW(buf, rr_, i_) do { _Pragma("unroll") for (int j4 = 0; j4 < ((i_) + 3) / 4; ++j4) buf[j4] = *(const f32x4*)(Lm + (i_) * GP_LSTR + 4 * j4); rr_ = bf2f(*(const bf16*)(xsrc + (i_) * GP_STR * 2)) * scl[i_]; } while (0)
; template <int STRIP> __device__ __forceinline__ void ph_gdn_prep_fast(const bf16* __restrict__ proj, const float* __restrict__ small, const float* __restrict__ conv_w, const float* __restrict__ a_log, const float* __restrict__ dt_bias, ...
;     ...
;             rA = bf2f(*(const bf16*)xsrc) * scl[0];
;     ...
; #pragma unroll
;             for (int i = 0; i < 64; i += 2) {
;                 GDN_LOADROW(bB, rB, i + 1);
;                 GDN_ROW(bA, rA, i);
;                 if (i + 2 < 64) GDN_LOADROW(bA, rA, i + 2);
;                 GDN_ROW(bB, rB, i + 1);
;             }
	v_fma_f32 v116, v218, v250, -v138
	v_fmac_f32_dpp v116, -v198, v42 quad_perm:[0,0,0,0] row_mask:0xf bank_mask:0xf
	v_mul_f32_dpp v117, -v199, v43 quad_perm:[0,0,0,0] row_mask:0xf bank_mask:0xf
	v_mul_f32_dpp v118, -v198, v44 quad_perm:[1,1,1,1] row_mask:0xf bank_mask:0xf
	ds_read_b64 v[202:203], v125 offset:11824
	v_mul_f32_dpp v119, -v199, v45 quad_perm:[1,1,1,1] row_mask:0xf bank_mask:0xf
	v_fmac_f32_dpp v116, -v198, v46 quad_perm:[2,2,2,2] row_mask:0xf bank_mask:0xf
	v_fmac_f32_dpp v117, -v199, v47 quad_perm:[2,2,2,2] row_mask:0xf bank_mask:0xf
	ds_read_b64 v[204:205], v125 offset:11856
	v_fmac_f32_dpp v118, -v198, v48 quad_perm:[3,3,3,3] row_mask:0xf bank_mask:0xf
	v_fmac_f32_dpp v119, -v199, v49 quad_perm:[3,3,3,3] row_mask:0xf bank_mask:0xf
	v_fmac_f32_dpp v116, -v200, v50 quad_perm:[0,0,0,0] row_mask:0xf bank_mask:0xf
	ds_read_b32 v219, v124 offset:172
	v_fmac_f32_dpp v117, -v201, v51 quad_perm:[0,0,0,0] row_mask:0xf bank_mask:0xf
	v_add_f32_e32 v121, v117, v116
	v_add_f32_e32 v122, v118, v119
	v_add_f32_e32 v52, v122, v121
	ds_read_u16_d16_hi v251, v123 offset:11696
	s_waitcnt lgkmcnt(0)
	v_fma_f32 v116, v219, v251, -v139
	v_fmac_f32_dpp v116, -v202, v42 quad_perm:[0,0,0,0] row_mask:0xf bank_mask:0xf
	v_mul_f32_dpp v117, -v203, v43 quad_perm:[0,0,0,0] row_mask:0xf bank_mask:0xf
	ds_read_b64 v[206:207], v125 offset:12096
	v_mul_f32_dpp v118, -v202, v44 quad_perm:[1,1,1,1] row_mask:0xf bank_mask:0xf
	v_mul_f32_dpp v119, -v203, v45 quad_perm:[1,1,1,1] row_mask:0xf bank_mask:0xf
	v_fmac_f32_dpp v116, -v202, v46 quad_perm:[2,2,2,2] row_mask:0xf bank_mask:0xf
	ds_read_b64 v[164:165], v125 offset:12128
	v_fmac_f32_dpp v117, -v203, v47 quad_perm:[2,2,2,2] row_mask:0xf bank_mask:0xf
	v_fmac_f32_dpp v118, -v202, v48 quad_perm:[3,3,3,3] row_mask:0xf bank_mask:0xf
	v_fmac_f32_dpp v119, -v203, v49 quad_perm:[3,3,3,3] row_mask:0xf bank_mask:0xf
	ds_read_b32 v181, v124 offset:176
	v_fmac_f32_dpp v116, -v204, v50 quad_perm:[0,0,0,0] row_mask:0xf bank_mask:0xf
	v_fmac_f32_dpp v117, -v205, v51 quad_perm:[0,0,0,0] row_mask:0xf bank_mask:0xf
	v_fmac_f32_dpp v118, -v204, v52 quad_perm:[1,1,1,1] row_mask:0xf bank_mask:0xf
	ds_read_u16_d16_hi v252, v123 offset:11968
	v_add_f32_e32 v121, v117, v116
	v_add_f32_e32 v122, v118, v119
	v_add_f32_e32 v53, v122, v121
	s_waitcnt lgkmcnt(0)
	v_fma_f32 v116, v181, v252, -v152
	v_fmac_f32_dpp v116, -v206, v42 quad_perm:[0,0,0,0] row_mask:0xf bank_mask:0xf
	v_mul_f32_dpp v117, -v207, v43 quad_perm:[0,0,0,0] row_mask:0xf bank_mask:0xf
	v_mul_f32_dpp v118, -v206, v44 quad_perm:[1,1,1,1] row_mask:0xf bank_mask:0xf
	ds_read_b64 v[166:167], v125 offset:12368
	v_mul_f32_dpp v119, -v207, v45 quad_perm:[1,1,1,1] row_mask:0xf bank_mask:0xf
	v_fmac_f32_dpp v116, -v206, v46 quad_perm:[2,2,2,2] row_mask:0xf bank_mask:0xf
	v_fmac_f32_dpp v117, -v207, v47 quad_perm:[2,2,2,2] row_mask:0xf bank_mask:0xf
	ds_read_b64 v[168:169], v125 offset:12400
	v_fmac_f32_dpp v118, -v206, v48 quad_perm:[3,3,3,3] row_mask:0xf bank_mask:0xf
	v_fmac_f32_dpp v119, -v207, v49 quad_perm:[3,3,3,3] row_mask:0xf bank_mask:0xf
	v_fmac_f32_dpp v116, -v164, v50 quad_perm:[0,0,0,0] row_mask:0xf bank_mask:0xf
	ds_read_b32 v182, v124 offset:180
	v_fmac_f32_dpp v117, -v165, v51 quad_perm:[0,0,0,0] row_mask:0xf bank_mask:0xf
	v_fmac_f32_dpp v118, -v164, v52 quad_perm:[1,1,1,1] row_mask:0xf bank_mask:0xf
	v_fmac_f32_dpp v119, -v165, v53 quad_perm:[1,1,1,1] row_mask:0xf bank_mask:0xf
	ds_read_u16_d16_hi v253, v123 offset:12240
	v_add_f32_e32 v121, v117, v116
	v_add_f32_e32 v122, v118, v119
	v_add_f32_e32 v54, v122, v121
	s_waitcnt lgkmcnt(0)
	v_fma_f32 v116, v182, v253, -v153
	v_fmac_f32_dpp v116, -v166, v42 quad_perm:[0,0,0,0] row_mask:0xf bank_mask:0xf
	v_mul_f32_dpp v117, -v167, v43 quad_perm:[0,0,0,0] row_mask:0xf bank_mask:0xf
	v_mul_f32_dpp v118, -v166, v44 quad_perm:[1,1,1,1] row_mask:0xf bank_mask:0xf
	ds_read_b64 v[170:171], v125 offset:12640
	v_mul_f32_dpp v119, -v167, v45 quad_perm:[1,1,1,1] row_mask:0xf bank_mask:0xf
	v_fmac_f32_dpp v116, -v166, v46 quad_perm:[2,2,2,2] row_mask:0xf bank_mask:0xf
	v_fmac_f32_dpp v117, -v167, v47 quad_perm:[2,2,2,2] row_mask:0xf bank_mask:0xf
	ds_read_b64 v[84:85], v125 offset:12672
	v_fmac_f32_dpp v118, -v166, v48 quad_perm:[3,3,3,3] row_mask:0xf bank_mask:0xf
	v_fmac_f32_dpp v119, -v167, v49 quad_perm:[3,3,3,3] row_mask:0xf bank_mask:0xf
	v_fmac_f32_dpp v116, -v168, v50 quad_perm:[0,0,0,0] row_mask:0xf bank_mask:0xf
	ds_read_b32 v183, v124 offset:184
	v_fmac_f32_dpp v117, -v169, v51 quad_perm:[0,0,0,0] row_mask:0xf bank_mask:0xf
	v_fmac_f32_dpp v118, -v168, v52 quad_perm:[1,1,1,1] row_mask:0xf bank_mask:0xf
	v_fmac_f32_dpp v119, -v169, v53 quad_perm:[1,1,1,1] row_mask:0xf bank_mask:0xf
	ds_read_u16_d16_hi v126, v123 offset:12512
	v_fmac_f32_dpp v116, -v168, v54 quad_perm:[2,2,2,2] row_mask:0xf bank_mask:0xf
	v_add_f32_e32 v121, v117, v116
	v_add_f32_e32 v122, v118, v119
	v_add_f32_e32 v55, v122, v121
	s_waitcnt lgkmcnt(0)
; __device__ __forceinline__ float bf2f(bf16 v) { return __uint_as_float(((unsigned)v) << 16); }
; #define GDN_LOADROW(buf, rr_, i_) do { _Pragma("unroll") for (int j4 = 0; j4 < ((i_) + 3) / 4; ++j4) buf[j4] = *(const f32x4*)(Lm + (i_) * GP_LSTR + 4 * j4); rr_ = bf2f(*(const bf16*)(xsrc + (i_) * GP_STR * 2)) * scl[i_]; } while (0)
; template <int STRIP> __device__ __forceinline__ void ph_gdn_prep_fast(const bf16* __restrict__ proj, const float* __restrict__ small, const float* __restrict__ conv_w, const float* __restrict__ a_log, const float* __restrict__ dt_bias, ...
;     ...
;             rA = bf2f(*(const bf16*)xsrc) * scl[0];
;     ...
; #pragma unroll
;             for (int i = 0; i < 64; i += 2) {
;                 GDN_LOADROW(bB, rB, i + 1);
;                 GDN_ROW(bA, rA, i);
;                 if (i + 2 < 64) GDN_LOADROW(bA, rA, i + 2);
;                 GDN_ROW(bB, rB, i + 1);
;             }
	v_fma_f32 v116, v183, v126, -v154
	v_fmac_f32_dpp v116, -v170, v42 quad_perm:[0,0,0,0] row_mask:0xf bank_mask:0xf
	v_mul_f32_dpp v117, -v171, v43 quad_perm:[0,0,0,0] row_mask:0xf bank_mask:0xf
	ds_read_b64 v[172:173], v125 offset:12912
	v_mul_f32_dpp v118, -v170, v44 quad_perm:[1,1,1,1] row_mask:0xf bank_mask:0xf
	v_mul_f32_dpp v119, -v171, v45 quad_perm:[1,1,1,1] row_mask:0xf bank_mask:0xf
	v_fmac_f32_dpp v116, -v170, v46 quad_perm:[2,2,2,2] row_mask:0xf bank_mask:0xf
	ds_read_b64 v[174:175], v125 offset:12944
	v_fmac_f32_dpp v117, -v171, v47 quad_perm:[2,2,2,2] row_mask:0xf bank_mask:0xf
	v_fmac_f32_dpp v118, -v170, v48 quad_perm:[3,3,3,3] row_mask:0xf bank_mask:0xf
	v_fmac_f32_dpp v119, -v171, v49 quad_perm:[3,3,3,3] row_mask:0xf bank_mask:0xf
	ds_read_b32 v185, v124 offset:188
	v_fmac_f32_dpp v116, -v84, v50 quad_perm:[0,0,0,0] row_mask:0xf bank_mask:0xf
	v_fmac_f32_dpp v117, -v85, v51 quad_perm:[0,0,0,0] row_mask:0xf bank_mask:0xf
	v_fmac_f32_dpp v118, -v84, v52 quad_perm:[1,1,1,1] row_mask:0xf bank_mask:0xf
	ds_read_u16_d16_hi v127, v123 offset:12784
	v_fmac_f32_dpp v119, -v85, v53 quad_perm:[1,1,1,1] row_mask:0xf bank_mask:0xf
	v_fmac_f32_dpp v116, -v84, v54 quad_perm:[2,2,2,2] row_mask:0xf bank_mask:0xf
	v_fmac_f32_dpp v117, -v85, v55 quad_perm:[2,2,2,2] row_mask:0xf bank_mask:0xf
	ds_read_b64 v[176:177], v125 offset:13184
	v_add_f32_e32 v121, v117, v116
	v_add_f32_e32 v122, v118, v119
	v_add_f32_e32 v56, v122, v121
	s_waitcnt lgkmcnt(1)
	v_fma_f32 v116, v185, v127, -v155
	v_fmac_f32_dpp v116, -v172, v42 quad_perm:[0,0,0,0] row_mask:0xf bank_mask:0xf
	v_mul_f32_dpp v117, -v173, v43 quad_perm:[0,0,0,0] row_mask:0xf bank_mask:0xf
	v_mul_f32_dpp v118, -v172, v44 quad_perm:[1,1,1,1] row_mask:0xf bank_mask:0xf
	ds_read_b64 v[178:179], v125 offset:13216
	v_mul_f32_dpp v119, -v173, v45 quad_perm:[1,1,1,1] row_mask:0xf bank_mask:0xf
	v_fmac_f32_dpp v116, -v172, v46 quad_perm:[2,2,2,2] row_mask:0xf bank_mask:0xf
	v_fmac_f32_dpp v117, -v173, v47 quad_perm:[2,2,2,2] row_mask:0xf bank_mask:0xf
	ds_read_b32 v208, v124 offset:192
	v_fmac_f32_dpp v118, -v172, v48 quad_perm:[3,3,3,3] row_mask:0xf bank_mask:0xf
	v_fmac_f32_dpp v119, -v173, v49 quad_perm:[3,3,3,3] row_mask:0xf bank_mask:0xf
	v_fmac_f32_dpp v116, -v174, v50 quad_perm:[0,0,0,0] row_mask:0xf bank_mask:0xf
	ds_read_u16_d16_hi v244, v123 offset:13056
	v_fmac_f32_dpp v117, -v175, v51 quad_perm:[0,0,0,0] row_mask:0xf bank_mask:0xf
	v_fmac_f32_dpp v118, -v174, v52 quad_perm:[1,1,1,1] row_mask:0xf bank_mask:0xf
	v_fmac_f32_dpp v119, -v175, v53 quad_perm:[1,1,1,1] row_mask:0xf bank_mask:0xf
	ds_read_b64 v[222:223], v125 offset:13456
	v_fmac_f32_dpp v116, -v174, v54 quad_perm:[2,2,2,2] row_mask:0xf bank_mask:0xf
	v_fmac_f32_dpp v117, -v175, v55 quad_perm:[2,2,2,2] row_mask:0xf bank_mask:0xf
	v_fmac_f32_dpp v118, -v174, v56 quad_perm:[3,3,3,3] row_mask:0xf bank_mask:0xf
	ds_read_b64 v[224:225], v125 offset:13488
	v_add_f32_e32 v121, v117, v116
	v_add_f32_e32 v122, v118, v119
	v_add_f32_e32 v57, v122, v121
	s_waitcnt lgkmcnt(2)
	v_fma_f32 v116, v208, v244, -v140
	v_fmac_f32_dpp v116, -v176, v42 quad_perm:[0,0,0,0] row_mask:0xf bank_mask:0xf
	v_mul_f32_dpp v117, -v177, v43 quad_perm:[0,0,0,0] row_mask:0xf bank_mask:0xf
	v_mul_f32_dpp v118, -v176, v44 quad_perm:[1,1,1,1] row_mask:0xf bank_mask:0xf
	ds_read_b64 v[226:227], v125 offset:13520
	v_mul_f32_dpp v119, -v177, v45 quad_perm:[1,1,1,1] row_mask:0xf bank_mask:0xf
	v_fmac_f32_dpp v116, -v176, v46 quad_perm:[2,2,2,2] row_mask:0xf bank_mask:0xf
	v_fmac_f32_dpp v117, -v177, v47 quad_perm:[2,2,2,2] row_mask:0xf bank_mask:0xf
	ds_read_b32 v209, v124 offset:196
	v_fmac_f32_dpp v118, -v176, v48 quad_perm:[3,3,3,3] row_mask:0xf bank_mask:0xf
	v_fmac_f32_dpp v119, -v177, v49 quad_perm:[3,3,3,3] row_mask:0xf bank_mask:0xf
	v_fmac_f32_dpp v116, -v178, v50 quad_perm:[0,0,0,0] row_mask:0xf bank_mask:0xf
	ds_read_u16_d16_hi v245, v123 offset:13328
	v_fmac_f32_dpp v117, -v179, v51 quad_perm:[0,0,0,0] row_mask:0xf bank_mask:0xf
	v_fmac_f32_dpp v118, -v178, v52 quad_perm:[1,1,1,1] row_mask:0xf bank_mask:0xf
	v_fmac_f32_dpp v119, -v179, v53 quad_perm:[1,1,1,1] row_mask:0xf bank_mask:0xf
	ds_read_b64 v[228:229], v125 offset:13728
	v_fmac_f32_dpp v116, -v178, v54 quad_perm:[2,2,2,2] row_mask:0xf bank_mask:0xf
	v_fmac_f32_dpp v117, -v179, v55 quad_perm:[2,2,2,2] row_mask:0xf bank_mask:0xf
	v_fmac_f32_dpp v118, -v178, v56 quad_perm:[3,3,3,3] row_mask:0xf bank_mask:0xf
	ds_read_b64 v[86:87], v125 offset:13760
	v_fmac_f32_dpp v119, -v179, v57 quad_perm:[3,3,3,3] row_mask:0xf bank_mask:0xf
	v_add_f32_e32 v121, v117, v116
	v_add_f32_e32 v122, v118, v119
	v_add_f32_e32 v58, v122, v121
	s_waitcnt lgkmcnt(2)
	v_fma_f32 v116, v209, v245, -v141
	v_fmac_f32_dpp v116, -v222, v42 quad_perm:[0,0,0,0] row_mask:0xf bank_mask:0xf
	v_mul_f32_dpp v117, -v223, v43 quad_perm:[0,0,0,0] row_mask:0xf bank_mask:0xf
	ds_read_b64 v[88:89], v125 offset:13792
	v_mul_f32_dpp v118, -v222, v44 quad_perm:[1,1,1,1] row_mask:0xf bank_mask:0xf
	v_mul_f32_dpp v119, -v223, v45 quad_perm:[1,1,1,1] row_mask:0xf bank_mask:0xf
	v_fmac_f32_dpp v116, -v222, v46 quad_perm:[2,2,2,2] row_mask:0xf bank_mask:0xf
	ds_read_b32 v210, v124 offset:200
	v_fmac_f32_dpp v117, -v223, v47 quad_perm:[2,2,2,2] row_mask:0xf bank_mask:0xf
	v_fmac_f32_dpp v118, -v222, v48 quad_perm:[3,3,3,3] row_mask:0xf bank_mask:0xf
	v_fmac_f32_dpp v119, -v223, v49 quad_perm:[3,3,3,3] row_mask:0xf bank_mask:0xf
	ds_read_u16_d16_hi v246, v123 offset:13600
	v_fmac_f32_dpp v116, -v224, v50 quad_perm:[0,0,0,0] row_mask:0xf bank_mask:0xf
	v_fmac_f32_dpp v117, -v225, v51 quad_perm:[0,0,0,0] row_mask:0xf bank_mask:0xf
	v_fmac_f32_dpp v118, -v224, v52 quad_perm:[1,1,1,1] row_mask:0xf bank_mask:0xf
	ds_read_b64 v[90:91], v125 offset:14000
	v_fmac_f32_dpp v119, -v225, v53 quad_perm:[1,1,1,1] row_mask:0xf bank_mask:0xf
	v_fmac_f32_dpp v116, -v224, v54 quad_perm:[2,2,2,2] row_mask:0xf bank_mask:0xf
	v_fmac_f32_dpp v117, -v225, v55 quad_perm:[2,2,2,2] row_mask:0xf bank_mask:0xf
	ds_read_b64 v[92:93], v125 offset:14032
	v_fmac_f32_dpp v118, -v224, v56 quad_perm:[3,3,3,3] row_mask:0xf bank_mask:0xf
	v_fmac_f32_dpp v119, -v225, v57 quad_perm:[3,3,3,3] row_mask:0xf bank_mask:0xf
	v_fmac_f32_dpp v116, -v226, v58 quad_perm:[0,0,0,0] row_mask:0xf bank_mask:0xf
	ds_read_b64 v[186:187], v125 offset:14064
	v_add_f32_e32 v121, v117, v116
	v_add_f32_e32 v122, v118, v119
	v_add_f32_e32 v59, v122, v121
	s_waitcnt lgkmcnt(3)
; __device__ __forceinline__ float bf2f(bf16 v) { return __uint_as_float(((unsigned)v) << 16); }
; #define GDN_LOADROW(buf, rr_, i_) do { _Pragma("unroll") for (int j4 = 0; j4 < ((i_) + 3) / 4; ++j4) buf[j4] = *(const f32x4*)(Lm + (i_) * GP_LSTR + 4 * j4); rr_ = bf2f(*(const bf16*)(xsrc + (i_) * GP_STR * 2)) * scl[i_]; } while (0)
; template <int STRIP> __device__ __forceinline__ void ph_gdn_prep_fast(const bf16* __restrict__ proj, const float* __restrict__ small, const float* __restrict__ conv_w, const float* __restrict__ a_log, const float* __restrict__ dt_bias, ...
;     ...
;             rA = bf2f(*(const bf16*)xsrc) * scl[0];
;     ...
; #pragma unroll
;             for (int i = 0; i < 64; i += 2) {
;                 GDN_LOADROW(bB, rB, i + 1);
;                 GDN_ROW(bA, rA, i);
;                 if (i + 2 < 64) GDN_LOADROW(bA, rA, i + 2);
;                 GDN_ROW(bB, rB, i + 1);
;             }
	v_fma_f32 v116, v210, v246, -v142
	v_fmac_f32_dpp v116, -v228, v42 quad_perm:[0,0,0,0] row_mask:0xf bank_mask:0xf
	v_mul_f32_dpp v117, -v229, v43 quad_perm:[0,0,0,0] row_mask:0xf bank_mask:0xf
	v_mul_f32_dpp v118, -v228, v44 quad_perm:[1,1,1,1] row_mask:0xf bank_mask:0xf
	ds_read_b32 v211, v124 offset:204
	v_mul_f32_dpp v119, -v229, v45 quad_perm:[1,1,1,1] row_mask:0xf bank_mask:0xf
	v_fmac_f32_dpp v116, -v228, v46 quad_perm:[2,2,2,2] row_mask:0xf bank_mask:0xf
	v_fmac_f32_dpp v117, -v229, v47 quad_perm:[2,2,2,2] row_mask:0xf bank_mask:0xf
	ds_read_u16_d16_hi v247, v123 offset:13872
	v_fmac_f32_dpp v118, -v228, v48 quad_perm:[3,3,3,3] row_mask:0xf bank_mask:0xf
	v_fmac_f32_dpp v119, -v229, v49 quad_perm:[3,3,3,3] row_mask:0xf bank_mask:0xf
	v_fmac_f32_dpp v116, -v86, v50 quad_perm:[0,0,0,0] row_mask:0xf bank_mask:0xf
	ds_read_b64 v[188:189], v125 offset:14272
	v_fmac_f32_dpp v117, -v87, v51 quad_perm:[0,0,0,0] row_mask:0xf bank_mask:0xf
	v_fmac_f32_dpp v118, -v86, v52 quad_perm:[1,1,1,1] row_mask:0xf bank_mask:0xf
	v_fmac_f32_dpp v119, -v87, v53 quad_perm:[1,1,1,1] row_mask:0xf bank_mask:0xf
	ds_read_b64 v[190:191], v125 offset:14304
	v_fmac_f32_dpp v116, -v86, v54 quad_perm:[2,2,2,2] row_mask:0xf bank_mask:0xf
	v_fmac_f32_dpp v117, -v87, v55 quad_perm:[2,2,2,2] row_mask:0xf bank_mask:0xf
	v_fmac_f32_dpp v118, -v86, v56 quad_perm:[3,3,3,3] row_mask:0xf bank_mask:0xf
	ds_read_b64 v[192:193], v125 offset:14336
	v_fmac_f32_dpp v119, -v87, v57 quad_perm:[3,3,3,3] row_mask:0xf bank_mask:0xf
	v_fmac_f32_dpp v116, -v88, v58 quad_perm:[0,0,0,0] row_mask:0xf bank_mask:0xf
	v_fmac_f32_dpp v117, -v89, v59 quad_perm:[0,0,0,0] row_mask:0xf bank_mask:0xf
	ds_read_b32 v212, v124 offset:208
	v_add_f32_e32 v121, v117, v116
	v_add_f32_e32 v122, v118, v119
	v_add_f32_e32 v60, v122, v121
	s_waitcnt lgkmcnt(4)
	v_fma_f32 v116, v211, v247, -v143
	v_fmac_f32_dpp v116, -v90, v42 quad_perm:[0,0,0,0] row_mask:0xf bank_mask:0xf
	v_mul_f32_dpp v117, -v91, v43 quad_perm:[0,0,0,0] row_mask:0xf bank_mask:0xf
	v_mul_f32_dpp v118, -v90, v44 quad_perm:[1,1,1,1] row_mask:0xf bank_mask:0xf
	ds_read_u16_d16_hi v248, v123 offset:14144
	v_mul_f32_dpp v119, -v91, v45 quad_perm:[1,1,1,1] row_mask:0xf bank_mask:0xf
	v_fmac_f32_dpp v116, -v90, v46 quad_perm:[2,2,2,2] row_mask:0xf bank_mask:0xf
	v_fmac_f32_dpp v117, -v91, v47 quad_perm:[2,2,2,2] row_mask:0xf bank_mask:0xf
	ds_read_b64 v[194:195], v125 offset:14544
	v_fmac_f32_dpp v118, -v90, v48 quad_perm:[3,3,3,3] row_mask:0xf bank_mask:0xf
	v_fmac_f32_dpp v119, -v91, v49 quad_perm:[3,3,3,3] row_mask:0xf bank_mask:0xf
	v_fmac_f32_dpp v116, -v92, v50 quad_perm:[0,0,0,0] row_mask:0xf bank_mask:0xf
	ds_read_b64 v[196:197], v125 offset:14576
	v_fmac_f32_dpp v117, -v93, v51 quad_perm:[0,0,0,0] row_mask:0xf bank_mask:0xf
	v_fmac_f32_dpp v118, -v92, v52 quad_perm:[1,1,1,1] row_mask:0xf bank_mask:0xf
	v_fmac_f32_dpp v119, -v93, v53 quad_perm:[1,1,1,1] row_mask:0xf bank_mask:0xf
	ds_read_b64 v[198:199], v125 offset:14608
	v_fmac_f32_dpp v116, -v92, v54 quad_perm:[2,2,2,2] row_mask:0xf bank_mask:0xf
	v_fmac_f32_dpp v117, -v93, v55 quad_perm:[2,2,2,2] row_mask:0xf bank_mask:0xf
	v_fmac_f32_dpp v118, -v92, v56 quad_perm:[3,3,3,3] row_mask:0xf bank_mask:0xf
	ds_read_b32 v213, v124 offset:212
	v_fmac_f32_dpp v119, -v93, v57 quad_perm:[3,3,3,3] row_mask:0xf bank_mask:0xf
	v_fmac_f32_dpp v116, -v186, v58 quad_perm:[0,0,0,0] row_mask:0xf bank_mask:0xf
	v_fmac_f32_dpp v117, -v187, v59 quad_perm:[0,0,0,0] row_mask:0xf bank_mask:0xf
	ds_read_u16_d16_hi v249, v123 offset:14416
	v_fmac_f32_dpp v118, -v186, v60 quad_perm:[1,1,1,1] row_mask:0xf bank_mask:0xf
	v_add_f32_e32 v121, v117, v116
	v_add_f32_e32 v122, v118, v119
	v_add_f32_e32 v61, v122, v121
	s_waitcnt lgkmcnt(5)
	v_fma_f32 v116, v212, v248, -v156
	v_fmac_f32_dpp v116, -v188, v42 quad_perm:[0,0,0,0] row_mask:0xf bank_mask:0xf
	v_mul_f32_dpp v117, -v189, v43 quad_perm:[0,0,0,0] row_mask:0xf bank_mask:0xf
	ds_read_b64 v[200:201], v125 offset:14816
	v_mul_f32_dpp v118, -v188, v44 quad_perm:[1,1,1,1] row_mask:0xf bank_mask:0xf
	v_mul_f32_dpp v119, -v189, v45 quad_perm:[1,1,1,1] row_mask:0xf bank_mask:0xf
	v_fmac_f32_dpp v116, -v188, v46 quad_perm:[2,2,2,2] row_mask:0xf bank_mask:0xf
	ds_read_b64 v[202:203], v125 offset:14848
	v_fmac_f32_dpp v117, -v189, v47 quad_perm:[2,2,2,2] row_mask:0xf bank_mask:0xf
	v_fmac_f32_dpp v118, -v188, v48 quad_perm:[3,3,3,3] row_mask:0xf bank_mask:0xf
	v_fmac_f32_dpp v119, -v189, v49 quad_perm:[3,3,3,3] row_mask:0xf bank_mask:0xf
	ds_read_b64 v[204:205], v125 offset:14880
	v_fmac_f32_dpp v116, -v190, v50 quad_perm:[0,0,0,0] row_mask:0xf bank_mask:0xf
	v_fmac_f32_dpp v117, -v191, v51 quad_perm:[0,0,0,0] row_mask:0xf bank_mask:0xf
	v_fmac_f32_dpp v118, -v190, v52 quad_perm:[1,1,1,1] row_mask:0xf bank_mask:0xf
	ds_read_b32 v214, v124 offset:216
	v_fmac_f32_dpp v119, -v191, v53 quad_perm:[1,1,1,1] row_mask:0xf bank_mask:0xf
	v_fmac_f32_dpp v116, -v190, v54 quad_perm:[2,2,2,2] row_mask:0xf bank_mask:0xf
	v_fmac_f32_dpp v117, -v191, v55 quad_perm:[2,2,2,2] row_mask:0xf bank_mask:0xf
	ds_read_u16_d16_hi v250, v123 offset:14688
	v_fmac_f32_dpp v118, -v190, v56 quad_perm:[3,3,3,3] row_mask:0xf bank_mask:0xf
	v_fmac_f32_dpp v119, -v191, v57 quad_perm:[3,3,3,3] row_mask:0xf bank_mask:0xf
	v_fmac_f32_dpp v116, -v192, v58 quad_perm:[0,0,0,0] row_mask:0xf bank_mask:0xf
	ds_read_b64 v[206:207], v125 offset:15088
	v_fmac_f32_dpp v117, -v193, v59 quad_perm:[0,0,0,0] row_mask:0xf bank_mask:0xf
	v_fmac_f32_dpp v118, -v192, v60 quad_perm:[1,1,1,1] row_mask:0xf bank_mask:0xf
	v_fmac_f32_dpp v119, -v193, v61 quad_perm:[1,1,1,1] row_mask:0xf bank_mask:0xf
	ds_read_b64 v[164:165], v125 offset:15120
	v_add_f32_e32 v121, v117, v116
	v_add_f32_e32 v122, v118, v119
	v_add_f32_e32 v62, v122, v121
	s_waitcnt lgkmcnt(7)
; __device__ __forceinline__ float bf2f(bf16 v) { return __uint_as_float(((unsigned)v) << 16); }
; #define GDN_LOADROW(buf, rr_, i_) do { _Pragma("unroll") for (int j4 = 0; j4 < ((i_) + 3) / 4; ++j4) buf[j4] = *(const f32x4*)(Lm + (i_) * GP_LSTR + 4 * j4); rr_ = bf2f(*(const bf16*)(xsrc + (i_) * GP_STR * 2)) * scl[i_]; } while (0)
; template <int STRIP> __device__ __forceinline__ void ph_gdn_prep_fast(const bf16* __restrict__ proj, const float* __restrict__ small, const float* __restrict__ conv_w, const float* __restrict__ a_log, const float* __restrict__ dt_bias, ...
;     ...
;             rA = bf2f(*(const bf16*)xsrc) * scl[0];
;     ...
; #pragma unroll
;             for (int i = 0; i < 64; i += 2) {
;                 GDN_LOADROW(bB, rB, i + 1);
;                 GDN_ROW(bA, rA, i);
;                 if (i + 2 < 64) GDN_LOADROW(bA, rA, i + 2);
;                 GDN_ROW(bB, rB, i + 1);
;             }
	v_fma_f32 v116, v213, v249, -v157
	v_fmac_f32_dpp v116, -v194, v42 quad_perm:[0,0,0,0] row_mask:0xf bank_mask:0xf
	v_mul_f32_dpp v117, -v195, v43 quad_perm:[0,0,0,0] row_mask:0xf bank_mask:0xf
	v_mul_f32_dpp v118, -v194, v44 quad_perm:[1,1,1,1] row_mask:0xf bank_mask:0xf
	ds_read_b64 v[166:167], v125 offset:15152
	v_mul_f32_dpp v119, -v195, v45 quad_perm:[1,1,1,1] row_mask:0xf bank_mask:0xf
	v_fmac_f32_dpp v116, -v194, v46 quad_perm:[2,2,2,2] row_mask:0xf bank_mask:0xf
	v_fmac_f32_dpp v117, -v195, v47 quad_perm:[2,2,2,2] row_mask:0xf bank_mask:0xf
	ds_read_b32 v215, v124 offset:220
	v_fmac_f32_dpp v118, -v194, v48 quad_perm:[3,3,3,3] row_mask:0xf bank_mask:0xf
	v_fmac_f32_dpp v119, -v195, v49 quad_perm:[3,3,3,3] row_mask:0xf bank_mask:0xf
	v_fmac_f32_dpp v116, -v196, v50 quad_perm:[0,0,0,0] row_mask:0xf bank_mask:0xf
	ds_read_u16_d16_hi v251, v123 offset:14960
	v_fmac_f32_dpp v117, -v197, v51 quad_perm:[0,0,0,0] row_mask:0xf bank_mask:0xf
	v_fmac_f32_dpp v118, -v196, v52 quad_perm:[1,1,1,1] row_mask:0xf bank_mask:0xf
	v_fmac_f32_dpp v119, -v197, v53 quad_perm:[1,1,1,1] row_mask:0xf bank_mask:0xf
	ds_read_b64 v[168:169], v125 offset:15360
	v_fmac_f32_dpp v116, -v196, v54 quad_perm:[2,2,2,2] row_mask:0xf bank_mask:0xf
	v_fmac_f32_dpp v117, -v197, v55 quad_perm:[2,2,2,2] row_mask:0xf bank_mask:0xf
	v_fmac_f32_dpp v118, -v196, v56 quad_perm:[3,3,3,3] row_mask:0xf bank_mask:0xf
	ds_read_b64 v[170:171], v125 offset:15392
	v_fmac_f32_dpp v119, -v197, v57 quad_perm:[3,3,3,3] row_mask:0xf bank_mask:0xf
	v_fmac_f32_dpp v116, -v198, v58 quad_perm:[0,0,0,0] row_mask:0xf bank_mask:0xf
	v_fmac_f32_dpp v117, -v199, v59 quad_perm:[0,0,0,0] row_mask:0xf bank_mask:0xf
	ds_read_b64 v[84:85], v125 offset:15424
	v_fmac_f32_dpp v118, -v198, v60 quad_perm:[1,1,1,1] row_mask:0xf bank_mask:0xf
	v_fmac_f32_dpp v119, -v199, v61 quad_perm:[1,1,1,1] row_mask:0xf bank_mask:0xf
	v_fmac_f32_dpp v116, -v198, v62 quad_perm:[2,2,2,2] row_mask:0xf bank_mask:0xf
	ds_read_b32 v216, v124 offset:224
	v_add_f32_e32 v121, v117, v116
	v_add_f32_e32 v122, v118, v119
	v_add_f32_e32 v63, v122, v121
	s_waitcnt lgkmcnt(9)
	v_fma_f32 v116, v214, v250, -v158
	v_fmac_f32_dpp v116, -v200, v42 quad_perm:[0,0,0,0] row_mask:0xf bank_mask:0xf
	v_mul_f32_dpp v117, -v201, v43 quad_perm:[0,0,0,0] row_mask:0xf bank_mask:0xf
	v_mul_f32_dpp v118, -v200, v44 quad_perm:[1,1,1,1] row_mask:0xf bank_mask:0xf
	ds_read_u16_d16_hi v252, v123 offset:15232
	v_mul_f32_dpp v119, -v201, v45 quad_perm:[1,1,1,1] row_mask:0xf bank_mask:0xf
	v_fmac_f32_dpp v116, -v200, v46 quad_perm:[2,2,2,2] row_mask:0xf bank_mask:0xf
	v_fmac_f32_dpp v117, -v201, v47 quad_perm:[2,2,2,2] row_mask:0xf bank_mask:0xf
	ds_read_b64 v[172:173], v125 offset:15632
	v_fmac_f32_dpp v118, -v200, v48 quad_perm:[3,3,3,3] row_mask:0xf bank_mask:0xf
	v_fmac_f32_dpp v119, -v201, v49 quad_perm:[3,3,3,3] row_mask:0xf bank_mask:0xf
	v_fmac_f32_dpp v116, -v202, v50 quad_perm:[0,0,0,0] row_mask:0xf bank_mask:0xf
	ds_read_b64 v[174:175], v125 offset:15664
	v_fmac_f32_dpp v117, -v203, v51 quad_perm:[0,0,0,0] row_mask:0xf bank_mask:0xf
	v_fmac_f32_dpp v118, -v202, v52 quad_perm:[1,1,1,1] row_mask:0xf bank_mask:0xf
	v_fmac_f32_dpp v119, -v203, v53 quad_perm:[1,1,1,1] row_mask:0xf bank_mask:0xf
	ds_read_b64 v[176:177], v125 offset:15696
	v_fmac_f32_dpp v116, -v202, v54 quad_perm:[2,2,2,2] row_mask:0xf bank_mask:0xf
	v_fmac_f32_dpp v117, -v203, v55 quad_perm:[2,2,2,2] row_mask:0xf bank_mask:0xf
	v_fmac_f32_dpp v118, -v202, v56 quad_perm:[3,3,3,3] row_mask:0xf bank_mask:0xf
	ds_read_b64 v[178:179], v125 offset:15728
	v_fmac_f32_dpp v119, -v203, v57 quad_perm:[3,3,3,3] row_mask:0xf bank_mask:0xf
	v_fmac_f32_dpp v116, -v204, v58 quad_perm:[0,0,0,0] row_mask:0xf bank_mask:0xf
	v_fmac_f32_dpp v117, -v205, v59 quad_perm:[0,0,0,0] row_mask:0xf bank_mask:0xf
	ds_read_b32 v217, v124 offset:228
	v_fmac_f32_dpp v118, -v204, v60 quad_perm:[1,1,1,1] row_mask:0xf bank_mask:0xf
	v_fmac_f32_dpp v119, -v205, v61 quad_perm:[1,1,1,1] row_mask:0xf bank_mask:0xf
	v_fmac_f32_dpp v116, -v204, v62 quad_perm:[2,2,2,2] row_mask:0xf bank_mask:0xf
	ds_read_u16_d16_hi v253, v123 offset:15504
	v_fmac_f32_dpp v117, -v205, v63 quad_perm:[2,2,2,2] row_mask:0xf bank_mask:0xf
	v_add_f32_e32 v121, v117, v116
	v_add_f32_e32 v122, v118, v119
	v_add_f32_e32 v64, v122, v121
	s_waitcnt lgkmcnt(11)
	v_fma_f32 v116, v215, v251, -v159
	v_fmac_f32_dpp v116, -v206, v42 quad_perm:[0,0,0,0] row_mask:0xf bank_mask:0xf
	v_mul_f32_dpp v117, -v207, v43 quad_perm:[0,0,0,0] row_mask:0xf bank_mask:0xf
	ds_read_b64 v[222:223], v125 offset:15904
	v_mul_f32_dpp v118, -v206, v44 quad_perm:[1,1,1,1] row_mask:0xf bank_mask:0xf
	v_mul_f32_dpp v119, -v207, v45 quad_perm:[1,1,1,1] row_mask:0xf bank_mask:0xf
	v_fmac_f32_dpp v116, -v206, v46 quad_perm:[2,2,2,2] row_mask:0xf bank_mask:0xf
	ds_read_b64 v[224:225], v125 offset:15936
	v_fmac_f32_dpp v117, -v207, v47 quad_perm:[2,2,2,2] row_mask:0xf bank_mask:0xf
	v_fmac_f32_dpp v118, -v206, v48 quad_perm:[3,3,3,3] row_mask:0xf bank_mask:0xf
	v_fmac_f32_dpp v119, -v207, v49 quad_perm:[3,3,3,3] row_mask:0xf bank_mask:0xf
	ds_read_b64 v[226:227], v125 offset:15968
	v_fmac_f32_dpp v116, -v164, v50 quad_perm:[0,0,0,0] row_mask:0xf bank_mask:0xf
	v_fmac_f32_dpp v117, -v165, v51 quad_perm:[0,0,0,0] row_mask:0xf bank_mask:0xf
	v_fmac_f32_dpp v118, -v164, v52 quad_perm:[1,1,1,1] row_mask:0xf bank_mask:0xf
	ds_read_b64 v[228:229], v125 offset:16000
	v_fmac_f32_dpp v119, -v165, v53 quad_perm:[1,1,1,1] row_mask:0xf bank_mask:0xf
	v_fmac_f32_dpp v116, -v164, v54 quad_perm:[2,2,2,2] row_mask:0xf bank_mask:0xf
	v_fmac_f32_dpp v117, -v165, v55 quad_perm:[2,2,2,2] row_mask:0xf bank_mask:0xf
	ds_read_b32 v218, v124 offset:232
	v_fmac_f32_dpp v118, -v164, v56 quad_perm:[3,3,3,3] row_mask:0xf bank_mask:0xf
	v_fmac_f32_dpp v119, -v165, v57 quad_perm:[3,3,3,3] row_mask:0xf bank_mask:0xf
	v_fmac_f32_dpp v116, -v166, v58 quad_perm:[0,0,0,0] row_mask:0xf bank_mask:0xf
	ds_read_u16_d16_hi v126, v123 offset:15776
	v_fmac_f32_dpp v117, -v167, v59 quad_perm:[0,0,0,0] row_mask:0xf bank_mask:0xf
	v_fmac_f32_dpp v118, -v166, v60 quad_perm:[1,1,1,1] row_mask:0xf bank_mask:0xf
	v_fmac_f32_dpp v119, -v167, v61 quad_perm:[1,1,1,1] row_mask:0xf bank_mask:0xf
	v_fmac_f32_dpp v116, -v166, v62 quad_perm:[2,2,2,2] row_mask:0xf bank_mask:0xf
	v_fmac_f32_dpp v117, -v167, v63 quad_perm:[2,2,2,2] row_mask:0xf bank_mask:0xf
	v_fmac_f32_dpp v118, -v166, v64 quad_perm:[3,3,3,3] row_mask:0xf bank_mask:0xf
	v_add_f32_e32 v121, v117, v116
	v_add_f32_e32 v122, v118, v119
	v_add_f32_e32 v65, v122, v121
	s_waitcnt lgkmcnt(12)
; __device__ __forceinline__ float bf2f(bf16 v) { return __uint_as_float(((unsigned)v) << 16); }
; #define GDN_LOADROW(buf, rr_, i_) do { _Pragma("unroll") for (int j4 = 0; j4 < ((i_) + 3) / 4; ++j4) buf[j4] = *(const f32x4*)(Lm + (i_) * GP_LSTR + 4 * j4); rr_ = bf2f(*(const bf16*)(xsrc + (i_) * GP_STR * 2)) * scl[i_]; } while (0)
; template <int STRIP> __device__ __forceinline__ void ph_gdn_prep_fast(const bf16* __restrict__ proj, const float* __restrict__ small, const float* __restrict__ conv_w, const float* __restrict__ a_log, const float* __restrict__ dt_bias, ...
;     ...
;             rA = bf2f(*(const bf16*)xsrc) * scl[0];
;     ...
; #pragma unroll
;             for (int i = 0; i < 64; i += 2) {
;                 GDN_LOADROW(bB, rB, i + 1);
;                 GDN_ROW(bA, rA, i);
;                 if (i + 2 < 64) GDN_LOADROW(bA, rA, i + 2);
;                 GDN_ROW(bB, rB, i + 1);
;             }
	v_fma_f32 v116, v216, v252, -v144
	v_fmac_f32_dpp v116, -v168, v42 quad_perm:[0,0,0,0] row_mask:0xf bank_mask:0xf
	v_mul_f32_dpp v117, -v169, v43 quad_perm:[0,0,0,0] row_mask:0xf bank_mask:0xf
	v_mul_f32_dpp v118, -v168, v44 quad_perm:[1,1,1,1] row_mask:0xf bank_mask:0xf
	ds_read_b64 v[86:87], v125 offset:16176
	v_mul_f32_dpp v119, -v169, v45 quad_perm:[1,1,1,1] row_mask:0xf bank_mask:0xf
	v_fmac_f32_dpp v116, -v168, v46 quad_perm:[2,2,2,2] row_mask:0xf bank_mask:0xf
	v_fmac_f32_dpp v117, -v169, v47 quad_perm:[2,2,2,2] row_mask:0xf bank_mask:0xf
	ds_read_b64 v[88:89], v125 offset:16208
	v_fmac_f32_dpp v118, -v168, v48 quad_perm:[3,3,3,3] row_mask:0xf bank_mask:0xf
	v_fmac_f32_dpp v119, -v169, v49 quad_perm:[3,3,3,3] row_mask:0xf bank_mask:0xf
	v_fmac_f32_dpp v116, -v170, v50 quad_perm:[0,0,0,0] row_mask:0xf bank_mask:0xf
	ds_read_b64 v[90:91], v125 offset:16240
	v_fmac_f32_dpp v117, -v171, v51 quad_perm:[0,0,0,0] row_mask:0xf bank_mask:0xf
	v_fmac_f32_dpp v118, -v170, v52 quad_perm:[1,1,1,1] row_mask:0xf bank_mask:0xf
	v_fmac_f32_dpp v119, -v171, v53 quad_perm:[1,1,1,1] row_mask:0xf bank_mask:0xf
	ds_read_b64 v[92:93], v125 offset:16272
	v_fmac_f32_dpp v116, -v170, v54 quad_perm:[2,2,2,2] row_mask:0xf bank_mask:0xf
	v_fmac_f32_dpp v117, -v171, v55 quad_perm:[2,2,2,2] row_mask:0xf bank_mask:0xf
	v_fmac_f32_dpp v118, -v170, v56 quad_perm:[3,3,3,3] row_mask:0xf bank_mask:0xf
	ds_read_b32 v219, v124 offset:236
	v_fmac_f32_dpp v119, -v171, v57 quad_perm:[3,3,3,3] row_mask:0xf bank_mask:0xf
	v_fmac_f32_dpp v116, -v84, v58 quad_perm:[0,0,0,0] row_mask:0xf bank_mask:0xf
	v_fmac_f32_dpp v117, -v85, v59 quad_perm:[0,0,0,0] row_mask:0xf bank_mask:0xf
	ds_read_u16_d16_hi v127, v123 offset:16048
	v_fmac_f32_dpp v118, -v84, v60 quad_perm:[1,1,1,1] row_mask:0xf bank_mask:0xf
	v_fmac_f32_dpp v119, -v85, v61 quad_perm:[1,1,1,1] row_mask:0xf bank_mask:0xf
	v_fmac_f32_dpp v116, -v84, v62 quad_perm:[2,2,2,2] row_mask:0xf bank_mask:0xf
	v_fmac_f32_dpp v117, -v85, v63 quad_perm:[2,2,2,2] row_mask:0xf bank_mask:0xf
	v_fmac_f32_dpp v118, -v84, v64 quad_perm:[3,3,3,3] row_mask:0xf bank_mask:0xf
	v_fmac_f32_dpp v119, -v85, v65 quad_perm:[3,3,3,3] row_mask:0xf bank_mask:0xf
	v_add_f32_e32 v121, v117, v116
	v_add_f32_e32 v122, v118, v119
	v_add_f32_e32 v66, v122, v121
	s_waitcnt lgkmcnt(12)
	v_fma_f32 v116, v217, v253, -v145
	v_fmac_f32_dpp v116, -v172, v42 quad_perm:[0,0,0,0] row_mask:0xf bank_mask:0xf
	v_mul_f32_dpp v117, -v173, v43 quad_perm:[0,0,0,0] row_mask:0xf bank_mask:0xf
	v_mul_f32_dpp v118, -v172, v44 quad_perm:[1,1,1,1] row_mask:0xf bank_mask:0xf
	ds_read_b64 v[186:187], v125 offset:16448
	v_mul_f32_dpp v119, -v173, v45 quad_perm:[1,1,1,1] row_mask:0xf bank_mask:0xf
	v_fmac_f32_dpp v116, -v172, v46 quad_perm:[2,2,2,2] row_mask:0xf bank_mask:0xf
	v_fmac_f32_dpp v117, -v173, v47 quad_perm:[2,2,2,2] row_mask:0xf bank_mask:0xf
	ds_read_b64 v[188:189], v125 offset:16480
	v_fmac_f32_dpp v118, -v172, v48 quad_perm:[3,3,3,3] row_mask:0xf bank_mask:0xf
	v_fmac_f32_dpp v119, -v173, v49 quad_perm:[3,3,3,3] row_mask:0xf bank_mask:0xf
	v_fmac_f32_dpp v116, -v174, v50 quad_perm:[0,0,0,0] row_mask:0xf bank_mask:0xf
	ds_read_b64 v[190:191], v125 offset:16512
	v_fmac_f32_dpp v117, -v175, v51 quad_perm:[0,0,0,0] row_mask:0xf bank_mask:0xf
	v_fmac_f32_dpp v118, -v174, v52 quad_perm:[1,1,1,1] row_mask:0xf bank_mask:0xf
	v_fmac_f32_dpp v119, -v175, v53 quad_perm:[1,1,1,1] row_mask:0xf bank_mask:0xf
	ds_read_b64 v[192:193], v125 offset:16544
	v_fmac_f32_dpp v116, -v174, v54 quad_perm:[2,2,2,2] row_mask:0xf bank_mask:0xf
	v_fmac_f32_dpp v117, -v175, v55 quad_perm:[2,2,2,2] row_mask:0xf bank_mask:0xf
	v_fmac_f32_dpp v118, -v174, v56 quad_perm:[3,3,3,3] row_mask:0xf bank_mask:0xf
	ds_read_b32 v181, v124 offset:240
	v_fmac_f32_dpp v119, -v175, v57 quad_perm:[3,3,3,3] row_mask:0xf bank_mask:0xf
	v_fmac_f32_dpp v116, -v176, v58 quad_perm:[0,0,0,0] row_mask:0xf bank_mask:0xf
	v_fmac_f32_dpp v117, -v177, v59 quad_perm:[0,0,0,0] row_mask:0xf bank_mask:0xf
	ds_read_u16_d16_hi v244, v123 offset:16320
	v_fmac_f32_dpp v118, -v176, v60 quad_perm:[1,1,1,1] row_mask:0xf bank_mask:0xf
	v_fmac_f32_dpp v119, -v177, v61 quad_perm:[1,1,1,1] row_mask:0xf bank_mask:0xf
	v_fmac_f32_dpp v116, -v176, v62 quad_perm:[2,2,2,2] row_mask:0xf bank_mask:0xf
	v_fmac_f32_dpp v117, -v177, v63 quad_perm:[2,2,2,2] row_mask:0xf bank_mask:0xf
	v_fmac_f32_dpp v118, -v176, v64 quad_perm:[3,3,3,3] row_mask:0xf bank_mask:0xf
	v_fmac_f32_dpp v119, -v177, v65 quad_perm:[3,3,3,3] row_mask:0xf bank_mask:0xf
	v_fmac_f32_dpp v116, -v178, v66 quad_perm:[0,0,0,0] row_mask:0xf bank_mask:0xf
	v_add_f32_e32 v121, v117, v116
	v_add_f32_e32 v122, v118, v119
	v_add_f32_e32 v67, v122, v121
	s_waitcnt lgkmcnt(12)
; __device__ __forceinline__ float bf2f(bf16 v) { return __uint_as_float(((unsigned)v) << 16); }
; #define GDN_LOADROW(buf, rr_, i_) do { _Pragma("unroll") for (int j4 = 0; j4 < ((i_) + 3) / 4; ++j4) buf[j4] = *(const f32x4*)(Lm + (i_) * GP_LSTR + 4 * j4); rr_ = bf2f(*(const bf16*)(xsrc + (i_) * GP_STR * 2)) * scl[i_]; } while (0)
; template <int STRIP> __device__ __forceinline__ void ph_gdn_prep_fast(const bf16* __restrict__ proj, const float* __restrict__ small, const float* __restrict__ conv_w, const float* __restrict__ a_log, const float* __restrict__ dt_bias, ...
;     ...
;             rA = bf2f(*(const bf16*)xsrc) * scl[0];
;     ...
; #pragma unroll
;             for (int i = 0; i < 64; i += 2) {
;                 GDN_LOADROW(bB, rB, i + 1);
;                 GDN_ROW(bA, rA, i);
;                 if (i + 2 < 64) GDN_LOADROW(bA, rA, i + 2);
;                 GDN_ROW(bB, rB, i + 1);
;             }
	v_fma_f32 v116, v218, v126, -v146
	v_fmac_f32_dpp v116, -v222, v42 quad_perm:[0,0,0,0] row_mask:0xf bank_mask:0xf
	v_mul_f32_dpp v117, -v223, v43 quad_perm:[0,0,0,0] row_mask:0xf bank_mask:0xf
	ds_read_b64 v[194:195], v125 offset:16720
	v_mul_f32_dpp v118, -v222, v44 quad_perm:[1,1,1,1] row_mask:0xf bank_mask:0xf
	v_mul_f32_dpp v119, -v223, v45 quad_perm:[1,1,1,1] row_mask:0xf bank_mask:0xf
	v_fmac_f32_dpp v116, -v222, v46 quad_perm:[2,2,2,2] row_mask:0xf bank_mask:0xf
	ds_read_b64 v[196:197], v125 offset:16752
	v_fmac_f32_dpp v117, -v223, v47 quad_perm:[2,2,2,2] row_mask:0xf bank_mask:0xf
	v_fmac_f32_dpp v118, -v222, v48 quad_perm:[3,3,3,3] row_mask:0xf bank_mask:0xf
	v_fmac_f32_dpp v119, -v223, v49 quad_perm:[3,3,3,3] row_mask:0xf bank_mask:0xf
	ds_read_b64 v[198:199], v125 offset:16784
	v_fmac_f32_dpp v116, -v224, v50 quad_perm:[0,0,0,0] row_mask:0xf bank_mask:0xf
	v_fmac_f32_dpp v117, -v225, v51 quad_perm:[0,0,0,0] row_mask:0xf bank_mask:0xf
	v_fmac_f32_dpp v118, -v224, v52 quad_perm:[1,1,1,1] row_mask:0xf bank_mask:0xf
	ds_read_b64 v[200:201], v125 offset:16816
	v_fmac_f32_dpp v119, -v225, v53 quad_perm:[1,1,1,1] row_mask:0xf bank_mask:0xf
	v_fmac_f32_dpp v116, -v224, v54 quad_perm:[2,2,2,2] row_mask:0xf bank_mask:0xf
	v_fmac_f32_dpp v117, -v225, v55 quad_perm:[2,2,2,2] row_mask:0xf bank_mask:0xf
	ds_read_b32 v182, v124 offset:244
	v_fmac_f32_dpp v118, -v224, v56 quad_perm:[3,3,3,3] row_mask:0xf bank_mask:0xf
	v_fmac_f32_dpp v119, -v225, v57 quad_perm:[3,3,3,3] row_mask:0xf bank_mask:0xf
	v_fmac_f32_dpp v116, -v226, v58 quad_perm:[0,0,0,0] row_mask:0xf bank_mask:0xf
	ds_read_u16_d16_hi v245, v123 offset:16592
	v_fmac_f32_dpp v117, -v227, v59 quad_perm:[0,0,0,0] row_mask:0xf bank_mask:0xf
	v_fmac_f32_dpp v118, -v226, v60 quad_perm:[1,1,1,1] row_mask:0xf bank_mask:0xf
	v_fmac_f32_dpp v119, -v227, v61 quad_perm:[1,1,1,1] row_mask:0xf bank_mask:0xf
	v_fmac_f32_dpp v116, -v226, v62 quad_perm:[2,2,2,2] row_mask:0xf bank_mask:0xf
	v_fmac_f32_dpp v117, -v227, v63 quad_perm:[2,2,2,2] row_mask:0xf bank_mask:0xf
	v_fmac_f32_dpp v118, -v226, v64 quad_perm:[3,3,3,3] row_mask:0xf bank_mask:0xf
	v_fmac_f32_dpp v119, -v227, v65 quad_perm:[3,3,3,3] row_mask:0xf bank_mask:0xf
	v_fmac_f32_dpp v116, -v228, v66 quad_perm:[0,0,0,0] row_mask:0xf bank_mask:0xf
	v_fmac_f32_dpp v117, -v229, v67 quad_perm:[0,0,0,0] row_mask:0xf bank_mask:0xf
	v_add_f32_e32 v121, v117, v116
	v_add_f32_e32 v122, v118, v119
	v_add_f32_e32 v68, v122, v121
	s_waitcnt lgkmcnt(12)
	v_fma_f32 v116, v219, v127, -v147
	v_fmac_f32_dpp v116, -v86, v42 quad_perm:[0,0,0,0] row_mask:0xf bank_mask:0xf
	v_mul_f32_dpp v117, -v87, v43 quad_perm:[0,0,0,0] row_mask:0xf bank_mask:0xf
	v_mul_f32_dpp v118, -v86, v44 quad_perm:[1,1,1,1] row_mask:0xf bank_mask:0xf
	ds_read_b64 v[202:203], v125 offset:16992
	v_mul_f32_dpp v119, -v87, v45 quad_perm:[1,1,1,1] row_mask:0xf bank_mask:0xf
	v_fmac_f32_dpp v116, -v86, v46 quad_perm:[2,2,2,2] row_mask:0xf bank_mask:0xf
	v_fmac_f32_dpp v117, -v87, v47 quad_perm:[2,2,2,2] row_mask:0xf bank_mask:0xf
	ds_read_b64 v[204:205], v125 offset:17024
	v_fmac_f32_dpp v118, -v86, v48 quad_perm:[3,3,3,3] row_mask:0xf bank_mask:0xf
	v_fmac_f32_dpp v119, -v87, v49 quad_perm:[3,3,3,3] row_mask:0xf bank_mask:0xf
	v_fmac_f32_dpp v116, -v88, v50 quad_perm:[0,0,0,0] row_mask:0xf bank_mask:0xf
	ds_read_b64 v[206:207], v125 offset:17056
	v_fmac_f32_dpp v117, -v89, v51 quad_perm:[0,0,0,0] row_mask:0xf bank_mask:0xf
	v_fmac_f32_dpp v118, -v88, v52 quad_perm:[1,1,1,1] row_mask:0xf bank_mask:0xf
	v_fmac_f32_dpp v119, -v89, v53 quad_perm:[1,1,1,1] row_mask:0xf bank_mask:0xf
	ds_read_b64 v[164:165], v125 offset:17088
	v_fmac_f32_dpp v116, -v88, v54 quad_perm:[2,2,2,2] row_mask:0xf bank_mask:0xf
	v_fmac_f32_dpp v117, -v89, v55 quad_perm:[2,2,2,2] row_mask:0xf bank_mask:0xf
	v_fmac_f32_dpp v118, -v88, v56 quad_perm:[3,3,3,3] row_mask:0xf bank_mask:0xf
	ds_read_b32 v183, v124 offset:248
	v_fmac_f32_dpp v119, -v89, v57 quad_perm:[3,3,3,3] row_mask:0xf bank_mask:0xf
	v_fmac_f32_dpp v116, -v90, v58 quad_perm:[0,0,0,0] row_mask:0xf bank_mask:0xf
	v_fmac_f32_dpp v117, -v91, v59 quad_perm:[0,0,0,0] row_mask:0xf bank_mask:0xf
	ds_read_u16_d16_hi v246, v123 offset:16864
	v_fmac_f32_dpp v118, -v90, v60 quad_perm:[1,1,1,1] row_mask:0xf bank_mask:0xf
	v_fmac_f32_dpp v119, -v91, v61 quad_perm:[1,1,1,1] row_mask:0xf bank_mask:0xf
	v_fmac_f32_dpp v116, -v90, v62 quad_perm:[2,2,2,2] row_mask:0xf bank_mask:0xf
	v_fmac_f32_dpp v117, -v91, v63 quad_perm:[2,2,2,2] row_mask:0xf bank_mask:0xf
	v_fmac_f32_dpp v118, -v90, v64 quad_perm:[3,3,3,3] row_mask:0xf bank_mask:0xf
	v_fmac_f32_dpp v119, -v91, v65 quad_perm:[3,3,3,3] row_mask:0xf bank_mask:0xf
	v_fmac_f32_dpp v116, -v92, v66 quad_perm:[0,0,0,0] row_mask:0xf bank_mask:0xf
	v_fmac_f32_dpp v117, -v93, v67 quad_perm:[0,0,0,0] row_mask:0xf bank_mask:0xf
	v_fmac_f32_dpp v118, -v92, v68 quad_perm:[1,1,1,1] row_mask:0xf bank_mask:0xf
	v_add_f32_e32 v121, v117, v116
	v_add_f32_e32 v122, v118, v119
	v_add_f32_e32 v69, v122, v121
	s_waitcnt lgkmcnt(12)
; __device__ __forceinline__ float bf2f(bf16 v) { return __uint_as_float(((unsigned)v) << 16); }
; #define GDN_LOADROW(buf, rr_, i_) do { _Pragma("unroll") for (int j4 = 0; j4 < ((i_) + 3) / 4; ++j4) buf[j4] = *(const f32x4*)(Lm + (i_) * GP_LSTR + 4 * j4); rr_ = bf2f(*(const bf16*)(xsrc + (i_) * GP_STR * 2)) * scl[i_]; } while (0)
; template <int STRIP> __device__ __forceinline__ void ph_gdn_prep_fast(const bf16* __restrict__ proj, const float* __restrict__ small, const float* __restrict__ conv_w, const float* __restrict__ a_log, const float* __restrict__ dt_bias, ...
;     ...
;             rA = bf2f(*(const bf16*)xsrc) * scl[0];
;     ...
; #pragma unroll
;             for (int i = 0; i < 64; i += 2) {
;                 GDN_LOADROW(bB, rB, i + 1);
;                 GDN_ROW(bA, rA, i);
;                 if (i + 2 < 64) GDN_LOADROW(bA, rA, i + 2);
;                 GDN_ROW(bB, rB, i + 1);
;             }
	v_fma_f32 v116, v181, v244, -v160
	v_fmac_f32_dpp v116, -v186, v42 quad_perm:[0,0,0,0] row_mask:0xf bank_mask:0xf
	v_mul_f32_dpp v117, -v187, v43 quad_perm:[0,0,0,0] row_mask:0xf bank_mask:0xf
	v_mul_f32_dpp v118, -v186, v44 quad_perm:[1,1,1,1] row_mask:0xf bank_mask:0xf
	ds_read_b64 v[166:167], v125 offset:17264
	v_mul_f32_dpp v119, -v187, v45 quad_perm:[1,1,1,1] row_mask:0xf bank_mask:0xf
	v_fmac_f32_dpp v116, -v186, v46 quad_perm:[2,2,2,2] row_mask:0xf bank_mask:0xf
	v_fmac_f32_dpp v117, -v187, v47 quad_perm:[2,2,2,2] row_mask:0xf bank_mask:0xf
	ds_read_b64 v[168:169], v125 offset:17296
	v_fmac_f32_dpp v118, -v186, v48 quad_perm:[3,3,3,3] row_mask:0xf bank_mask:0xf
	v_fmac_f32_dpp v119, -v187, v49 quad_perm:[3,3,3,3] row_mask:0xf bank_mask:0xf
	v_fmac_f32_dpp v116, -v188, v50 quad_perm:[0,0,0,0] row_mask:0xf bank_mask:0xf
	ds_read_b64 v[170:171], v125 offset:17328
	v_fmac_f32_dpp v117, -v189, v51 quad_perm:[0,0,0,0] row_mask:0xf bank_mask:0xf
	v_fmac_f32_dpp v118, -v188, v52 quad_perm:[1,1,1,1] row_mask:0xf bank_mask:0xf
	v_fmac_f32_dpp v119, -v189, v53 quad_perm:[1,1,1,1] row_mask:0xf bank_mask:0xf
	ds_read_b64 v[84:85], v125 offset:17360
	v_fmac_f32_dpp v116, -v188, v54 quad_perm:[2,2,2,2] row_mask:0xf bank_mask:0xf
	v_fmac_f32_dpp v117, -v189, v55 quad_perm:[2,2,2,2] row_mask:0xf bank_mask:0xf
	v_fmac_f32_dpp v118, -v188, v56 quad_perm:[3,3,3,3] row_mask:0xf bank_mask:0xf
	ds_read_b32 v185, v124 offset:252
	v_fmac_f32_dpp v119, -v189, v57 quad_perm:[3,3,3,3] row_mask:0xf bank_mask:0xf
	v_fmac_f32_dpp v116, -v190, v58 quad_perm:[0,0,0,0] row_mask:0xf bank_mask:0xf
	v_fmac_f32_dpp v117, -v191, v59 quad_perm:[0,0,0,0] row_mask:0xf bank_mask:0xf
	ds_read_u16_d16_hi v247, v123 offset:17136
	v_fmac_f32_dpp v118, -v190, v60 quad_perm:[1,1,1,1] row_mask:0xf bank_mask:0xf
	v_fmac_f32_dpp v119, -v191, v61 quad_perm:[1,1,1,1] row_mask:0xf bank_mask:0xf
	v_fmac_f32_dpp v116, -v190, v62 quad_perm:[2,2,2,2] row_mask:0xf bank_mask:0xf
	v_fmac_f32_dpp v117, -v191, v63 quad_perm:[2,2,2,2] row_mask:0xf bank_mask:0xf
	v_fmac_f32_dpp v118, -v190, v64 quad_perm:[3,3,3,3] row_mask:0xf bank_mask:0xf
	v_fmac_f32_dpp v119, -v191, v65 quad_perm:[3,3,3,3] row_mask:0xf bank_mask:0xf
	v_fmac_f32_dpp v116, -v192, v66 quad_perm:[0,0,0,0] row_mask:0xf bank_mask:0xf
	v_fmac_f32_dpp v117, -v193, v67 quad_perm:[0,0,0,0] row_mask:0xf bank_mask:0xf
	v_fmac_f32_dpp v118, -v192, v68 quad_perm:[1,1,1,1] row_mask:0xf bank_mask:0xf
	v_fmac_f32_dpp v119, -v193, v69 quad_perm:[1,1,1,1] row_mask:0xf bank_mask:0xf
	v_add_f32_e32 v121, v117, v116
	v_add_f32_e32 v122, v118, v119
	v_add_f32_e32 v70, v122, v121
	s_waitcnt lgkmcnt(12)
	v_fma_f32 v116, v182, v245, -v161
	v_fmac_f32_dpp v116, -v194, v42 quad_perm:[0,0,0,0] row_mask:0xf bank_mask:0xf
	v_mul_f32_dpp v117, -v195, v43 quad_perm:[0,0,0,0] row_mask:0xf bank_mask:0xf
	v_mul_f32_dpp v118, -v194, v44 quad_perm:[1,1,1,1] row_mask:0xf bank_mask:0xf
	v_mul_f32_dpp v119, -v195, v45 quad_perm:[1,1,1,1] row_mask:0xf bank_mask:0xf
	v_fmac_f32_dpp v116, -v194, v46 quad_perm:[2,2,2,2] row_mask:0xf bank_mask:0xf
	v_fmac_f32_dpp v117, -v195, v47 quad_perm:[2,2,2,2] row_mask:0xf bank_mask:0xf
	v_fmac_f32_dpp v118, -v194, v48 quad_perm:[3,3,3,3] row_mask:0xf bank_mask:0xf
	v_fmac_f32_dpp v119, -v195, v49 quad_perm:[3,3,3,3] row_mask:0xf bank_mask:0xf
	v_fmac_f32_dpp v116, -v196, v50 quad_perm:[0,0,0,0] row_mask:0xf bank_mask:0xf
	v_fmac_f32_dpp v117, -v197, v51 quad_perm:[0,0,0,0] row_mask:0xf bank_mask:0xf
	v_fmac_f32_dpp v118, -v196, v52 quad_perm:[1,1,1,1] row_mask:0xf bank_mask:0xf
	v_fmac_f32_dpp v119, -v197, v53 quad_perm:[1,1,1,1] row_mask:0xf bank_mask:0xf
	v_fmac_f32_dpp v116, -v196, v54 quad_perm:[2,2,2,2] row_mask:0xf bank_mask:0xf
	v_fmac_f32_dpp v117, -v197, v55 quad_perm:[2,2,2,2] row_mask:0xf bank_mask:0xf
	v_fmac_f32_dpp v118, -v196, v56 quad_perm:[3,3,3,3] row_mask:0xf bank_mask:0xf
	v_fmac_f32_dpp v119, -v197, v57 quad_perm:[3,3,3,3] row_mask:0xf bank_mask:0xf
	v_fmac_f32_dpp v116, -v198, v58 quad_perm:[0,0,0,0] row_mask:0xf bank_mask:0xf
	v_fmac_f32_dpp v117, -v199, v59 quad_perm:[0,0,0,0] row_mask:0xf bank_mask:0xf
	v_fmac_f32_dpp v118, -v198, v60 quad_perm:[1,1,1,1] row_mask:0xf bank_mask:0xf
	v_fmac_f32_dpp v119, -v199, v61 quad_perm:[1,1,1,1] row_mask:0xf bank_mask:0xf
	v_fmac_f32_dpp v116, -v198, v62 quad_perm:[2,2,2,2] row_mask:0xf bank_mask:0xf
	v_fmac_f32_dpp v117, -v199, v63 quad_perm:[2,2,2,2] row_mask:0xf bank_mask:0xf
	v_fmac_f32_dpp v118, -v198, v64 quad_perm:[3,3,3,3] row_mask:0xf bank_mask:0xf
	v_fmac_f32_dpp v119, -v199, v65 quad_perm:[3,3,3,3] row_mask:0xf bank_mask:0xf
	v_fmac_f32_dpp v116, -v200, v66 quad_perm:[0,0,0,0] row_mask:0xf bank_mask:0xf
	v_fmac_f32_dpp v117, -v201, v67 quad_perm:[0,0,0,0] row_mask:0xf bank_mask:0xf
	v_fmac_f32_dpp v118, -v200, v68 quad_perm:[1,1,1,1] row_mask:0xf bank_mask:0xf
	v_fmac_f32_dpp v119, -v201, v69 quad_perm:[1,1,1,1] row_mask:0xf bank_mask:0xf
	v_fmac_f32_dpp v116, -v200, v70 quad_perm:[2,2,2,2] row_mask:0xf bank_mask:0xf
	v_add_f32_e32 v121, v117, v116
	v_add_f32_e32 v122, v118, v119
	v_add_f32_e32 v71, v122, v121
	s_waitcnt lgkmcnt(6)
; __device__ __forceinline__ float bf2f(bf16 v) { return __uint_as_float(((unsigned)v) << 16); }
; #define GDN_LOADROW(buf, rr_, i_) do { _Pragma("unroll") for (int j4 = 0; j4 < ((i_) + 3) / 4; ++j4) buf[j4] = *(const f32x4*)(Lm + (i_) * GP_LSTR + 4 * j4); rr_ = bf2f(*(const bf16*)(xsrc + (i_) * GP_STR * 2)) * scl[i_]; } while (0)
; template <int STRIP> __device__ __forceinline__ void ph_gdn_prep_fast(const bf16* __restrict__ proj, const float* __restrict__ small, const float* __restrict__ conv_w, const float* __restrict__ a_log, const float* __restrict__ dt_bias, ...
;     ...
;             rA = bf2f(*(const bf16*)xsrc) * scl[0];
;     ...
; #pragma unroll
;             for (int i = 0; i < 64; i += 2) {
;                 GDN_LOADROW(bB, rB, i + 1);
;                 GDN_ROW(bA, rA, i);
;                 if (i + 2 < 64) GDN_LOADROW(bA, rA, i + 2);
;                 GDN_ROW(bB, rB, i + 1);
;             }
;     ...
;             if (STRIP == 3) { if (U[63] == 12345.678f) EGL[ci] = U[5]; } else
;             if (!isw) { const int v = cc >> 4, c15 = cc & 15; bf16* dst = UF + ((size_t)ci * 8 + v) * 64 * 16;
	v_fma_f32 v116, v183, v246, -v162
	v_fmac_f32_dpp v116, -v202, v42 quad_perm:[0,0,0,0] row_mask:0xf bank_mask:0xf
	v_mul_f32_dpp v117, -v203, v43 quad_perm:[0,0,0,0] row_mask:0xf bank_mask:0xf
	v_mul_f32_dpp v118, -v202, v44 quad_perm:[1,1,1,1] row_mask:0xf bank_mask:0xf
	v_mul_f32_dpp v119, -v203, v45 quad_perm:[1,1,1,1] row_mask:0xf bank_mask:0xf
	v_fmac_f32_dpp v116, -v202, v46 quad_perm:[2,2,2,2] row_mask:0xf bank_mask:0xf
	v_fmac_f32_dpp v117, -v203, v47 quad_perm:[2,2,2,2] row_mask:0xf bank_mask:0xf
	v_fmac_f32_dpp v118, -v202, v48 quad_perm:[3,3,3,3] row_mask:0xf bank_mask:0xf
	v_fmac_f32_dpp v119, -v203, v49 quad_perm:[3,3,3,3] row_mask:0xf bank_mask:0xf
	v_fmac_f32_dpp v116, -v204, v50 quad_perm:[0,0,0,0] row_mask:0xf bank_mask:0xf
	v_fmac_f32_dpp v117, -v205, v51 quad_perm:[0,0,0,0] row_mask:0xf bank_mask:0xf
	v_fmac_f32_dpp v118, -v204, v52 quad_perm:[1,1,1,1] row_mask:0xf bank_mask:0xf
	v_fmac_f32_dpp v119, -v205, v53 quad_perm:[1,1,1,1] row_mask:0xf bank_mask:0xf
	v_fmac_f32_dpp v116, -v204, v54 quad_perm:[2,2,2,2] row_mask:0xf bank_mask:0xf
	v_fmac_f32_dpp v117, -v205, v55 quad_perm:[2,2,2,2] row_mask:0xf bank_mask:0xf
	v_fmac_f32_dpp v118, -v204, v56 quad_perm:[3,3,3,3] row_mask:0xf bank_mask:0xf
	v_fmac_f32_dpp v119, -v205, v57 quad_perm:[3,3,3,3] row_mask:0xf bank_mask:0xf
	v_fmac_f32_dpp v116, -v206, v58 quad_perm:[0,0,0,0] row_mask:0xf bank_mask:0xf
	v_fmac_f32_dpp v117, -v207, v59 quad_perm:[0,0,0,0] row_mask:0xf bank_mask:0xf
	v_fmac_f32_dpp v118, -v206, v60 quad_perm:[1,1,1,1] row_mask:0xf bank_mask:0xf
	v_fmac_f32_dpp v119, -v207, v61 quad_perm:[1,1,1,1] row_mask:0xf bank_mask:0xf
	v_fmac_f32_dpp v116, -v206, v62 quad_perm:[2,2,2,2] row_mask:0xf bank_mask:0xf
	v_fmac_f32_dpp v117, -v207, v63 quad_perm:[2,2,2,2] row_mask:0xf bank_mask:0xf
	v_fmac_f32_dpp v118, -v206, v64 quad_perm:[3,3,3,3] row_mask:0xf bank_mask:0xf
	v_fmac_f32_dpp v119, -v207, v65 quad_perm:[3,3,3,3] row_mask:0xf bank_mask:0xf
	v_fmac_f32_dpp v116, -v164, v66 quad_perm:[0,0,0,0] row_mask:0xf bank_mask:0xf
	v_fmac_f32_dpp v117, -v165, v67 quad_perm:[0,0,0,0] row_mask:0xf bank_mask:0xf
	v_fmac_f32_dpp v118, -v164, v68 quad_perm:[1,1,1,1] row_mask:0xf bank_mask:0xf
	v_fmac_f32_dpp v119, -v165, v69 quad_perm:[1,1,1,1] row_mask:0xf bank_mask:0xf
	v_fmac_f32_dpp v116, -v164, v70 quad_perm:[2,2,2,2] row_mask:0xf bank_mask:0xf
	v_fmac_f32_dpp v117, -v165, v71 quad_perm:[2,2,2,2] row_mask:0xf bank_mask:0xf
	v_add_f32_e32 v121, v117, v116
	v_add_f32_e32 v122, v118, v119
	v_add_f32_e32 v26, v122, v121
	s_waitcnt lgkmcnt(0)
	v_fma_f32 v116, v185, v247, -v163
	v_fmac_f32_dpp v116, -v166, v42 quad_perm:[0,0,0,0] row_mask:0xf bank_mask:0xf
	v_mul_f32_dpp v117, -v167, v43 quad_perm:[0,0,0,0] row_mask:0xf bank_mask:0xf
	v_mul_f32_dpp v118, -v166, v44 quad_perm:[1,1,1,1] row_mask:0xf bank_mask:0xf
	v_mul_f32_dpp v119, -v167, v45 quad_perm:[1,1,1,1] row_mask:0xf bank_mask:0xf
	v_fmac_f32_dpp v116, -v166, v46 quad_perm:[2,2,2,2] row_mask:0xf bank_mask:0xf
	v_fmac_f32_dpp v117, -v167, v47 quad_perm:[2,2,2,2] row_mask:0xf bank_mask:0xf
	v_fmac_f32_dpp v118, -v166, v48 quad_perm:[3,3,3,3] row_mask:0xf bank_mask:0xf
	v_fmac_f32_dpp v119, -v167, v49 quad_perm:[3,3,3,3] row_mask:0xf bank_mask:0xf
	v_fmac_f32_dpp v116, -v168, v50 quad_perm:[0,0,0,0] row_mask:0xf bank_mask:0xf
	v_fmac_f32_dpp v117, -v169, v51 quad_perm:[0,0,0,0] row_mask:0xf bank_mask:0xf
	v_fmac_f32_dpp v118, -v168, v52 quad_perm:[1,1,1,1] row_mask:0xf bank_mask:0xf
	v_fmac_f32_dpp v119, -v169, v53 quad_perm:[1,1,1,1] row_mask:0xf bank_mask:0xf
	v_fmac_f32_dpp v116, -v168, v54 quad_perm:[2,2,2,2] row_mask:0xf bank_mask:0xf
	v_fmac_f32_dpp v117, -v169, v55 quad_perm:[2,2,2,2] row_mask:0xf bank_mask:0xf
	v_fmac_f32_dpp v118, -v168, v56 quad_perm:[3,3,3,3] row_mask:0xf bank_mask:0xf
	v_fmac_f32_dpp v119, -v169, v57 quad_perm:[3,3,3,3] row_mask:0xf bank_mask:0xf
	v_fmac_f32_dpp v116, -v170, v58 quad_perm:[0,0,0,0] row_mask:0xf bank_mask:0xf
	v_fmac_f32_dpp v117, -v171, v59 quad_perm:[0,0,0,0] row_mask:0xf bank_mask:0xf
	v_fmac_f32_dpp v118, -v170, v60 quad_perm:[1,1,1,1] row_mask:0xf bank_mask:0xf
	v_fmac_f32_dpp v119, -v171, v61 quad_perm:[1,1,1,1] row_mask:0xf bank_mask:0xf
	v_fmac_f32_dpp v116, -v170, v62 quad_perm:[2,2,2,2] row_mask:0xf bank_mask:0xf
	v_fmac_f32_dpp v117, -v171, v63 quad_perm:[2,2,2,2] row_mask:0xf bank_mask:0xf
	v_fmac_f32_dpp v118, -v170, v64 quad_perm:[3,3,3,3] row_mask:0xf bank_mask:0xf
	v_fmac_f32_dpp v119, -v171, v65 quad_perm:[3,3,3,3] row_mask:0xf bank_mask:0xf
	v_fmac_f32_dpp v116, -v84, v66 quad_perm:[0,0,0,0] row_mask:0xf bank_mask:0xf
	v_fmac_f32_dpp v117, -v85, v67 quad_perm:[0,0,0,0] row_mask:0xf bank_mask:0xf
	v_fmac_f32_dpp v118, -v84, v68 quad_perm:[1,1,1,1] row_mask:0xf bank_mask:0xf
	v_fmac_f32_dpp v119, -v85, v69 quad_perm:[1,1,1,1] row_mask:0xf bank_mask:0xf
	v_fmac_f32_dpp v116, -v84, v70 quad_perm:[2,2,2,2] row_mask:0xf bank_mask:0xf
	v_fmac_f32_dpp v117, -v85, v71 quad_perm:[2,2,2,2] row_mask:0xf bank_mask:0xf
	v_fmac_f32_dpp v118, -v84, v26 quad_perm:[3,3,3,3] row_mask:0xf bank_mask:0xf
	v_add_f32_e32 v121, v117, v116
	v_add_f32_e32 v122, v118, v119
	v_add_f32_e32 v72, v122, v121
	v_add_u32_e32 v8, v79, v8
	v_ashrrev_i32_e32 v9, 31, v8
	v_lshlrev_b64 v[8:9], 14, v[8:9]
	v_lshlrev_b32_e32 v73, 4, v78
	s_and_saveexec_b64 s[0:1], vcc
	s_xor_b64 s[0:1], exec, s[0:1]
	s_cbranch_execz .LBB0_1305
; __device__ __forceinline__ bf16 f2bf(float f) { return (bf16)(pk2(f, 0.f) & 0xffffu); }
; __device__ __forceinline__ int gperm(int x) { return (x & ~31) | ((x & 12) << 1) | ((x & 16) >> 2) | (x & 3); }
; template <int STRIP> __device__ __forceinline__ void ph_gdn_prep_fast(const bf16* __restrict__ proj, const float* __restrict__ small, const float* __restrict__ conv_w, const float* __restrict__ a_log, const float* __restrict__ dt_bias, ...
;     ...
;             else { bf16* dst = WP + (size_t)ci * 64 * 128 + gperm(cc);
; #pragma unroll
;                 for (int i = 0; i < 64; ++i) __builtin_nontemporal_store(f2bf(U[i]), dst + i * 128); }
	v_and_b32_e32 v2, 24, v18
	v_lshrrev_b32_e32 v18, 2, v78
	v_and_b32_e32 v18, 4, v18
	v_and_b32_e32 v73, 0x63, v78
	v_or3_b32 v2, v18, v73, v2
	v_lshl_add_u64 v[74:75], s[34:35], 0, v[8:9]
	v_lshlrev_b32_e32 v2, 1, v2
	v_lshl_add_u64 v[74:75], v[74:75], 0, v[2:3]
	v_cvt_pk_bf16_f32 v2, v4, s0
	global_store_short v[74:75], v2, off nt
	v_cvt_pk_bf16_f32 v2, v5, s0
	global_store_short v[74:75], v2, off offset:256 nt
	v_cvt_pk_bf16_f32 v2, v6, s0
	global_store_short v[74:75], v2, off offset:512 nt
	v_cvt_pk_bf16_f32 v2, v12, s0
	global_store_short v[74:75], v2, off offset:768 nt
	v_cvt_pk_bf16_f32 v2, v7, s0
	global_store_short v[74:75], v2, off offset:1024 nt
	v_cvt_pk_bf16_f32 v2, v13, s0
	global_store_short v[74:75], v2, off offset:1280 nt
	v_cvt_pk_bf16_f32 v2, v14, s0
	global_store_short v[74:75], v2, off offset:1536 nt
	v_cvt_pk_bf16_f32 v2, v15, s0
	global_store_short v[74:75], v2, off offset:1792 nt
	v_cvt_pk_bf16_f32 v2, v16, s0
	global_store_short v[74:75], v2, off offset:2048 nt
	v_cvt_pk_bf16_f32 v2, v17, s0
	global_store_short v[74:75], v2, off offset:2304 nt
	v_cvt_pk_bf16_f32 v2, v19, s0
	global_store_short v[74:75], v2, off offset:2560 nt
	v_cvt_pk_bf16_f32 v2, v20, s0
	global_store_short v[74:75], v2, off offset:2816 nt
	v_cvt_pk_bf16_f32 v2, v21, s0
	global_store_short v[74:75], v2, off offset:3072 nt
	v_cvt_pk_bf16_f32 v2, v22, s0
	v_add_co_u32_e32 v4, vcc, s79, v74
	global_store_short v[74:75], v2, off offset:3328 nt
	v_cvt_pk_bf16_f32 v2, v23, s0
	v_addc_co_u32_e32 v5, vcc, 0, v75, vcc
	global_store_short v[74:75], v2, off offset:3584 nt
	v_cvt_pk_bf16_f32 v2, v24, s0
	v_add_co_u32_e32 v6, vcc, s76, v74
	global_store_short v[74:75], v2, off offset:3840 nt
	v_cvt_pk_bf16_f32 v2, v25, s0
	v_addc_co_u32_e32 v7, vcc, 0, v75, vcc
	global_store_short v[6:7], v2, off offset:-4096 nt
	v_cvt_pk_bf16_f32 v2, v27, s0
	global_store_short v[4:5], v2, off offset:256 nt
	v_cvt_pk_bf16_f32 v2, v28, s0
	global_store_short v[4:5], v2, off offset:512 nt
	v_cvt_pk_bf16_f32 v2, v29, s0
	global_store_short v[4:5], v2, off offset:768 nt
	v_cvt_pk_bf16_f32 v2, v30, s0
	global_store_short v[4:5], v2, off offset:1024 nt
	v_cvt_pk_bf16_f32 v2, v31, s0
	global_store_short v[4:5], v2, off offset:1280 nt
	v_cvt_pk_bf16_f32 v2, v32, s0
	global_store_short v[4:5], v2, off offset:1536 nt
	v_cvt_pk_bf16_f32 v2, v33, s0
	global_store_short v[4:5], v2, off offset:1792 nt
	v_cvt_pk_bf16_f32 v2, v34, s0
	global_store_short v[4:5], v2, off offset:2048 nt
	v_cvt_pk_bf16_f32 v2, v35, s0
	global_store_short v[4:5], v2, off offset:2304 nt
	v_cvt_pk_bf16_f32 v2, v36, s0
	global_store_short v[4:5], v2, off offset:2560 nt
	v_cvt_pk_bf16_f32 v2, v37, s0
	global_store_short v[4:5], v2, off offset:2816 nt
	v_cvt_pk_bf16_f32 v2, v38, s0
	global_store_short v[4:5], v2, off offset:3072 nt
	v_cvt_pk_bf16_f32 v2, v39, s0
	global_store_short v[4:5], v2, off offset:3328 nt
	v_cvt_pk_bf16_f32 v2, v40, s0
	global_store_short v[4:5], v2, off offset:3584 nt
	v_cvt_pk_bf16_f32 v2, v41, s0
	global_store_short v[4:5], v2, off offset:3840 nt
	v_cvt_pk_bf16_f32 v2, v42, s0
	global_store_short v[6:7], v2, off nt
	v_cvt_pk_bf16_f32 v2, v43, s0
	global_store_short v[6:7], v2, off offset:256 nt
	v_cvt_pk_bf16_f32 v2, v44, s0
	global_store_short v[6:7], v2, off offset:512 nt
	v_cvt_pk_bf16_f32 v2, v45, s0
	global_store_short v[6:7], v2, off offset:768 nt
	v_cvt_pk_bf16_f32 v2, v46, s0
	global_store_short v[6:7], v2, off offset:1024 nt
	v_cvt_pk_bf16_f32 v2, v47, s0
	global_store_short v[6:7], v2, off offset:1280 nt
	v_cvt_pk_bf16_f32 v2, v48, s0
	global_store_short v[6:7], v2, off offset:1536 nt
	v_cvt_pk_bf16_f32 v2, v49, s0
	global_store_short v[6:7], v2, off offset:1792 nt
	v_cvt_pk_bf16_f32 v2, v50, s0
	global_store_short v[6:7], v2, off offset:2048 nt
	v_cvt_pk_bf16_f32 v2, v51, s0
	global_store_short v[6:7], v2, off offset:2304 nt
	v_cvt_pk_bf16_f32 v2, v52, s0
	global_store_short v[6:7], v2, off offset:2560 nt
	v_cvt_pk_bf16_f32 v2, v53, s0
	global_store_short v[6:7], v2, off offset:2816 nt
	v_cvt_pk_bf16_f32 v2, v54, s0
	global_store_short v[6:7], v2, off offset:3072 nt
	v_cvt_pk_bf16_f32 v2, v55, s0
	global_store_short v[6:7], v2, off offset:3328 nt
	v_cvt_pk_bf16_f32 v2, v56, s0
	s_movk_i32 s2, 0x3000
	global_store_short v[6:7], v2, off offset:3584 nt
	v_cvt_pk_bf16_f32 v2, v57, s0
	v_add_co_u32_e32 v4, vcc, s2, v74
	global_store_short v[6:7], v2, off offset:3840 nt
	v_cvt_pk_bf16_f32 v2, v58, s0
	v_addc_co_u32_e32 v5, vcc, 0, v75, vcc
	global_store_short v[4:5], v2, off nt
	v_cvt_pk_bf16_f32 v2, v59, s0
	global_store_short v[4:5], v2, off offset:256 nt
	v_cvt_pk_bf16_f32 v2, v60, s0
	global_store_short v[4:5], v2, off offset:512 nt
	v_cvt_pk_bf16_f32 v2, v61, s0
	global_store_short v[4:5], v2, off offset:768 nt
	v_cvt_pk_bf16_f32 v2, v62, s0
	global_store_short v[4:5], v2, off offset:1024 nt
	v_cvt_pk_bf16_f32 v2, v63, s0
	global_store_short v[4:5], v2, off offset:1280 nt
	v_cvt_pk_bf16_f32 v2, v64, s0
	global_store_short v[4:5], v2, off offset:1536 nt
	v_cvt_pk_bf16_f32 v2, v65, s0
	global_store_short v[4:5], v2, off offset:1792 nt
	v_cvt_pk_bf16_f32 v2, v66, s0
	global_store_short v[4:5], v2, off offset:2048 nt
	v_cvt_pk_bf16_f32 v2, v67, s0
	global_store_short v[4:5], v2, off offset:2304 nt
	v_cvt_pk_bf16_f32 v2, v68, s0
	global_store_short v[4:5], v2, off offset:2560 nt
	v_cvt_pk_bf16_f32 v2, v69, s0
	global_store_short v[4:5], v2, off offset:2816 nt
	v_cvt_pk_bf16_f32 v2, v70, s0
	global_store_short v[4:5], v2, off offset:3072 nt
	v_cvt_pk_bf16_f32 v2, v71, s0
	global_store_short v[4:5], v2, off offset:3328 nt
	v_cvt_pk_bf16_f32 v2, v26, s0
	global_store_short v[4:5], v2, off offset:3584 nt
	v_cvt_pk_bf16_f32 v2, v72, s0
	global_store_short v[4:5], v2, off offset:3840 nt
	v_lshlrev_b32_e32 v73, 4, v78
